# v40: v36 + nt (non-temporal) hint on the GEMM1 epilogue output stores (keep L2 for operand tiles)
# baseline (speedup 1.0000x reference)
.LBB0_242:
	s_lshl_b32 s18, s18, 6
	s_ashr_i32 s19, s18, 31
	s_lshl_b64 s[18:19], s[18:19], 1
	s_add_u32 s18, s73, s18
	v_pk_mul_f32 v[132:133], v[128:129], v[132:133]
	v_pk_mul_f32 v[130:131], v[126:127], v[130:131]
	s_addc_u32 s19, s76, s19
	v_ashrrev_i32_e32 v147, 31, v146
	v_pk_mul_f32 v[134:135], v[122:123], v[134:135]
	v_ashrrev_i32_e32 v175, 31, v174
	v_lshl_add_u64 v[138:139], v[146:147], 1, s[18:19]
	v_pk_mul_f32 v[136:137], v[124:125], v[136:137]
	v_cvt_pk_bf16_f32 v130, v130, v131
	v_cvt_pk_bf16_f32 v131, v132, v133
	v_cvt_pk_bf16_f32 v132, v134, v135
	v_lshlrev_b64 v[134:135], 12, v[174:175]
	v_cvt_pk_bf16_f32 v133, v136, v137
	v_lshl_add_u64 v[134:135], v[138:139], 0, v[134:135]
	global_store_dwordx4 v[134:135], v[130:133], off nt
	s_and_b64 vcc, exec, s[40:41]
	s_nop 0
	v_mov_b64_e32 v[132:133], v[104:105]
	v_mov_b64_e32 v[130:131], v[102:103]
	s_cbranch_vccnz .LBB0_244
	v_mul_f32_e32 v130, 0xbfb8aa3b, v102
	v_mul_f32_e32 v131, 0xbfb8aa3b, v103
	v_mul_f32_e32 v132, 0xbfb8aa3b, v104
	v_mul_f32_e32 v133, 0xbfb8aa3b, v105
	v_exp_f32_e32 v130, v130
	v_exp_f32_e32 v131, v131
	v_exp_f32_e32 v132, v132
	v_exp_f32_e32 v133, v133
	v_add_f32_e32 v130, 1.0, v130
	v_add_f32_e32 v131, 1.0, v131
	v_add_f32_e32 v132, 1.0, v132
	v_add_f32_e32 v133, 1.0, v133
	v_rcp_f32_e32 v130, v130
	v_rcp_f32_e32 v132, v132
	v_rcp_f32_e32 v133, v133
	v_rcp_f32_e32 v131, v131
	v_pk_mul_f32 v[132:133], v[104:105], v[132:133]
	v_pk_mul_f32 v[130:131], v[102:103], v[130:131]

.LBB0_246:
	v_pk_mul_f32 v[132:133], v[112:113], v[132:133]
	v_pk_mul_f32 v[130:131], v[110:111], v[130:131]
	v_pk_mul_f32 v[134:135], v[106:107], v[134:135]
	v_cvt_pk_bf16_f32 v130, v130, v131
	v_cvt_pk_bf16_f32 v131, v132, v133
	v_cvt_pk_bf16_f32 v132, v134, v135
	v_or_b32_e32 v134, 16, v174
	v_ashrrev_i32_e32 v135, 31, v134
	v_pk_mul_f32 v[136:137], v[108:109], v[136:137]
	v_lshlrev_b64 v[134:135], 12, v[134:135]
	v_cvt_pk_bf16_f32 v133, v136, v137
	v_lshl_add_u64 v[134:135], v[138:139], 0, v[134:135]
	global_store_dwordx4 v[134:135], v[130:133], off nt
	s_and_b64 vcc, exec, s[40:41]
	s_nop 0
	v_mov_b64_e32 v[132:133], v[88:89]
	v_mov_b64_e32 v[130:131], v[86:87]
	s_cbranch_vccnz .LBB0_248
	v_mul_f32_e32 v130, 0xbfb8aa3b, v86
	v_mul_f32_e32 v131, 0xbfb8aa3b, v87
	v_mul_f32_e32 v132, 0xbfb8aa3b, v88
	v_mul_f32_e32 v133, 0xbfb8aa3b, v89
	v_exp_f32_e32 v130, v130
	v_exp_f32_e32 v131, v131
	v_exp_f32_e32 v132, v132
	v_exp_f32_e32 v133, v133
	v_add_f32_e32 v130, 1.0, v130
	v_add_f32_e32 v131, 1.0, v131
	v_add_f32_e32 v132, 1.0, v132
	v_add_f32_e32 v133, 1.0, v133
	v_rcp_f32_e32 v130, v130
	v_rcp_f32_e32 v132, v132
	v_rcp_f32_e32 v133, v133
	v_rcp_f32_e32 v131, v131
	v_pk_mul_f32 v[132:133], v[88:89], v[132:133]
	v_pk_mul_f32 v[130:131], v[86:87], v[130:131]

.LBB0_250:
	v_pk_mul_f32 v[132:133], v[96:97], v[132:133]
	v_pk_mul_f32 v[130:131], v[94:95], v[130:131]
	v_pk_mul_f32 v[134:135], v[90:91], v[134:135]
	v_cvt_pk_bf16_f32 v130, v130, v131
	v_cvt_pk_bf16_f32 v131, v132, v133
	v_cvt_pk_bf16_f32 v132, v134, v135
	v_or_b32_e32 v134, 32, v174
	v_ashrrev_i32_e32 v135, 31, v134
	v_pk_mul_f32 v[136:137], v[92:93], v[136:137]
	v_lshlrev_b64 v[134:135], 12, v[134:135]
	v_cvt_pk_bf16_f32 v133, v136, v137
	v_lshl_add_u64 v[134:135], v[138:139], 0, v[134:135]
	global_store_dwordx4 v[134:135], v[130:133], off nt
	s_and_b64 vcc, exec, s[40:41]
	s_nop 0
	v_mov_b64_e32 v[132:133], v[72:73]
	v_mov_b64_e32 v[130:131], v[70:71]
	s_cbranch_vccnz .LBB0_252
	v_mul_f32_e32 v130, 0xbfb8aa3b, v70
	v_mul_f32_e32 v131, 0xbfb8aa3b, v71
	v_mul_f32_e32 v132, 0xbfb8aa3b, v72
	v_mul_f32_e32 v133, 0xbfb8aa3b, v73
	v_exp_f32_e32 v130, v130
	v_exp_f32_e32 v131, v131
	v_exp_f32_e32 v132, v132
	v_exp_f32_e32 v133, v133
	v_add_f32_e32 v130, 1.0, v130
	v_add_f32_e32 v131, 1.0, v131
	v_add_f32_e32 v132, 1.0, v132
	v_add_f32_e32 v133, 1.0, v133
	v_rcp_f32_e32 v130, v130
	v_rcp_f32_e32 v132, v132
	v_rcp_f32_e32 v133, v133
	v_rcp_f32_e32 v131, v131
	v_pk_mul_f32 v[132:133], v[72:73], v[132:133]
	v_pk_mul_f32 v[130:131], v[70:71], v[130:131]

.LBB0_254:
	v_pk_mul_f32 v[132:133], v[80:81], v[132:133]
	v_pk_mul_f32 v[130:131], v[78:79], v[130:131]
	v_pk_mul_f32 v[134:135], v[74:75], v[134:135]
	v_cvt_pk_bf16_f32 v130, v130, v131
	v_cvt_pk_bf16_f32 v131, v132, v133
	v_cvt_pk_bf16_f32 v132, v134, v135
	v_or_b32_e32 v134, 48, v174
	v_ashrrev_i32_e32 v135, 31, v134
	v_pk_mul_f32 v[136:137], v[76:77], v[136:137]
	v_lshlrev_b64 v[134:135], 12, v[134:135]
	v_cvt_pk_bf16_f32 v133, v136, v137
	v_lshl_add_u64 v[134:135], v[138:139], 0, v[134:135]
	global_store_dwordx4 v[134:135], v[130:133], off nt
	s_and_b64 vcc, exec, s[40:41]
	s_nop 0
	v_mov_b64_e32 v[132:133], v[56:57]
	v_mov_b64_e32 v[130:131], v[54:55]
	s_cbranch_vccnz .LBB0_256
	v_mul_f32_e32 v130, 0xbfb8aa3b, v54
	v_mul_f32_e32 v131, 0xbfb8aa3b, v55
	v_mul_f32_e32 v132, 0xbfb8aa3b, v56
	v_mul_f32_e32 v133, 0xbfb8aa3b, v57
	v_exp_f32_e32 v130, v130
	v_exp_f32_e32 v131, v131
	v_exp_f32_e32 v132, v132
	v_exp_f32_e32 v133, v133
	v_add_f32_e32 v130, 1.0, v130
	v_add_f32_e32 v131, 1.0, v131
	v_add_f32_e32 v132, 1.0, v132
	v_add_f32_e32 v133, 1.0, v133
	v_rcp_f32_e32 v130, v130
	v_rcp_f32_e32 v132, v132
	v_rcp_f32_e32 v133, v133
	v_rcp_f32_e32 v131, v131
	v_pk_mul_f32 v[132:133], v[56:57], v[132:133]
	v_pk_mul_f32 v[130:131], v[54:55], v[130:131]

.LBB0_258:
	v_pk_mul_f32 v[132:133], v[64:65], v[132:133]
	v_pk_mul_f32 v[130:131], v[62:63], v[130:131]
	v_pk_mul_f32 v[134:135], v[58:59], v[134:135]
	v_cvt_pk_bf16_f32 v130, v130, v131
	v_cvt_pk_bf16_f32 v131, v132, v133
	v_cvt_pk_bf16_f32 v132, v134, v135
	v_lshlrev_b64 v[134:135], 12, v[174:175]
	v_lshl_add_u64 v[134:135], v[138:139], 0, v[134:135]
	v_pk_mul_f32 v[136:137], v[60:61], v[136:137]
	v_add_co_u32_e32 v134, vcc, 0x80000, v134
	v_cvt_pk_bf16_f32 v133, v136, v137
	s_nop 0
	v_addc_co_u32_e32 v135, vcc, 0, v135, vcc
	global_store_dwordx4 v[134:135], v[130:133], off nt
	s_and_b64 vcc, exec, s[40:41]
	s_nop 0
	v_mov_b64_e32 v[132:133], v[40:41]
	v_mov_b64_e32 v[130:131], v[38:39]
	s_cbranch_vccnz .LBB0_260
	v_mul_f32_e32 v130, 0xbfb8aa3b, v38
	v_mul_f32_e32 v131, 0xbfb8aa3b, v39
	v_mul_f32_e32 v132, 0xbfb8aa3b, v40
	v_mul_f32_e32 v133, 0xbfb8aa3b, v41
	v_exp_f32_e32 v130, v130
	v_exp_f32_e32 v131, v131
	v_exp_f32_e32 v132, v132
	v_exp_f32_e32 v133, v133
	v_add_f32_e32 v130, 1.0, v130
	v_add_f32_e32 v131, 1.0, v131
	v_add_f32_e32 v132, 1.0, v132
	v_add_f32_e32 v133, 1.0, v133
	v_rcp_f32_e32 v130, v130
	v_rcp_f32_e32 v132, v132
	v_rcp_f32_e32 v133, v133
	v_rcp_f32_e32 v131, v131
	v_pk_mul_f32 v[132:133], v[40:41], v[132:133]
	v_pk_mul_f32 v[130:131], v[38:39], v[130:131]

.LBB0_262:
	v_pk_mul_f32 v[132:133], v[48:49], v[132:133]
	v_pk_mul_f32 v[130:131], v[46:47], v[130:131]
	v_pk_mul_f32 v[134:135], v[42:43], v[134:135]
	v_cvt_pk_bf16_f32 v130, v130, v131
	v_cvt_pk_bf16_f32 v131, v132, v133
	v_cvt_pk_bf16_f32 v132, v134, v135
	v_lshlrev_b64 v[134:135], 12, v[174:175]
	v_lshl_add_u64 v[134:135], v[138:139], 0, v[134:135]
	v_pk_mul_f32 v[136:137], v[44:45], v[136:137]
	v_add_co_u32_e32 v134, vcc, 0x90000, v134
	v_cvt_pk_bf16_f32 v133, v136, v137
	s_nop 0
	v_addc_co_u32_e32 v135, vcc, 0, v135, vcc
	global_store_dwordx4 v[134:135], v[130:133], off nt
	s_and_b64 vcc, exec, s[40:41]
	s_nop 0
	v_mov_b64_e32 v[132:133], v[24:25]
	v_mov_b64_e32 v[130:131], v[22:23]
	s_cbranch_vccnz .LBB0_264
	v_mul_f32_e32 v130, 0xbfb8aa3b, v22
	v_mul_f32_e32 v131, 0xbfb8aa3b, v23
	v_mul_f32_e32 v132, 0xbfb8aa3b, v24
	v_mul_f32_e32 v133, 0xbfb8aa3b, v25
	v_exp_f32_e32 v130, v130
	v_exp_f32_e32 v131, v131
	v_exp_f32_e32 v132, v132
	v_exp_f32_e32 v133, v133
	v_add_f32_e32 v130, 1.0, v130
	v_add_f32_e32 v131, 1.0, v131
	v_add_f32_e32 v132, 1.0, v132
	v_add_f32_e32 v133, 1.0, v133
	v_rcp_f32_e32 v130, v130
	v_rcp_f32_e32 v132, v132
	v_rcp_f32_e32 v133, v133
	v_rcp_f32_e32 v131, v131
	v_pk_mul_f32 v[132:133], v[24:25], v[132:133]
	v_pk_mul_f32 v[130:131], v[22:23], v[130:131]

.LBB0_266:
	v_pk_mul_f32 v[132:133], v[32:33], v[132:133]
	v_pk_mul_f32 v[130:131], v[30:31], v[130:131]
	v_pk_mul_f32 v[134:135], v[26:27], v[134:135]
	v_cvt_pk_bf16_f32 v130, v130, v131
	v_cvt_pk_bf16_f32 v131, v132, v133
	v_cvt_pk_bf16_f32 v132, v134, v135
	v_lshlrev_b64 v[134:135], 12, v[174:175]
	v_lshl_add_u64 v[134:135], v[138:139], 0, v[134:135]
	v_pk_mul_f32 v[136:137], v[28:29], v[136:137]
	v_add_co_u32_e32 v134, vcc, 0xa0000, v134
	v_cvt_pk_bf16_f32 v133, v136, v137
	s_nop 0
	v_addc_co_u32_e32 v135, vcc, 0, v135, vcc
	global_store_dwordx4 v[134:135], v[130:133], off nt
	s_and_b64 vcc, exec, s[40:41]
	s_nop 0
	v_mov_b64_e32 v[132:133], v[8:9]
	v_mov_b64_e32 v[130:131], v[6:7]
	s_cbranch_vccnz .LBB0_268
	v_mul_f32_e32 v130, 0xbfb8aa3b, v6
	v_mul_f32_e32 v131, 0xbfb8aa3b, v7
	v_mul_f32_e32 v132, 0xbfb8aa3b, v8
	v_mul_f32_e32 v133, 0xbfb8aa3b, v9
	v_exp_f32_e32 v130, v130
	v_exp_f32_e32 v131, v131
	v_exp_f32_e32 v132, v132
	v_exp_f32_e32 v133, v133
	v_add_f32_e32 v130, 1.0, v130
	v_add_f32_e32 v131, 1.0, v131
	v_add_f32_e32 v132, 1.0, v132
	v_add_f32_e32 v133, 1.0, v133
	v_rcp_f32_e32 v130, v130
	v_rcp_f32_e32 v132, v132
	v_rcp_f32_e32 v133, v133
	v_rcp_f32_e32 v131, v131
	v_pk_mul_f32 v[132:133], v[8:9], v[132:133]
	v_pk_mul_f32 v[130:131], v[6:7], v[130:131]

.LBB0_270:
	v_pk_mul_f32 v[132:133], v[16:17], v[132:133]
	v_pk_mul_f32 v[130:131], v[14:15], v[130:131]
	v_pk_mul_f32 v[134:135], v[10:11], v[134:135]
	v_cvt_pk_bf16_f32 v130, v130, v131
	v_cvt_pk_bf16_f32 v131, v132, v133
	v_cvt_pk_bf16_f32 v132, v134, v135
	v_lshlrev_b64 v[134:135], 12, v[174:175]
	v_lshl_add_u64 v[134:135], v[138:139], 0, v[134:135]
	v_pk_mul_f32 v[136:137], v[12:13], v[136:137]
	v_add_co_u32_e32 v134, vcc, 0xb0000, v134
	v_cvt_pk_bf16_f32 v133, v136, v137
	s_nop 0
	v_addc_co_u32_e32 v135, vcc, 0, v135, vcc
	s_mov_b64 s[28:29], 0
	global_store_dwordx4 v[134:135], v[130:133], off nt

.LBB0_272:
	s_and_b64 vcc, exec, s[34:35]
	s_cbranch_vccz .LBB0_274
	s_lshl_b32 s18, s30, 11
	s_addk_i32 s18, 0xa000
	s_ashr_i32 s19, s18, 31
	s_mov_b64 s[30:31], s[38:39]
	v_readlane_b32 s36, v251, 8
	s_lshl_b64 s[18:19], s[18:19], 2
	v_readlane_b32 s44, v251, 16
	v_readlane_b32 s45, v251, 17
	s_add_u32 s18, s44, s18
	s_addc_u32 s19, s45, s19
	v_ashrrev_i32_e32 v177, 31, v176
	v_lshl_add_u64 v[134:135], v[176:177], 2, s[18:19]
	global_load_dwordx4 v[138:141], v[134:135], off offset:16
	global_load_dwordx4 v[142:145], v[134:135], off
	global_load_dwordx4 v[130:133], v[134:135], off offset:528
	s_nop 0
	global_load_dwordx4 v[134:137], v[134:135], off offset:512
	v_ashrrev_i32_e32 v175, 31, v174
	v_lshl_add_u64 v[150:151], v[176:177], 1, s[0:1]
	v_lshlrev_b64 v[148:149], 12, v[174:175]
	v_lshl_add_u64 v[148:149], v[150:151], 0, v[148:149]
	s_mov_b32 s18, 0x80000
	v_readlane_b32 s38, v251, 10
	v_readlane_b32 s39, v251, 11
	v_readlane_b32 s44, v251, 6
	v_readlane_b32 s37, v251, 9
	v_readlane_b32 s40, v251, 12
	v_readlane_b32 s41, v251, 13
	v_readlane_b32 s42, v251, 14
	v_readlane_b32 s43, v251, 15
	v_readlane_b32 s46, v251, 18
	v_readlane_b32 s47, v251, 19
	v_readlane_b32 s48, v251, 20
	v_readlane_b32 s49, v251, 21
	v_readlane_b32 s50, v251, 22
	v_readlane_b32 s51, v251, 23
	s_mov_b64 s[38:39], s[30:31]
	v_readlane_b32 s36, v254, 6
	v_readlane_b32 s45, v251, 7
	s_waitcnt vmcnt(0)
	v_pk_add_f32 v[152:153], v[128:129], v[144:145]
	s_nop 0
	v_mul_f32_e32 v152, 0xbfb8aa3b, v152
	v_exp_f32_e32 v152, v152
	v_pk_add_f32 v[154:155], v[126:127], v[142:143]
	v_add_f32_e32 v152, 1.0, v152
	v_rcp_f32_e32 v157, v152
	v_mul_f32_e32 v152, 0xbfb8aa3b, v153
	v_exp_f32_e32 v152, v152
	v_mul_f32_e32 v147, 0xbfb8aa3b, v154
	v_mul_f32_e32 v154, 0xbfb8aa3b, v155
	v_exp_f32_e32 v154, v154
	v_add_f32_e32 v152, 1.0, v152
	v_rcp_f32_e32 v158, v152
	v_pk_add_f32 v[152:153], v[124:125], v[140:141]
	v_add_f32_e32 v154, 1.0, v154
	v_mul_f32_e32 v152, 0xbfb8aa3b, v152
	v_exp_f32_e32 v152, v152
	v_rcp_f32_e32 v156, v154
	v_pk_add_f32 v[154:155], v[122:123], v[138:139]
	v_exp_f32_e32 v147, v147
	v_add_f32_e32 v152, 1.0, v152
	v_mul_f32_e32 v154, 0xbfb8aa3b, v154
	v_mul_f32_e32 v155, 0xbfb8aa3b, v155
	v_rcp_f32_e32 v159, v152
	v_mul_f32_e32 v152, 0xbfb8aa3b, v153
	v_exp_f32_e32 v154, v154
	v_exp_f32_e32 v155, v155
	v_exp_f32_e32 v152, v152
	v_add_f32_e32 v147, 1.0, v147
	v_add_f32_e32 v154, 1.0, v154
	v_add_f32_e32 v155, 1.0, v155
	v_add_f32_e32 v152, 1.0, v152
	v_rcp_f32_e32 v147, v147
	v_rcp_f32_e32 v154, v154
	v_rcp_f32_e32 v155, v155
	v_rcp_f32_e32 v160, v152
	v_cvt_pk_bf16_f32 v152, v147, v156
	v_cvt_pk_bf16_f32 v153, v157, v158
	v_cvt_pk_bf16_f32 v154, v154, v155
	v_cvt_pk_bf16_f32 v155, v159, v160
	global_store_dwordx4 v[148:149], v[152:155], off nt
	s_nop 1
	v_pk_add_f32 v[152:153], v[120:121], v[136:137]
	v_pk_add_f32 v[154:155], v[118:119], v[134:135]
	v_mul_f32_e32 v152, 0xbfb8aa3b, v152
	v_exp_f32_e32 v152, v152
	v_mul_f32_e32 v147, 0xbfb8aa3b, v154
	v_mul_f32_e32 v154, 0xbfb8aa3b, v155
	v_exp_f32_e32 v154, v154
	v_add_f32_e32 v152, 1.0, v152
	v_rcp_f32_e32 v157, v152
	v_mul_f32_e32 v152, 0xbfb8aa3b, v153
	v_exp_f32_e32 v152, v152
	v_add_f32_e32 v154, 1.0, v154
	v_rcp_f32_e32 v156, v154
	v_pk_add_f32 v[154:155], v[114:115], v[130:131]
	v_add_f32_e32 v152, 1.0, v152
	v_rcp_f32_e32 v158, v152
	v_pk_add_f32 v[152:153], v[116:117], v[132:133]
	v_mul_f32_e32 v154, 0xbfb8aa3b, v154
	v_mul_f32_e32 v152, 0xbfb8aa3b, v152
	v_exp_f32_e32 v152, v152
	v_mul_f32_e32 v155, 0xbfb8aa3b, v155
	v_exp_f32_e32 v147, v147
	v_exp_f32_e32 v154, v154
	v_add_f32_e32 v152, 1.0, v152
	v_rcp_f32_e32 v159, v152
	v_mul_f32_e32 v152, 0xbfb8aa3b, v153
	v_exp_f32_e32 v155, v155
	v_exp_f32_e32 v152, v152
	v_add_f32_e32 v147, 1.0, v147
	v_add_f32_e32 v154, 1.0, v154
	v_add_f32_e32 v155, 1.0, v155
	v_add_f32_e32 v152, 1.0, v152
	v_rcp_f32_e32 v147, v147
	v_rcp_f32_e32 v154, v154
	v_rcp_f32_e32 v155, v155
	v_rcp_f32_e32 v160, v152
	v_cvt_pk_bf16_f32 v152, v147, v156
	v_cvt_pk_bf16_f32 v153, v157, v158
	v_cvt_pk_bf16_f32 v154, v154, v155
	v_cvt_pk_bf16_f32 v155, v159, v160
	global_store_dwordx4 v[148:149], v[152:155], off offset:256 nt
	v_pk_add_f32 v[156:157], v[110:111], v[142:143]
	s_nop 0
	v_pk_add_f32 v[154:155], v[112:113], v[144:145]
	v_mul_f32_e32 v147, 0xbfb8aa3b, v156
	v_mul_f32_e32 v154, 0xbfb8aa3b, v154
	v_exp_f32_e32 v154, v154
	v_mul_f32_e32 v156, 0xbfb8aa3b, v157
	v_exp_f32_e32 v156, v156
	v_exp_f32_e32 v147, v147
	v_add_f32_e32 v154, 1.0, v154
	v_rcp_f32_e32 v159, v154
	v_mul_f32_e32 v154, 0xbfb8aa3b, v155
	v_exp_f32_e32 v154, v154
	v_add_f32_e32 v156, 1.0, v156
	v_rcp_f32_e32 v158, v156
	v_pk_add_f32 v[156:157], v[106:107], v[138:139]
	v_add_f32_e32 v154, 1.0, v154
	v_rcp_f32_e32 v160, v154
	v_pk_add_f32 v[154:155], v[108:109], v[140:141]
	v_mul_f32_e32 v156, 0xbfb8aa3b, v156
	v_mul_f32_e32 v154, 0xbfb8aa3b, v154
	v_exp_f32_e32 v154, v154
	v_mul_f32_e32 v157, 0xbfb8aa3b, v157
	v_exp_f32_e32 v156, v156
	v_exp_f32_e32 v157, v157
	v_add_f32_e32 v154, 1.0, v154
	v_rcp_f32_e32 v161, v154
	v_mul_f32_e32 v154, 0xbfb8aa3b, v155
	v_exp_f32_e32 v154, v154
	v_add_f32_e32 v147, 1.0, v147
	v_add_f32_e32 v156, 1.0, v156
	v_add_f32_e32 v157, 1.0, v157
	v_add_f32_e32 v154, 1.0, v154
	v_rcp_f32_e32 v147, v147
	v_rcp_f32_e32 v156, v156
	v_rcp_f32_e32 v157, v157
	v_rcp_f32_e32 v175, v154
	v_or_b32_e32 v152, 16, v174
	v_ashrrev_i32_e32 v153, 31, v152
	v_lshlrev_b64 v[152:153], 12, v[152:153]
	v_lshl_add_u64 v[152:153], v[150:151], 0, v[152:153]
	v_cvt_pk_bf16_f32 v154, v147, v158
	v_cvt_pk_bf16_f32 v155, v159, v160
	v_cvt_pk_bf16_f32 v156, v156, v157
	v_cvt_pk_bf16_f32 v157, v161, v175
	global_store_dwordx4 v[152:153], v[154:157], off nt
	s_nop 1
	v_pk_add_f32 v[154:155], v[104:105], v[136:137]
	v_pk_add_f32 v[156:157], v[102:103], v[134:135]
	v_mul_f32_e32 v154, 0xbfb8aa3b, v154
	v_exp_f32_e32 v154, v154
	v_mul_f32_e32 v147, 0xbfb8aa3b, v156
	v_mul_f32_e32 v156, 0xbfb8aa3b, v157
	v_exp_f32_e32 v156, v156
	v_add_f32_e32 v154, 1.0, v154
	v_rcp_f32_e32 v159, v154
	v_mul_f32_e32 v154, 0xbfb8aa3b, v155
	v_exp_f32_e32 v154, v154
	v_add_f32_e32 v156, 1.0, v156
	v_rcp_f32_e32 v158, v156
	v_pk_add_f32 v[156:157], v[98:99], v[130:131]
	v_add_f32_e32 v154, 1.0, v154
	v_rcp_f32_e32 v160, v154
	v_pk_add_f32 v[154:155], v[100:101], v[132:133]
	v_mul_f32_e32 v156, 0xbfb8aa3b, v156
	v_mul_f32_e32 v154, 0xbfb8aa3b, v154
	v_exp_f32_e32 v154, v154
	v_mul_f32_e32 v157, 0xbfb8aa3b, v157
	v_exp_f32_e32 v147, v147
	v_exp_f32_e32 v156, v156
	v_add_f32_e32 v154, 1.0, v154
	v_rcp_f32_e32 v161, v154
	v_mul_f32_e32 v154, 0xbfb8aa3b, v155
	v_exp_f32_e32 v157, v157
	v_exp_f32_e32 v154, v154
	v_add_f32_e32 v147, 1.0, v147
	v_add_f32_e32 v156, 1.0, v156
	v_add_f32_e32 v157, 1.0, v157
	v_add_f32_e32 v154, 1.0, v154
	v_rcp_f32_e32 v147, v147
	v_rcp_f32_e32 v156, v156
	v_rcp_f32_e32 v157, v157
	v_rcp_f32_e32 v175, v154
	v_cvt_pk_bf16_f32 v154, v147, v158
	v_cvt_pk_bf16_f32 v155, v159, v160
	v_cvt_pk_bf16_f32 v156, v156, v157
	v_cvt_pk_bf16_f32 v157, v161, v175
	global_store_dwordx4 v[152:153], v[154:157], off offset:256 nt
	v_or_b32_e32 v152, 32, v174
	v_ashrrev_i32_e32 v153, 31, v152
	v_pk_add_f32 v[154:155], v[96:97], v[144:145]
	v_pk_add_f32 v[156:157], v[94:95], v[142:143]
	v_mul_f32_e32 v154, 0xbfb8aa3b, v154
	v_exp_f32_e32 v154, v154
	v_mul_f32_e32 v147, 0xbfb8aa3b, v156
	v_mul_f32_e32 v156, 0xbfb8aa3b, v157
	v_exp_f32_e32 v156, v156
	v_add_f32_e32 v154, 1.0, v154
	v_rcp_f32_e32 v159, v154
	v_mul_f32_e32 v154, 0xbfb8aa3b, v155
	v_exp_f32_e32 v154, v154
	v_add_f32_e32 v156, 1.0, v156
	v_rcp_f32_e32 v158, v156
	v_pk_add_f32 v[156:157], v[90:91], v[138:139]
	v_add_f32_e32 v154, 1.0, v154
	v_rcp_f32_e32 v160, v154
	v_pk_add_f32 v[154:155], v[92:93], v[140:141]
	v_mul_f32_e32 v156, 0xbfb8aa3b, v156
	v_mul_f32_e32 v154, 0xbfb8aa3b, v154
	v_exp_f32_e32 v154, v154
	v_mul_f32_e32 v157, 0xbfb8aa3b, v157
	v_exp_f32_e32 v147, v147
	v_exp_f32_e32 v156, v156
	v_add_f32_e32 v154, 1.0, v154
	v_rcp_f32_e32 v161, v154
	v_mul_f32_e32 v154, 0xbfb8aa3b, v155
	v_exp_f32_e32 v157, v157
	v_exp_f32_e32 v154, v154
	v_add_f32_e32 v147, 1.0, v147
	v_add_f32_e32 v156, 1.0, v156
	v_add_f32_e32 v157, 1.0, v157
	v_add_f32_e32 v154, 1.0, v154
	v_rcp_f32_e32 v147, v147
	v_rcp_f32_e32 v156, v156
	v_rcp_f32_e32 v157, v157
	v_rcp_f32_e32 v175, v154
	v_lshlrev_b64 v[152:153], 12, v[152:153]
	v_lshl_add_u64 v[152:153], v[150:151], 0, v[152:153]
	v_cvt_pk_bf16_f32 v154, v147, v158
	v_cvt_pk_bf16_f32 v155, v159, v160
	v_cvt_pk_bf16_f32 v156, v156, v157
	v_cvt_pk_bf16_f32 v157, v161, v175
	global_store_dwordx4 v[152:153], v[154:157], off nt
	s_nop 1
	v_pk_add_f32 v[154:155], v[88:89], v[136:137]
	v_pk_add_f32 v[156:157], v[86:87], v[134:135]
	v_mul_f32_e32 v154, 0xbfb8aa3b, v154
	v_exp_f32_e32 v154, v154
	v_mul_f32_e32 v147, 0xbfb8aa3b, v156
	v_mul_f32_e32 v156, 0xbfb8aa3b, v157
	v_exp_f32_e32 v156, v156
	v_add_f32_e32 v154, 1.0, v154
	v_rcp_f32_e32 v159, v154
	v_mul_f32_e32 v154, 0xbfb8aa3b, v155
	v_exp_f32_e32 v154, v154
	v_add_f32_e32 v156, 1.0, v156
	v_rcp_f32_e32 v158, v156
	v_pk_add_f32 v[156:157], v[82:83], v[130:131]
	v_add_f32_e32 v154, 1.0, v154
	v_rcp_f32_e32 v160, v154
	v_pk_add_f32 v[154:155], v[84:85], v[132:133]
	v_mul_f32_e32 v156, 0xbfb8aa3b, v156
	v_mul_f32_e32 v154, 0xbfb8aa3b, v154
	v_exp_f32_e32 v154, v154
	v_mul_f32_e32 v157, 0xbfb8aa3b, v157
	v_exp_f32_e32 v147, v147
	v_exp_f32_e32 v156, v156
	v_add_f32_e32 v154, 1.0, v154
	v_rcp_f32_e32 v161, v154
	v_mul_f32_e32 v154, 0xbfb8aa3b, v155
	v_exp_f32_e32 v157, v157
	v_exp_f32_e32 v154, v154
	v_add_f32_e32 v147, 1.0, v147
	v_add_f32_e32 v156, 1.0, v156
	v_add_f32_e32 v157, 1.0, v157
	v_add_f32_e32 v154, 1.0, v154
	v_rcp_f32_e32 v147, v147
	v_rcp_f32_e32 v156, v156
	v_rcp_f32_e32 v157, v157
	v_rcp_f32_e32 v175, v154
	v_cvt_pk_bf16_f32 v154, v147, v158
	v_cvt_pk_bf16_f32 v155, v159, v160
	v_cvt_pk_bf16_f32 v156, v156, v157
	v_cvt_pk_bf16_f32 v157, v161, v175
	global_store_dwordx4 v[152:153], v[154:157], off offset:256 nt
	v_or_b32_e32 v152, 48, v174
	v_ashrrev_i32_e32 v153, 31, v152
	v_lshlrev_b64 v[152:153], 12, v[152:153]
	v_lshl_add_u64 v[150:151], v[150:151], 0, v[152:153]
	v_pk_add_f32 v[152:153], v[80:81], v[144:145]
	v_pk_add_f32 v[154:155], v[78:79], v[142:143]
	v_mul_f32_e32 v152, 0xbfb8aa3b, v152
	v_exp_f32_e32 v152, v152
	v_mul_f32_e32 v147, 0xbfb8aa3b, v154
	v_mul_f32_e32 v154, 0xbfb8aa3b, v155
	v_exp_f32_e32 v154, v154
	v_add_f32_e32 v152, 1.0, v152
	v_rcp_f32_e32 v157, v152
	v_mul_f32_e32 v152, 0xbfb8aa3b, v153
	v_exp_f32_e32 v152, v152
	v_add_f32_e32 v154, 1.0, v154
	v_rcp_f32_e32 v156, v154
	v_pk_add_f32 v[154:155], v[74:75], v[138:139]
	v_add_f32_e32 v152, 1.0, v152
	v_rcp_f32_e32 v158, v152
	v_pk_add_f32 v[152:153], v[76:77], v[140:141]
	v_mul_f32_e32 v154, 0xbfb8aa3b, v154
	v_mul_f32_e32 v152, 0xbfb8aa3b, v152
	v_exp_f32_e32 v152, v152
	v_mul_f32_e32 v155, 0xbfb8aa3b, v155
	v_exp_f32_e32 v147, v147
	v_exp_f32_e32 v154, v154
	v_add_f32_e32 v152, 1.0, v152
	v_rcp_f32_e32 v159, v152
	v_mul_f32_e32 v152, 0xbfb8aa3b, v153
	v_exp_f32_e32 v155, v155
	v_exp_f32_e32 v152, v152
	v_add_f32_e32 v147, 1.0, v147
	v_add_f32_e32 v154, 1.0, v154
	v_add_f32_e32 v155, 1.0, v155
	v_add_f32_e32 v152, 1.0, v152
	v_rcp_f32_e32 v147, v147
	v_rcp_f32_e32 v154, v154
	v_rcp_f32_e32 v155, v155
	v_rcp_f32_e32 v160, v152
	v_cvt_pk_bf16_f32 v152, v147, v156
	v_cvt_pk_bf16_f32 v153, v157, v158
	v_cvt_pk_bf16_f32 v154, v154, v155
	v_cvt_pk_bf16_f32 v155, v159, v160
	global_store_dwordx4 v[150:151], v[152:155], off nt
	s_nop 1
	v_pk_add_f32 v[152:153], v[72:73], v[136:137]
	v_pk_add_f32 v[154:155], v[70:71], v[134:135]
	v_mul_f32_e32 v152, 0xbfb8aa3b, v152
	v_exp_f32_e32 v152, v152
	v_mul_f32_e32 v147, 0xbfb8aa3b, v154
	v_mul_f32_e32 v154, 0xbfb8aa3b, v155
	v_exp_f32_e32 v154, v154
	v_add_f32_e32 v152, 1.0, v152
	v_rcp_f32_e32 v157, v152
	v_mul_f32_e32 v152, 0xbfb8aa3b, v153
	v_exp_f32_e32 v152, v152
	v_add_f32_e32 v154, 1.0, v154
	v_rcp_f32_e32 v156, v154
	v_pk_add_f32 v[154:155], v[66:67], v[130:131]
	v_add_f32_e32 v152, 1.0, v152
	v_rcp_f32_e32 v158, v152
	v_pk_add_f32 v[152:153], v[68:69], v[132:133]
	v_mul_f32_e32 v154, 0xbfb8aa3b, v154
	v_mul_f32_e32 v152, 0xbfb8aa3b, v152
	v_exp_f32_e32 v152, v152
	v_mul_f32_e32 v155, 0xbfb8aa3b, v155
	v_exp_f32_e32 v147, v147
	v_exp_f32_e32 v154, v154
	v_add_f32_e32 v152, 1.0, v152
	v_rcp_f32_e32 v159, v152
	v_mul_f32_e32 v152, 0xbfb8aa3b, v153
	v_exp_f32_e32 v155, v155
	v_exp_f32_e32 v152, v152
	v_add_f32_e32 v147, 1.0, v147
	v_add_f32_e32 v154, 1.0, v154
	v_add_f32_e32 v155, 1.0, v155
	v_add_f32_e32 v152, 1.0, v152
	v_rcp_f32_e32 v147, v147
	v_rcp_f32_e32 v154, v154
	v_rcp_f32_e32 v155, v155
	v_rcp_f32_e32 v160, v152
	v_cvt_pk_bf16_f32 v152, v147, v156
	v_cvt_pk_bf16_f32 v153, v157, v158
	v_cvt_pk_bf16_f32 v154, v154, v155
	v_cvt_pk_bf16_f32 v155, v159, v160
	global_store_dwordx4 v[150:151], v[152:155], off offset:256 nt
	v_lshl_add_u64 v[150:151], v[148:149], 0, s[10:11]
	s_nop 0
	v_pk_add_f32 v[152:153], v[64:65], v[144:145]
	v_pk_add_f32 v[154:155], v[62:63], v[142:143]
	v_mul_f32_e32 v152, 0xbfb8aa3b, v152
	v_exp_f32_e32 v152, v152
	v_mul_f32_e32 v147, 0xbfb8aa3b, v154
	v_mul_f32_e32 v154, 0xbfb8aa3b, v155
	v_exp_f32_e32 v154, v154
	v_add_f32_e32 v152, 1.0, v152
	v_rcp_f32_e32 v157, v152
	v_mul_f32_e32 v152, 0xbfb8aa3b, v153
	v_exp_f32_e32 v152, v152
	v_add_f32_e32 v154, 1.0, v154
	v_rcp_f32_e32 v156, v154
	v_pk_add_f32 v[154:155], v[58:59], v[138:139]
	v_add_f32_e32 v152, 1.0, v152
	v_rcp_f32_e32 v158, v152
	v_pk_add_f32 v[152:153], v[60:61], v[140:141]
	v_exp_f32_e32 v147, v147
	v_mul_f32_e32 v152, 0xbfb8aa3b, v152
	v_exp_f32_e32 v152, v152
	v_mul_f32_e32 v154, 0xbfb8aa3b, v154
	v_mul_f32_e32 v155, 0xbfb8aa3b, v155
	v_exp_f32_e32 v154, v154
	v_add_f32_e32 v152, 1.0, v152
	v_rcp_f32_e32 v159, v152
	v_mul_f32_e32 v152, 0xbfb8aa3b, v153
	v_exp_f32_e32 v155, v155
	v_exp_f32_e32 v152, v152
	v_add_f32_e32 v147, 1.0, v147
	v_rcp_f32_e32 v147, v147
	v_add_f32_e32 v154, 1.0, v154
	v_add_f32_e32 v155, 1.0, v155
	v_add_f32_e32 v152, 1.0, v152
	v_rcp_f32_e32 v154, v154
	v_rcp_f32_e32 v155, v155
	v_rcp_f32_e32 v160, v152
	v_cvt_pk_bf16_f32 v152, v147, v156
	v_add_co_u32_e32 v156, vcc, s18, v148
	v_cvt_pk_bf16_f32 v153, v157, v158
	v_cvt_pk_bf16_f32 v154, v154, v155
	v_cvt_pk_bf16_f32 v155, v159, v160
	v_addc_co_u32_e32 v157, vcc, 0, v149, vcc
	global_store_dwordx4 v[156:157], v[152:155], off nt
	s_mov_b64 s[18:19], 0x90000
	s_nop 0
	v_pk_add_f32 v[152:153], v[56:57], v[136:137]
	v_pk_add_f32 v[154:155], v[54:55], v[134:135]
	v_mul_f32_e32 v152, 0xbfb8aa3b, v152
	v_exp_f32_e32 v152, v152
	v_mul_f32_e32 v147, 0xbfb8aa3b, v154
	v_mul_f32_e32 v154, 0xbfb8aa3b, v155
	v_exp_f32_e32 v154, v154
	v_add_f32_e32 v152, 1.0, v152
	v_rcp_f32_e32 v157, v152
	v_mul_f32_e32 v152, 0xbfb8aa3b, v153
	v_exp_f32_e32 v152, v152
	v_add_f32_e32 v154, 1.0, v154
	v_rcp_f32_e32 v156, v154
	v_pk_add_f32 v[154:155], v[50:51], v[130:131]
	v_add_f32_e32 v152, 1.0, v152
	v_rcp_f32_e32 v158, v152
	v_pk_add_f32 v[152:153], v[52:53], v[132:133]
	v_mul_f32_e32 v154, 0xbfb8aa3b, v154
	v_mul_f32_e32 v152, 0xbfb8aa3b, v152
	v_exp_f32_e32 v152, v152
	v_mul_f32_e32 v155, 0xbfb8aa3b, v155
	v_exp_f32_e32 v147, v147
	v_exp_f32_e32 v154, v154
	v_add_f32_e32 v152, 1.0, v152
	v_rcp_f32_e32 v159, v152
	v_mul_f32_e32 v152, 0xbfb8aa3b, v153
	v_exp_f32_e32 v155, v155
	v_exp_f32_e32 v152, v152
	v_add_f32_e32 v147, 1.0, v147
	v_add_f32_e32 v154, 1.0, v154
	v_add_f32_e32 v155, 1.0, v155
	v_add_f32_e32 v152, 1.0, v152
	v_rcp_f32_e32 v147, v147
	v_rcp_f32_e32 v154, v154
	v_rcp_f32_e32 v155, v155
	v_rcp_f32_e32 v160, v152
	v_cvt_pk_bf16_f32 v152, v147, v156
	v_cvt_pk_bf16_f32 v153, v157, v158
	v_cvt_pk_bf16_f32 v154, v154, v155
	v_cvt_pk_bf16_f32 v155, v159, v160
	global_store_dwordx4 v[150:151], v[152:155], off offset:256 nt
	v_lshl_add_u64 v[150:151], v[148:149], 0, s[18:19]
	s_mov_b32 s18, 0x90000
	v_pk_add_f32 v[152:153], v[48:49], v[144:145]
	v_pk_add_f32 v[154:155], v[46:47], v[142:143]
	v_mul_f32_e32 v152, 0xbfb8aa3b, v152
	v_exp_f32_e32 v152, v152
	v_mul_f32_e32 v147, 0xbfb8aa3b, v154
	v_mul_f32_e32 v154, 0xbfb8aa3b, v155
	v_exp_f32_e32 v154, v154
	v_add_f32_e32 v152, 1.0, v152
	v_rcp_f32_e32 v157, v152
	v_mul_f32_e32 v152, 0xbfb8aa3b, v153
	v_exp_f32_e32 v152, v152
	v_add_f32_e32 v154, 1.0, v154
	v_rcp_f32_e32 v156, v154
	v_pk_add_f32 v[154:155], v[42:43], v[138:139]
	v_add_f32_e32 v152, 1.0, v152
	v_rcp_f32_e32 v158, v152
	v_pk_add_f32 v[152:153], v[44:45], v[140:141]
	v_exp_f32_e32 v147, v147
	v_mul_f32_e32 v152, 0xbfb8aa3b, v152
	v_exp_f32_e32 v152, v152
	v_mul_f32_e32 v154, 0xbfb8aa3b, v154
	v_mul_f32_e32 v155, 0xbfb8aa3b, v155
	v_exp_f32_e32 v154, v154
	v_add_f32_e32 v152, 1.0, v152
	v_rcp_f32_e32 v159, v152
	v_mul_f32_e32 v152, 0xbfb8aa3b, v153
	v_exp_f32_e32 v155, v155
	v_exp_f32_e32 v152, v152
	v_add_f32_e32 v147, 1.0, v147
	v_rcp_f32_e32 v147, v147
	v_add_f32_e32 v154, 1.0, v154
	v_add_f32_e32 v155, 1.0, v155
	v_add_f32_e32 v152, 1.0, v152
	v_rcp_f32_e32 v154, v154
	v_rcp_f32_e32 v155, v155
	v_rcp_f32_e32 v160, v152
	v_cvt_pk_bf16_f32 v152, v147, v156
	v_add_co_u32_e32 v156, vcc, s18, v148
	v_cvt_pk_bf16_f32 v153, v157, v158
	v_cvt_pk_bf16_f32 v154, v154, v155
	v_cvt_pk_bf16_f32 v155, v159, v160
	v_addc_co_u32_e32 v157, vcc, 0, v149, vcc
	global_store_dwordx4 v[156:157], v[152:155], off nt
	s_mov_b64 s[18:19], 0xa0000
	s_nop 0
	v_pk_add_f32 v[152:153], v[40:41], v[136:137]
	v_pk_add_f32 v[154:155], v[38:39], v[134:135]
	v_mul_f32_e32 v152, 0xbfb8aa3b, v152
	v_exp_f32_e32 v152, v152
	v_mul_f32_e32 v147, 0xbfb8aa3b, v154
	v_mul_f32_e32 v154, 0xbfb8aa3b, v155
	v_exp_f32_e32 v154, v154
	v_add_f32_e32 v152, 1.0, v152
	v_rcp_f32_e32 v157, v152
	v_mul_f32_e32 v152, 0xbfb8aa3b, v153
	v_exp_f32_e32 v152, v152
	v_add_f32_e32 v154, 1.0, v154
	v_rcp_f32_e32 v156, v154
	v_pk_add_f32 v[154:155], v[34:35], v[130:131]
	v_add_f32_e32 v152, 1.0, v152
	v_rcp_f32_e32 v158, v152
	v_pk_add_f32 v[152:153], v[36:37], v[132:133]
	v_mul_f32_e32 v154, 0xbfb8aa3b, v154
	v_mul_f32_e32 v152, 0xbfb8aa3b, v152
	v_exp_f32_e32 v152, v152
	v_mul_f32_e32 v155, 0xbfb8aa3b, v155
	v_exp_f32_e32 v147, v147
	v_exp_f32_e32 v154, v154
	v_add_f32_e32 v152, 1.0, v152
	v_rcp_f32_e32 v159, v152
	v_mul_f32_e32 v152, 0xbfb8aa3b, v153
	v_exp_f32_e32 v155, v155
	v_exp_f32_e32 v152, v152
	v_add_f32_e32 v147, 1.0, v147
	v_add_f32_e32 v154, 1.0, v154
	v_add_f32_e32 v155, 1.0, v155
	v_add_f32_e32 v152, 1.0, v152
	v_rcp_f32_e32 v147, v147
	v_rcp_f32_e32 v154, v154
	v_rcp_f32_e32 v155, v155
	v_rcp_f32_e32 v160, v152
	v_cvt_pk_bf16_f32 v152, v147, v156
	v_cvt_pk_bf16_f32 v153, v157, v158
	v_cvt_pk_bf16_f32 v154, v154, v155
	v_cvt_pk_bf16_f32 v155, v159, v160
	global_store_dwordx4 v[150:151], v[152:155], off offset:256 nt
	v_lshl_add_u64 v[150:151], v[148:149], 0, s[18:19]
	s_mov_b32 s18, 0xa0000
	v_pk_add_f32 v[152:153], v[32:33], v[144:145]
	v_pk_add_f32 v[154:155], v[30:31], v[142:143]
	v_mul_f32_e32 v152, 0xbfb8aa3b, v152
	v_exp_f32_e32 v152, v152
	v_mul_f32_e32 v147, 0xbfb8aa3b, v154
	v_mul_f32_e32 v154, 0xbfb8aa3b, v155
	v_exp_f32_e32 v154, v154
	v_add_f32_e32 v152, 1.0, v152
	v_rcp_f32_e32 v157, v152
	v_mul_f32_e32 v152, 0xbfb8aa3b, v153
	v_exp_f32_e32 v152, v152
	v_add_f32_e32 v154, 1.0, v154
	v_rcp_f32_e32 v156, v154
	v_pk_add_f32 v[154:155], v[26:27], v[138:139]
	v_add_f32_e32 v152, 1.0, v152
	v_rcp_f32_e32 v158, v152
	v_pk_add_f32 v[152:153], v[28:29], v[140:141]
	v_exp_f32_e32 v147, v147
	v_mul_f32_e32 v152, 0xbfb8aa3b, v152
	v_exp_f32_e32 v152, v152
	v_mul_f32_e32 v154, 0xbfb8aa3b, v154
	v_mul_f32_e32 v155, 0xbfb8aa3b, v155
	v_exp_f32_e32 v154, v154
	v_add_f32_e32 v152, 1.0, v152
	v_rcp_f32_e32 v159, v152
	v_mul_f32_e32 v152, 0xbfb8aa3b, v153
	v_exp_f32_e32 v155, v155
	v_exp_f32_e32 v152, v152
	v_add_f32_e32 v147, 1.0, v147
	v_rcp_f32_e32 v147, v147
	v_add_f32_e32 v154, 1.0, v154
	v_add_f32_e32 v155, 1.0, v155
	v_add_f32_e32 v152, 1.0, v152
	v_rcp_f32_e32 v154, v154
	v_rcp_f32_e32 v155, v155
	v_rcp_f32_e32 v160, v152
	v_cvt_pk_bf16_f32 v152, v147, v156
	v_add_co_u32_e32 v156, vcc, s18, v148
	v_cvt_pk_bf16_f32 v153, v157, v158
	v_cvt_pk_bf16_f32 v154, v154, v155
	v_cvt_pk_bf16_f32 v155, v159, v160
	v_addc_co_u32_e32 v157, vcc, 0, v149, vcc
	global_store_dwordx4 v[156:157], v[152:155], off nt
	v_pk_add_f32 v[138:139], v[10:11], v[138:139]
	v_pk_add_f32 v[140:141], v[12:13], v[140:141]
	v_pk_add_f32 v[152:153], v[24:25], v[136:137]
	v_pk_add_f32 v[154:155], v[22:23], v[134:135]
	v_mul_f32_e32 v152, 0xbfb8aa3b, v152
	v_exp_f32_e32 v152, v152
	v_mul_f32_e32 v147, 0xbfb8aa3b, v154
	v_mul_f32_e32 v154, 0xbfb8aa3b, v155
	v_exp_f32_e32 v154, v154
	v_add_f32_e32 v152, 1.0, v152
	v_rcp_f32_e32 v157, v152
	v_mul_f32_e32 v152, 0xbfb8aa3b, v153
	v_exp_f32_e32 v152, v152
	v_exp_f32_e32 v147, v147
	v_add_f32_e32 v154, 1.0, v154
	v_rcp_f32_e32 v156, v154
	v_add_f32_e32 v152, 1.0, v152
	v_rcp_f32_e32 v158, v152
	v_pk_add_f32 v[152:153], v[20:21], v[132:133]
	v_pk_add_f32 v[154:155], v[18:19], v[130:131]
	v_mul_f32_e32 v152, 0xbfb8aa3b, v152
	v_exp_f32_e32 v152, v152
	v_mul_f32_e32 v138, 0xbfb8aa3b, v138
	v_add_f32_e32 v147, 1.0, v147
	v_mul_f32_e32 v154, 0xbfb8aa3b, v154
	v_add_f32_e32 v152, 1.0, v152
	v_rcp_f32_e32 v159, v152
	v_mul_f32_e32 v152, 0xbfb8aa3b, v153
	v_mul_f32_e32 v155, 0xbfb8aa3b, v155
	v_exp_f32_e32 v152, v152
	v_exp_f32_e32 v138, v138
	v_rcp_f32_e32 v147, v147
	v_exp_f32_e32 v154, v154
	v_exp_f32_e32 v155, v155
	v_add_f32_e32 v152, 1.0, v152
	v_add_f32_e32 v138, 1.0, v138
	v_add_f32_e32 v154, 1.0, v154
	v_add_f32_e32 v155, 1.0, v155
	v_rcp_f32_e32 v160, v152
	v_cvt_pk_bf16_f32 v152, v147, v156
	v_rcp_f32_e32 v147, v138
	v_mul_f32_e32 v138, 0xbfb8aa3b, v139
	v_rcp_f32_e32 v154, v154
	v_rcp_f32_e32 v155, v155
	v_exp_f32_e32 v138, v138
	v_cvt_pk_bf16_f32 v153, v157, v158
	v_pk_add_f32 v[142:143], v[14:15], v[142:143]
	v_cvt_pk_bf16_f32 v154, v154, v155
	v_cvt_pk_bf16_f32 v155, v159, v160
	v_add_f32_e32 v138, 1.0, v138
	global_store_dwordx4 v[150:151], v[152:155], off offset:256 nt
	v_pk_add_f32 v[144:145], v[16:17], v[144:145]
	v_mul_f32_e32 v142, 0xbfb8aa3b, v142
	v_rcp_f32_e32 v152, v138
	v_mul_f32_e32 v138, 0xbfb8aa3b, v140
	v_exp_f32_e32 v138, v138
	v_mul_f32_e32 v143, 0xbfb8aa3b, v143
	v_exp_f32_e32 v142, v142
	v_exp_f32_e32 v143, v143
	v_add_f32_e32 v138, 1.0, v138
	v_mul_f32_e32 v144, 0xbfb8aa3b, v144
	v_mul_f32_e32 v145, 0xbfb8aa3b, v145
	v_rcp_f32_e32 v153, v138
	v_mul_f32_e32 v138, 0xbfb8aa3b, v141
	v_exp_f32_e32 v144, v144
	v_exp_f32_e32 v145, v145
	v_exp_f32_e32 v138, v138
	v_add_f32_e32 v142, 1.0, v142
	v_add_f32_e32 v143, 1.0, v143
	v_pk_add_f32 v[130:131], v[2:3], v[130:131]
	v_rcp_f32_e32 v142, v142
	v_rcp_f32_e32 v143, v143
	v_add_f32_e32 v144, 1.0, v144
	v_add_f32_e32 v145, 1.0, v145
	v_add_f32_e32 v138, 1.0, v138
	v_mul_f32_e32 v130, 0xbfb8aa3b, v130
	v_rcp_f32_e32 v144, v144
	v_rcp_f32_e32 v145, v145
	v_rcp_f32_e32 v141, v138
	v_exp_f32_e32 v130, v130
	s_mov_b64 s[18:19], 0xb0000
	v_lshl_add_u64 v[150:151], v[148:149], 0, s[18:19]
	s_mov_b32 s18, 0xb0000
	v_cvt_pk_bf16_f32 v138, v142, v143
	v_add_co_u32_e32 v142, vcc, s18, v148
	v_cvt_pk_bf16_f32 v139, v144, v145
	v_cvt_pk_bf16_f32 v140, v147, v152
	v_cvt_pk_bf16_f32 v141, v153, v141
	v_addc_co_u32_e32 v143, vcc, 0, v149, vcc
	v_add_f32_e32 v130, 1.0, v130
	global_store_dwordx4 v[142:143], v[138:141], off nt
	v_pk_add_f32 v[132:133], v[4:5], v[132:133]
	v_pk_add_f32 v[136:137], v[8:9], v[136:137]
	v_rcp_f32_e32 v138, v130
	v_mul_f32_e32 v130, 0xbfb8aa3b, v131
	v_exp_f32_e32 v130, v130
	v_pk_add_f32 v[134:135], v[6:7], v[134:135]
	v_mul_f32_e32 v136, 0xbfb8aa3b, v136
	v_mul_f32_e32 v134, 0xbfb8aa3b, v134
	v_add_f32_e32 v130, 1.0, v130
	v_rcp_f32_e32 v139, v130
	v_mul_f32_e32 v130, 0xbfb8aa3b, v132
	v_exp_f32_e32 v130, v130
	v_mul_f32_e32 v135, 0xbfb8aa3b, v135
	v_mul_f32_e32 v137, 0xbfb8aa3b, v137
	v_exp_f32_e32 v134, v134
	v_add_f32_e32 v130, 1.0, v130
	v_rcp_f32_e32 v140, v130
	v_mul_f32_e32 v130, 0xbfb8aa3b, v133
	v_exp_f32_e32 v135, v135
	v_exp_f32_e32 v136, v136
	v_exp_f32_e32 v137, v137
	v_exp_f32_e32 v130, v130
	v_add_f32_e32 v134, 1.0, v134
	v_add_f32_e32 v135, 1.0, v135
	v_add_f32_e32 v136, 1.0, v136
	v_add_f32_e32 v137, 1.0, v137
	v_add_f32_e32 v130, 1.0, v130
	v_rcp_f32_e32 v134, v134
	v_rcp_f32_e32 v135, v135
	v_rcp_f32_e32 v136, v136
	v_rcp_f32_e32 v137, v137
	v_rcp_f32_e32 v133, v130
	v_cvt_pk_bf16_f32 v130, v134, v135
	v_cvt_pk_bf16_f32 v132, v138, v139
	v_cvt_pk_bf16_f32 v131, v136, v137
	v_cvt_pk_bf16_f32 v133, v140, v133
	global_store_dwordx4 v[150:151], v[130:133], off offset:256 nt

.LBB0_275:
	s_and_b64 vcc, exec, s[34:35]
	s_cbranch_vccz .LBB0_280
	s_cmp_gt_i32 s27, 1
	s_mov_b64 s[30:31], -1
	s_cbranch_scc0 .LBB0_278
	v_mul_f32_e32 v134, 0xbfb8aa3b, v126
	v_mul_f32_e32 v135, 0xbfb8aa3b, v127
	v_mul_f32_e32 v136, 0xbfb8aa3b, v128
	v_mul_f32_e32 v137, 0xbfb8aa3b, v129
	v_mul_f32_e32 v138, 0xbfb8aa3b, v122
	v_mul_f32_e32 v139, 0xbfb8aa3b, v123
	v_exp_f32_e32 v134, v134
	v_exp_f32_e32 v135, v135
	v_exp_f32_e32 v136, v136
	v_exp_f32_e32 v137, v137
	v_exp_f32_e32 v138, v138
	v_exp_f32_e32 v139, v139
	v_mul_f32_e32 v140, 0xbfb8aa3b, v124
	v_mul_f32_e32 v141, 0xbfb8aa3b, v125
	v_add_f32_e32 v134, 1.0, v134
	v_add_f32_e32 v135, 1.0, v135
	v_add_f32_e32 v136, 1.0, v136
	v_add_f32_e32 v137, 1.0, v137
	v_add_f32_e32 v138, 1.0, v138
	v_add_f32_e32 v139, 1.0, v139
	v_exp_f32_e32 v140, v140
	v_exp_f32_e32 v141, v141
	v_rcp_f32_e32 v134, v134
	v_rcp_f32_e32 v135, v135
	v_rcp_f32_e32 v136, v136
	v_rcp_f32_e32 v137, v137
	v_rcp_f32_e32 v138, v138
	v_rcp_f32_e32 v139, v139
	v_add_f32_e32 v140, 1.0, v140
	v_add_f32_e32 v141, 1.0, v141
	v_rcp_f32_e32 v140, v140
	v_rcp_f32_e32 v141, v141
	v_pk_mul_f32 v[134:135], v[126:127], v[134:135]
	v_pk_mul_f32 v[136:137], v[128:129], v[136:137]
	v_pk_mul_f32 v[138:139], v[122:123], v[138:139]
	v_cvt_pk_bf16_f32 v134, v134, v135
	v_cvt_pk_bf16_f32 v135, v136, v137
	v_cvt_pk_bf16_f32 v136, v138, v139
	v_mul_f32_e32 v138, 0xbfb8aa3b, v118
	v_mul_f32_e32 v139, 0xbfb8aa3b, v119
	v_exp_f32_e32 v138, v138
	v_exp_f32_e32 v139, v139
	v_ashrrev_i32_e32 v177, 31, v176
	v_ashrrev_i32_e32 v175, 31, v174
	v_lshl_add_u64 v[132:133], v[176:177], 1, s[0:1]
	v_lshlrev_b64 v[130:131], 12, v[174:175]
	v_pk_mul_f32 v[140:141], v[124:125], v[140:141]
	v_lshl_add_u64 v[130:131], v[132:133], 0, v[130:131]
	v_cvt_pk_bf16_f32 v137, v140, v141
	global_store_dwordx4 v[130:131], v[134:137], off nt
	v_mul_f32_e32 v140, 0xbfb8aa3b, v116
	v_mul_f32_e32 v141, 0xbfb8aa3b, v117
	v_add_f32_e32 v134, 1.0, v138
	v_add_f32_e32 v135, 1.0, v139
	v_mul_f32_e32 v136, 0xbfb8aa3b, v120
	v_mul_f32_e32 v137, 0xbfb8aa3b, v121
	v_mul_f32_e32 v138, 0xbfb8aa3b, v114
	v_mul_f32_e32 v139, 0xbfb8aa3b, v115
	v_exp_f32_e32 v136, v136
	v_exp_f32_e32 v137, v137
	v_exp_f32_e32 v138, v138
	v_exp_f32_e32 v139, v139
	v_exp_f32_e32 v140, v140
	v_exp_f32_e32 v141, v141
	v_add_f32_e32 v136, 1.0, v136
	v_add_f32_e32 v137, 1.0, v137
	v_add_f32_e32 v138, 1.0, v138
	v_add_f32_e32 v139, 1.0, v139
	v_add_f32_e32 v140, 1.0, v140
	v_add_f32_e32 v141, 1.0, v141
	v_rcp_f32_e32 v134, v134
	v_rcp_f32_e32 v135, v135
	v_rcp_f32_e32 v136, v136
	v_rcp_f32_e32 v137, v137
	v_rcp_f32_e32 v138, v138
	v_rcp_f32_e32 v139, v139
	v_rcp_f32_e32 v140, v140
	v_rcp_f32_e32 v141, v141
	v_pk_mul_f32 v[134:135], v[118:119], v[134:135]
	v_pk_mul_f32 v[136:137], v[120:121], v[136:137]
	v_pk_mul_f32 v[138:139], v[114:115], v[138:139]
	v_pk_mul_f32 v[140:141], v[116:117], v[140:141]
	v_cvt_pk_bf16_f32 v134, v134, v135
	v_cvt_pk_bf16_f32 v135, v136, v137
	v_cvt_pk_bf16_f32 v136, v138, v139
	v_cvt_pk_bf16_f32 v137, v140, v141
	global_store_dwordx4 v[130:131], v[134:137], off offset:256 nt
	v_mul_f32_e32 v140, 0xbfb8aa3b, v106
	v_mul_f32_e32 v141, 0xbfb8aa3b, v107
	v_mul_f32_e32 v136, 0xbfb8aa3b, v110
	v_mul_f32_e32 v137, 0xbfb8aa3b, v111
	v_exp_f32_e32 v136, v136
	v_exp_f32_e32 v137, v137
	v_or_b32_e32 v134, 16, v174
	v_ashrrev_i32_e32 v135, 31, v134
	v_lshlrev_b64 v[134:135], 12, v[134:135]
	v_lshl_add_u64 v[138:139], v[132:133], 0, v[134:135]
	v_add_f32_e32 v134, 1.0, v136
	v_add_f32_e32 v135, 1.0, v137
	v_mul_f32_e32 v136, 0xbfb8aa3b, v112
	v_mul_f32_e32 v137, 0xbfb8aa3b, v113
	v_exp_f32_e32 v136, v136
	v_exp_f32_e32 v137, v137
	v_exp_f32_e32 v140, v140
	v_exp_f32_e32 v141, v141
	v_mul_f32_e32 v142, 0xbfb8aa3b, v108
	v_mul_f32_e32 v143, 0xbfb8aa3b, v109
	v_add_f32_e32 v136, 1.0, v136
	v_add_f32_e32 v137, 1.0, v137
	v_add_f32_e32 v140, 1.0, v140
	v_add_f32_e32 v141, 1.0, v141
	v_exp_f32_e32 v142, v142
	v_exp_f32_e32 v143, v143
	v_rcp_f32_e32 v134, v134
	v_rcp_f32_e32 v135, v135
	v_rcp_f32_e32 v136, v136
	v_rcp_f32_e32 v137, v137
	v_rcp_f32_e32 v140, v140
	v_rcp_f32_e32 v141, v141
	v_add_f32_e32 v142, 1.0, v142
	v_add_f32_e32 v143, 1.0, v143
	v_rcp_f32_e32 v142, v142
	v_rcp_f32_e32 v143, v143
	v_pk_mul_f32 v[134:135], v[110:111], v[134:135]
	v_pk_mul_f32 v[136:137], v[112:113], v[136:137]
	v_pk_mul_f32 v[140:141], v[106:107], v[140:141]
	v_cvt_pk_bf16_f32 v134, v134, v135
	v_cvt_pk_bf16_f32 v135, v136, v137
	v_cvt_pk_bf16_f32 v136, v140, v141
	v_mul_f32_e32 v140, 0xbfb8aa3b, v102
	v_mul_f32_e32 v141, 0xbfb8aa3b, v103
	v_exp_f32_e32 v140, v140
	v_exp_f32_e32 v141, v141
	v_pk_mul_f32 v[142:143], v[108:109], v[142:143]
	s_mov_b32 s18, 0x80000
	v_cvt_pk_bf16_f32 v137, v142, v143
	global_store_dwordx4 v[138:139], v[134:137], off nt
	v_mul_f32_e32 v142, 0xbfb8aa3b, v100
	v_mul_f32_e32 v143, 0xbfb8aa3b, v101
	v_add_f32_e32 v134, 1.0, v140
	v_add_f32_e32 v135, 1.0, v141
	v_mul_f32_e32 v136, 0xbfb8aa3b, v104
	v_mul_f32_e32 v137, 0xbfb8aa3b, v105
	v_mul_f32_e32 v140, 0xbfb8aa3b, v98
	v_mul_f32_e32 v141, 0xbfb8aa3b, v99
	v_exp_f32_e32 v136, v136
	v_exp_f32_e32 v137, v137
	v_exp_f32_e32 v140, v140
	v_exp_f32_e32 v141, v141
	v_exp_f32_e32 v142, v142
	v_exp_f32_e32 v143, v143
	v_add_f32_e32 v136, 1.0, v136
	v_add_f32_e32 v137, 1.0, v137
	v_add_f32_e32 v140, 1.0, v140
	v_add_f32_e32 v141, 1.0, v141
	v_add_f32_e32 v142, 1.0, v142
	v_add_f32_e32 v143, 1.0, v143
	v_rcp_f32_e32 v134, v134
	v_rcp_f32_e32 v135, v135
	v_rcp_f32_e32 v136, v136
	v_rcp_f32_e32 v137, v137
	v_rcp_f32_e32 v140, v140
	v_rcp_f32_e32 v141, v141
	v_rcp_f32_e32 v142, v142
	v_rcp_f32_e32 v143, v143
	v_pk_mul_f32 v[134:135], v[102:103], v[134:135]
	v_pk_mul_f32 v[136:137], v[104:105], v[136:137]
	v_pk_mul_f32 v[140:141], v[98:99], v[140:141]
	v_pk_mul_f32 v[142:143], v[100:101], v[142:143]
	v_cvt_pk_bf16_f32 v134, v134, v135
	v_cvt_pk_bf16_f32 v135, v136, v137
	v_cvt_pk_bf16_f32 v136, v140, v141
	v_cvt_pk_bf16_f32 v137, v142, v143
	global_store_dwordx4 v[138:139], v[134:137], off offset:256 nt
	v_mul_f32_e32 v140, 0xbfb8aa3b, v90
	v_mul_f32_e32 v141, 0xbfb8aa3b, v91
	v_mul_f32_e32 v136, 0xbfb8aa3b, v94
	v_mul_f32_e32 v137, 0xbfb8aa3b, v95
	v_exp_f32_e32 v136, v136
	v_exp_f32_e32 v137, v137
	v_or_b32_e32 v134, 32, v174
	v_ashrrev_i32_e32 v135, 31, v134
	v_lshlrev_b64 v[134:135], 12, v[134:135]
	v_lshl_add_u64 v[138:139], v[132:133], 0, v[134:135]
	v_add_f32_e32 v134, 1.0, v136
	v_add_f32_e32 v135, 1.0, v137
	v_mul_f32_e32 v136, 0xbfb8aa3b, v96
	v_mul_f32_e32 v137, 0xbfb8aa3b, v97
	v_exp_f32_e32 v136, v136
	v_exp_f32_e32 v137, v137
	v_exp_f32_e32 v140, v140
	v_exp_f32_e32 v141, v141
	v_mul_f32_e32 v142, 0xbfb8aa3b, v92
	v_mul_f32_e32 v143, 0xbfb8aa3b, v93
	v_add_f32_e32 v136, 1.0, v136
	v_add_f32_e32 v137, 1.0, v137
	v_add_f32_e32 v140, 1.0, v140
	v_add_f32_e32 v141, 1.0, v141
	v_exp_f32_e32 v142, v142
	v_exp_f32_e32 v143, v143
	v_rcp_f32_e32 v134, v134
	v_rcp_f32_e32 v135, v135
	v_rcp_f32_e32 v136, v136
	v_rcp_f32_e32 v137, v137
	v_rcp_f32_e32 v140, v140
	v_rcp_f32_e32 v141, v141
	v_add_f32_e32 v142, 1.0, v142
	v_add_f32_e32 v143, 1.0, v143
	v_rcp_f32_e32 v142, v142
	v_rcp_f32_e32 v143, v143
	v_pk_mul_f32 v[134:135], v[94:95], v[134:135]
	v_pk_mul_f32 v[136:137], v[96:97], v[136:137]
	v_pk_mul_f32 v[140:141], v[90:91], v[140:141]
	v_cvt_pk_bf16_f32 v134, v134, v135
	v_cvt_pk_bf16_f32 v135, v136, v137
	v_cvt_pk_bf16_f32 v136, v140, v141
	v_mul_f32_e32 v140, 0xbfb8aa3b, v86
	v_mul_f32_e32 v141, 0xbfb8aa3b, v87
	v_exp_f32_e32 v140, v140
	v_exp_f32_e32 v141, v141
	v_pk_mul_f32 v[142:143], v[92:93], v[142:143]
	s_mov_b64 s[30:31], 0
	v_cvt_pk_bf16_f32 v137, v142, v143
	global_store_dwordx4 v[138:139], v[134:137], off nt
	v_mul_f32_e32 v142, 0xbfb8aa3b, v84
	v_mul_f32_e32 v143, 0xbfb8aa3b, v85
	v_add_f32_e32 v134, 1.0, v140
	v_add_f32_e32 v135, 1.0, v141
	v_mul_f32_e32 v136, 0xbfb8aa3b, v88
	v_mul_f32_e32 v137, 0xbfb8aa3b, v89
	v_mul_f32_e32 v140, 0xbfb8aa3b, v82
	v_mul_f32_e32 v141, 0xbfb8aa3b, v83
	v_exp_f32_e32 v136, v136
	v_exp_f32_e32 v137, v137
	v_exp_f32_e32 v140, v140
	v_exp_f32_e32 v141, v141
	v_exp_f32_e32 v142, v142
	v_exp_f32_e32 v143, v143
	v_add_f32_e32 v136, 1.0, v136
	v_add_f32_e32 v137, 1.0, v137
	v_add_f32_e32 v140, 1.0, v140
	v_add_f32_e32 v141, 1.0, v141
	v_add_f32_e32 v142, 1.0, v142
	v_add_f32_e32 v143, 1.0, v143
	v_rcp_f32_e32 v134, v134
	v_rcp_f32_e32 v135, v135
	v_rcp_f32_e32 v136, v136
	v_rcp_f32_e32 v137, v137
	v_rcp_f32_e32 v140, v140
	v_rcp_f32_e32 v141, v141
	v_rcp_f32_e32 v142, v142
	v_rcp_f32_e32 v143, v143
	v_pk_mul_f32 v[134:135], v[86:87], v[134:135]
	v_pk_mul_f32 v[136:137], v[88:89], v[136:137]
	v_pk_mul_f32 v[140:141], v[82:83], v[140:141]
	v_pk_mul_f32 v[142:143], v[84:85], v[142:143]
	v_cvt_pk_bf16_f32 v134, v134, v135
	v_cvt_pk_bf16_f32 v135, v136, v137
	v_cvt_pk_bf16_f32 v136, v140, v141
	v_cvt_pk_bf16_f32 v137, v142, v143
	global_store_dwordx4 v[138:139], v[134:137], off offset:256 nt
	v_mul_f32_e32 v140, 0xbfb8aa3b, v76
	v_mul_f32_e32 v141, 0xbfb8aa3b, v77
	v_mul_f32_e32 v136, 0xbfb8aa3b, v78
	v_exp_f32_e32 v138, v136
	v_mul_f32_e32 v136, 0xbfb8aa3b, v79
	v_exp_f32_e32 v139, v136
	v_or_b32_e32 v134, 48, v174
	v_ashrrev_i32_e32 v135, 31, v134
	v_lshlrev_b64 v[134:135], 12, v[134:135]
	v_lshl_add_u64 v[136:137], v[132:133], 0, v[134:135]
	v_add_f32_e32 v132, 1.0, v138
	v_add_f32_e32 v133, 1.0, v139
	v_mul_f32_e32 v134, 0xbfb8aa3b, v80
	v_mul_f32_e32 v135, 0xbfb8aa3b, v81
	v_mul_f32_e32 v138, 0xbfb8aa3b, v74
	v_mul_f32_e32 v139, 0xbfb8aa3b, v75
	v_exp_f32_e32 v134, v134
	v_exp_f32_e32 v135, v135
	v_exp_f32_e32 v138, v138
	v_exp_f32_e32 v139, v139
	v_add_f32_e32 v134, 1.0, v134
	v_add_f32_e32 v135, 1.0, v135
	v_add_f32_e32 v138, 1.0, v138
	v_add_f32_e32 v139, 1.0, v139
	v_exp_f32_e32 v140, v140
	v_exp_f32_e32 v141, v141
	v_rcp_f32_e32 v132, v132
	v_rcp_f32_e32 v133, v133
	v_rcp_f32_e32 v134, v134
	v_rcp_f32_e32 v135, v135
	v_rcp_f32_e32 v138, v138
	v_rcp_f32_e32 v139, v139
	v_add_f32_e32 v140, 1.0, v140
	v_add_f32_e32 v141, 1.0, v141
	v_rcp_f32_e32 v140, v140
	v_rcp_f32_e32 v141, v141
	v_pk_mul_f32 v[132:133], v[78:79], v[132:133]
	v_pk_mul_f32 v[134:135], v[80:81], v[134:135]
	v_pk_mul_f32 v[138:139], v[74:75], v[138:139]
	v_cvt_pk_bf16_f32 v132, v132, v133
	v_cvt_pk_bf16_f32 v133, v134, v135
	v_cvt_pk_bf16_f32 v134, v138, v139
	v_mul_f32_e32 v138, 0xbfb8aa3b, v70
	v_mul_f32_e32 v139, 0xbfb8aa3b, v71
	v_exp_f32_e32 v138, v138
	v_exp_f32_e32 v139, v139
	v_pk_mul_f32 v[140:141], v[76:77], v[140:141]
	s_nop 0
	v_cvt_pk_bf16_f32 v135, v140, v141
	global_store_dwordx4 v[136:137], v[132:135], off nt
	v_mul_f32_e32 v140, 0xbfb8aa3b, v68
	v_mul_f32_e32 v141, 0xbfb8aa3b, v69
	v_add_f32_e32 v132, 1.0, v138
	v_add_f32_e32 v133, 1.0, v139
	v_mul_f32_e32 v134, 0xbfb8aa3b, v72
	v_mul_f32_e32 v135, 0xbfb8aa3b, v73
	v_mul_f32_e32 v138, 0xbfb8aa3b, v66
	v_mul_f32_e32 v139, 0xbfb8aa3b, v67
	v_exp_f32_e32 v134, v134
	v_exp_f32_e32 v135, v135
	v_exp_f32_e32 v138, v138
	v_exp_f32_e32 v139, v139
	v_exp_f32_e32 v140, v140
	v_exp_f32_e32 v141, v141
	v_add_f32_e32 v134, 1.0, v134
	v_add_f32_e32 v135, 1.0, v135
	v_add_f32_e32 v138, 1.0, v138
	v_add_f32_e32 v139, 1.0, v139
	v_add_f32_e32 v140, 1.0, v140
	v_add_f32_e32 v141, 1.0, v141
	v_rcp_f32_e32 v132, v132
	v_rcp_f32_e32 v133, v133
	v_rcp_f32_e32 v134, v134
	v_rcp_f32_e32 v135, v135
	v_rcp_f32_e32 v138, v138
	v_rcp_f32_e32 v139, v139
	v_rcp_f32_e32 v140, v140
	v_rcp_f32_e32 v141, v141
	v_pk_mul_f32 v[132:133], v[70:71], v[132:133]
	v_pk_mul_f32 v[134:135], v[72:73], v[134:135]
	v_pk_mul_f32 v[138:139], v[66:67], v[138:139]
	v_pk_mul_f32 v[140:141], v[68:69], v[140:141]
	v_cvt_pk_bf16_f32 v132, v132, v133
	v_cvt_pk_bf16_f32 v133, v134, v135
	v_cvt_pk_bf16_f32 v134, v138, v139
	v_cvt_pk_bf16_f32 v135, v140, v141
	global_store_dwordx4 v[136:137], v[132:135], off offset:256 nt
	v_mul_f32_e32 v140, 0xbfb8aa3b, v60
	v_mul_f32_e32 v141, 0xbfb8aa3b, v61
	v_mul_f32_e32 v132, 0xbfb8aa3b, v62
	v_mul_f32_e32 v133, 0xbfb8aa3b, v63
	v_mul_f32_e32 v134, 0xbfb8aa3b, v64
	v_mul_f32_e32 v135, 0xbfb8aa3b, v65
	v_exp_f32_e32 v132, v132
	v_exp_f32_e32 v133, v133
	v_exp_f32_e32 v134, v134
	v_exp_f32_e32 v135, v135
	v_exp_f32_e32 v140, v140
	v_exp_f32_e32 v141, v141
	v_mul_f32_e32 v138, 0xbfb8aa3b, v58
	v_mul_f32_e32 v139, 0xbfb8aa3b, v59
	v_exp_f32_e32 v138, v138
	v_exp_f32_e32 v139, v139
	v_add_f32_e32 v132, 1.0, v132
	v_add_f32_e32 v133, 1.0, v133
	v_add_f32_e32 v134, 1.0, v134
	v_add_f32_e32 v135, 1.0, v135
	v_add_f32_e32 v140, 1.0, v140
	v_add_f32_e32 v141, 1.0, v141
	v_rcp_f32_e32 v132, v132
	v_rcp_f32_e32 v133, v133
	v_rcp_f32_e32 v134, v134
	v_rcp_f32_e32 v135, v135
	v_rcp_f32_e32 v140, v140
	v_rcp_f32_e32 v141, v141
	v_add_f32_e32 v138, 1.0, v138
	v_add_f32_e32 v139, 1.0, v139
	v_rcp_f32_e32 v138, v138
	v_rcp_f32_e32 v139, v139
	v_pk_mul_f32 v[132:133], v[62:63], v[132:133]
	v_pk_mul_f32 v[134:135], v[64:65], v[134:135]
	v_pk_mul_f32 v[140:141], v[60:61], v[140:141]
	v_cvt_pk_bf16_f32 v132, v132, v133
	v_cvt_pk_bf16_f32 v133, v134, v135
	v_cvt_pk_bf16_f32 v135, v140, v141
	v_mul_f32_e32 v140, 0xbfb8aa3b, v54
	v_mul_f32_e32 v141, 0xbfb8aa3b, v55
	v_exp_f32_e32 v140, v140
	v_exp_f32_e32 v141, v141
	v_pk_mul_f32 v[138:139], v[58:59], v[138:139]
	v_lshl_add_u64 v[136:137], v[130:131], 0, s[10:11]
	v_cvt_pk_bf16_f32 v134, v138, v139
	v_add_co_u32_e32 v138, vcc, s18, v130
	s_mov_b64 s[18:19], 0x90000
	s_nop 0
	v_addc_co_u32_e32 v139, vcc, 0, v131, vcc
	global_store_dwordx4 v[138:139], v[132:135], off nt
	v_mul_f32_e32 v138, 0xbfb8aa3b, v50
	v_mul_f32_e32 v139, 0xbfb8aa3b, v51
	v_add_f32_e32 v132, 1.0, v140
	v_add_f32_e32 v133, 1.0, v141
	v_mul_f32_e32 v134, 0xbfb8aa3b, v56
	v_mul_f32_e32 v135, 0xbfb8aa3b, v57
	v_mul_f32_e32 v140, 0xbfb8aa3b, v52
	v_mul_f32_e32 v141, 0xbfb8aa3b, v53
	v_exp_f32_e32 v134, v134
	v_exp_f32_e32 v135, v135
	v_exp_f32_e32 v138, v138
	v_exp_f32_e32 v139, v139
	v_exp_f32_e32 v140, v140
	v_exp_f32_e32 v141, v141
	v_add_f32_e32 v134, 1.0, v134
	v_add_f32_e32 v135, 1.0, v135
	v_add_f32_e32 v138, 1.0, v138
	v_add_f32_e32 v139, 1.0, v139
	v_add_f32_e32 v140, 1.0, v140
	v_add_f32_e32 v141, 1.0, v141
	v_rcp_f32_e32 v132, v132
	v_rcp_f32_e32 v133, v133
	v_rcp_f32_e32 v134, v134
	v_rcp_f32_e32 v135, v135
	v_rcp_f32_e32 v138, v138
	v_rcp_f32_e32 v139, v139
	v_rcp_f32_e32 v140, v140
	v_rcp_f32_e32 v141, v141
	v_pk_mul_f32 v[132:133], v[54:55], v[132:133]
	v_pk_mul_f32 v[134:135], v[56:57], v[134:135]
	v_pk_mul_f32 v[138:139], v[50:51], v[138:139]
	v_pk_mul_f32 v[140:141], v[52:53], v[140:141]
	v_cvt_pk_bf16_f32 v132, v132, v133
	v_cvt_pk_bf16_f32 v133, v134, v135
	v_cvt_pk_bf16_f32 v134, v138, v139
	v_cvt_pk_bf16_f32 v135, v140, v141
	global_store_dwordx4 v[136:137], v[132:135], off offset:256 nt
	v_mul_f32_e32 v140, 0xbfb8aa3b, v44
	v_mul_f32_e32 v141, 0xbfb8aa3b, v45
	v_mul_f32_e32 v132, 0xbfb8aa3b, v46
	v_mul_f32_e32 v133, 0xbfb8aa3b, v47
	v_mul_f32_e32 v134, 0xbfb8aa3b, v48
	v_mul_f32_e32 v135, 0xbfb8aa3b, v49
	v_exp_f32_e32 v132, v132
	v_exp_f32_e32 v133, v133
	v_exp_f32_e32 v134, v134
	v_exp_f32_e32 v135, v135
	v_exp_f32_e32 v140, v140
	v_exp_f32_e32 v141, v141
	v_mul_f32_e32 v138, 0xbfb8aa3b, v42
	v_mul_f32_e32 v139, 0xbfb8aa3b, v43
	v_exp_f32_e32 v138, v138
	v_exp_f32_e32 v139, v139
	v_add_f32_e32 v132, 1.0, v132
	v_add_f32_e32 v133, 1.0, v133
	v_add_f32_e32 v134, 1.0, v134
	v_add_f32_e32 v135, 1.0, v135
	v_add_f32_e32 v140, 1.0, v140
	v_add_f32_e32 v141, 1.0, v141
	v_rcp_f32_e32 v132, v132
	v_rcp_f32_e32 v133, v133
	v_rcp_f32_e32 v134, v134
	v_rcp_f32_e32 v135, v135
	v_rcp_f32_e32 v140, v140
	v_rcp_f32_e32 v141, v141
	v_add_f32_e32 v138, 1.0, v138
	v_add_f32_e32 v139, 1.0, v139
	v_rcp_f32_e32 v138, v138
	v_rcp_f32_e32 v139, v139
	v_pk_mul_f32 v[132:133], v[46:47], v[132:133]
	v_pk_mul_f32 v[134:135], v[48:49], v[134:135]
	v_pk_mul_f32 v[140:141], v[44:45], v[140:141]
	v_cvt_pk_bf16_f32 v132, v132, v133
	v_cvt_pk_bf16_f32 v133, v134, v135
	v_cvt_pk_bf16_f32 v135, v140, v141
	v_mul_f32_e32 v140, 0xbfb8aa3b, v38
	v_mul_f32_e32 v141, 0xbfb8aa3b, v39
	v_exp_f32_e32 v140, v140
	v_exp_f32_e32 v141, v141
	v_lshl_add_u64 v[136:137], v[130:131], 0, s[18:19]
	v_pk_mul_f32 v[138:139], v[42:43], v[138:139]
	s_mov_b32 s18, 0x90000
	v_cvt_pk_bf16_f32 v134, v138, v139
	v_add_co_u32_e32 v138, vcc, s18, v130
	s_mov_b64 s[18:19], 0xa0000
	s_nop 0
	v_addc_co_u32_e32 v139, vcc, 0, v131, vcc
	global_store_dwordx4 v[138:139], v[132:135], off nt
	v_mul_f32_e32 v138, 0xbfb8aa3b, v34
	v_mul_f32_e32 v139, 0xbfb8aa3b, v35
	v_add_f32_e32 v132, 1.0, v140
	v_add_f32_e32 v133, 1.0, v141
	v_mul_f32_e32 v134, 0xbfb8aa3b, v40
	v_mul_f32_e32 v135, 0xbfb8aa3b, v41
	v_mul_f32_e32 v140, 0xbfb8aa3b, v36
	v_mul_f32_e32 v141, 0xbfb8aa3b, v37
	v_exp_f32_e32 v134, v134
	v_exp_f32_e32 v135, v135
	v_exp_f32_e32 v138, v138
	v_exp_f32_e32 v139, v139
	v_exp_f32_e32 v140, v140
	v_exp_f32_e32 v141, v141
	v_add_f32_e32 v134, 1.0, v134
	v_add_f32_e32 v135, 1.0, v135
	v_add_f32_e32 v138, 1.0, v138
	v_add_f32_e32 v139, 1.0, v139
	v_add_f32_e32 v140, 1.0, v140
	v_add_f32_e32 v141, 1.0, v141
	v_rcp_f32_e32 v132, v132
	v_rcp_f32_e32 v133, v133
	v_rcp_f32_e32 v134, v134
	v_rcp_f32_e32 v135, v135
	v_rcp_f32_e32 v138, v138
	v_rcp_f32_e32 v139, v139
	v_rcp_f32_e32 v140, v140
	v_rcp_f32_e32 v141, v141
	v_pk_mul_f32 v[132:133], v[38:39], v[132:133]
	v_pk_mul_f32 v[134:135], v[40:41], v[134:135]
	v_pk_mul_f32 v[138:139], v[34:35], v[138:139]
	v_pk_mul_f32 v[140:141], v[36:37], v[140:141]
	v_cvt_pk_bf16_f32 v132, v132, v133
	v_cvt_pk_bf16_f32 v133, v134, v135
	v_cvt_pk_bf16_f32 v134, v138, v139
	v_cvt_pk_bf16_f32 v135, v140, v141
	global_store_dwordx4 v[136:137], v[132:135], off offset:256 nt
	v_mul_f32_e32 v140, 0xbfb8aa3b, v28
	v_mul_f32_e32 v141, 0xbfb8aa3b, v29
	v_mul_f32_e32 v132, 0xbfb8aa3b, v30
	v_mul_f32_e32 v133, 0xbfb8aa3b, v31
	v_mul_f32_e32 v134, 0xbfb8aa3b, v32
	v_mul_f32_e32 v135, 0xbfb8aa3b, v33
	v_exp_f32_e32 v132, v132
	v_exp_f32_e32 v133, v133
	v_exp_f32_e32 v134, v134
	v_exp_f32_e32 v135, v135
	v_exp_f32_e32 v140, v140
	v_exp_f32_e32 v141, v141
	v_mul_f32_e32 v138, 0xbfb8aa3b, v26
	v_mul_f32_e32 v139, 0xbfb8aa3b, v27
	v_exp_f32_e32 v138, v138
	v_exp_f32_e32 v139, v139
	v_add_f32_e32 v132, 1.0, v132
	v_add_f32_e32 v133, 1.0, v133
	v_add_f32_e32 v134, 1.0, v134
	v_add_f32_e32 v135, 1.0, v135
	v_add_f32_e32 v140, 1.0, v140
	v_add_f32_e32 v141, 1.0, v141
	v_rcp_f32_e32 v132, v132
	v_rcp_f32_e32 v133, v133
	v_rcp_f32_e32 v134, v134
	v_rcp_f32_e32 v135, v135
	v_rcp_f32_e32 v140, v140
	v_rcp_f32_e32 v141, v141
	v_add_f32_e32 v138, 1.0, v138
	v_add_f32_e32 v139, 1.0, v139
	v_rcp_f32_e32 v138, v138
	v_rcp_f32_e32 v139, v139
	v_pk_mul_f32 v[132:133], v[30:31], v[132:133]
	v_pk_mul_f32 v[134:135], v[32:33], v[134:135]
	v_pk_mul_f32 v[140:141], v[28:29], v[140:141]
	v_cvt_pk_bf16_f32 v132, v132, v133
	v_cvt_pk_bf16_f32 v133, v134, v135
	v_cvt_pk_bf16_f32 v135, v140, v141
	v_mul_f32_e32 v140, 0xbfb8aa3b, v22
	v_mul_f32_e32 v141, 0xbfb8aa3b, v23
	v_exp_f32_e32 v140, v140
	v_exp_f32_e32 v141, v141
	v_lshl_add_u64 v[136:137], v[130:131], 0, s[18:19]
	v_pk_mul_f32 v[138:139], v[26:27], v[138:139]
	s_mov_b32 s18, 0xa0000
	v_cvt_pk_bf16_f32 v134, v138, v139
	v_add_co_u32_e32 v138, vcc, s18, v130
	s_mov_b64 s[18:19], 0xb0000
	s_nop 0
	v_addc_co_u32_e32 v139, vcc, 0, v131, vcc
	global_store_dwordx4 v[138:139], v[132:135], off nt
	v_mul_f32_e32 v138, 0xbfb8aa3b, v18
	v_mul_f32_e32 v139, 0xbfb8aa3b, v19
	v_add_f32_e32 v132, 1.0, v140
	v_add_f32_e32 v133, 1.0, v141
	v_mul_f32_e32 v134, 0xbfb8aa3b, v24
	v_mul_f32_e32 v135, 0xbfb8aa3b, v25
	v_mul_f32_e32 v140, 0xbfb8aa3b, v20
	v_mul_f32_e32 v141, 0xbfb8aa3b, v21
	v_exp_f32_e32 v134, v134
	v_exp_f32_e32 v135, v135
	v_exp_f32_e32 v138, v138
	v_exp_f32_e32 v139, v139
	v_exp_f32_e32 v140, v140
	v_exp_f32_e32 v141, v141
	v_add_f32_e32 v134, 1.0, v134
	v_add_f32_e32 v135, 1.0, v135
	v_add_f32_e32 v138, 1.0, v138
	v_add_f32_e32 v139, 1.0, v139
	v_add_f32_e32 v140, 1.0, v140
	v_add_f32_e32 v141, 1.0, v141
	v_rcp_f32_e32 v132, v132
	v_rcp_f32_e32 v133, v133
	v_rcp_f32_e32 v134, v134
	v_rcp_f32_e32 v135, v135
	v_rcp_f32_e32 v138, v138
	v_rcp_f32_e32 v139, v139
	v_rcp_f32_e32 v140, v140
	v_rcp_f32_e32 v141, v141
	v_pk_mul_f32 v[132:133], v[22:23], v[132:133]
	v_pk_mul_f32 v[134:135], v[24:25], v[134:135]
	v_pk_mul_f32 v[138:139], v[18:19], v[138:139]
	v_pk_mul_f32 v[140:141], v[20:21], v[140:141]
	v_cvt_pk_bf16_f32 v132, v132, v133
	v_cvt_pk_bf16_f32 v133, v134, v135
	v_cvt_pk_bf16_f32 v134, v138, v139
	v_cvt_pk_bf16_f32 v135, v140, v141
	global_store_dwordx4 v[136:137], v[132:135], off offset:256 nt
	v_mul_f32_e32 v138, 0xbfb8aa3b, v10
	v_mul_f32_e32 v139, 0xbfb8aa3b, v11
	v_mul_f32_e32 v132, 0xbfb8aa3b, v14
	v_mul_f32_e32 v133, 0xbfb8aa3b, v15
	v_mul_f32_e32 v134, 0xbfb8aa3b, v16
	v_mul_f32_e32 v135, 0xbfb8aa3b, v17
	v_exp_f32_e32 v132, v132
	v_exp_f32_e32 v133, v133
	v_exp_f32_e32 v134, v134
	v_exp_f32_e32 v135, v135
	v_exp_f32_e32 v138, v138
	v_exp_f32_e32 v139, v139
	v_mul_f32_e32 v140, 0xbfb8aa3b, v12
	v_mul_f32_e32 v141, 0xbfb8aa3b, v13
	v_add_f32_e32 v132, 1.0, v132
	v_add_f32_e32 v133, 1.0, v133
	v_add_f32_e32 v134, 1.0, v134
	v_add_f32_e32 v135, 1.0, v135
	v_add_f32_e32 v138, 1.0, v138
	v_add_f32_e32 v139, 1.0, v139
	v_exp_f32_e32 v140, v140
	v_exp_f32_e32 v141, v141
	v_rcp_f32_e32 v132, v132
	v_rcp_f32_e32 v133, v133
	v_rcp_f32_e32 v134, v134
	v_rcp_f32_e32 v135, v135
	v_rcp_f32_e32 v138, v138
	v_rcp_f32_e32 v139, v139
	v_add_f32_e32 v140, 1.0, v140
	v_add_f32_e32 v141, 1.0, v141
	v_rcp_f32_e32 v140, v140
	v_rcp_f32_e32 v141, v141
	v_pk_mul_f32 v[132:133], v[14:15], v[132:133]
	v_pk_mul_f32 v[134:135], v[16:17], v[134:135]
	v_pk_mul_f32 v[138:139], v[10:11], v[138:139]
	v_cvt_pk_bf16_f32 v132, v132, v133
	v_cvt_pk_bf16_f32 v133, v134, v135
	v_cvt_pk_bf16_f32 v134, v138, v139
	v_mul_f32_e32 v138, 0xbfb8aa3b, v6
	v_mul_f32_e32 v139, 0xbfb8aa3b, v7
	v_exp_f32_e32 v138, v138
	v_exp_f32_e32 v139, v139
	v_lshl_add_u64 v[136:137], v[130:131], 0, s[18:19]
	s_mov_b32 s18, 0xb0000
	v_pk_mul_f32 v[140:141], v[12:13], v[140:141]
	v_add_co_u32_e32 v130, vcc, s18, v130
	v_cvt_pk_bf16_f32 v135, v140, v141
	s_nop 0
	v_addc_co_u32_e32 v131, vcc, 0, v131, vcc
	global_store_dwordx4 v[130:131], v[132:135], off nt
	v_add_f32_e32 v130, 1.0, v138
	v_add_f32_e32 v131, 1.0, v139
	v_mul_f32_e32 v132, 0xbfb8aa3b, v8
	v_mul_f32_e32 v133, 0xbfb8aa3b, v9
	v_mul_f32_e32 v134, 0xbfb8aa3b, v2
	v_mul_f32_e32 v135, 0xbfb8aa3b, v3
	v_mul_f32_e32 v138, 0xbfb8aa3b, v4
	v_mul_f32_e32 v139, 0xbfb8aa3b, v5
	v_exp_f32_e32 v132, v132
	v_exp_f32_e32 v133, v133
	v_exp_f32_e32 v134, v134
	v_exp_f32_e32 v135, v135
	v_exp_f32_e32 v138, v138
	v_exp_f32_e32 v139, v139
	v_add_f32_e32 v132, 1.0, v132
	v_add_f32_e32 v133, 1.0, v133
	v_add_f32_e32 v134, 1.0, v134
	v_add_f32_e32 v135, 1.0, v135
	v_add_f32_e32 v138, 1.0, v138
	v_add_f32_e32 v139, 1.0, v139
	v_rcp_f32_e32 v130, v130
	v_rcp_f32_e32 v131, v131
	v_rcp_f32_e32 v132, v132
	v_rcp_f32_e32 v133, v133
	v_rcp_f32_e32 v134, v134
	v_rcp_f32_e32 v135, v135
	v_rcp_f32_e32 v138, v138
	v_rcp_f32_e32 v139, v139
	v_pk_mul_f32 v[130:131], v[6:7], v[130:131]
	v_pk_mul_f32 v[132:133], v[8:9], v[132:133]
	v_pk_mul_f32 v[134:135], v[2:3], v[134:135]
	v_pk_mul_f32 v[138:139], v[4:5], v[138:139]
	v_cvt_pk_bf16_f32 v130, v130, v131
	v_cvt_pk_bf16_f32 v131, v132, v133
	v_cvt_pk_bf16_f32 v132, v134, v135
	v_cvt_pk_bf16_f32 v133, v138, v139
	global_store_dwordx4 v[136:137], v[130:133], off offset:256 nt

.LBB0_283:
	v_lshl_add_u64 v[134:135], v[176:177], 1, s[0:1]
	v_lshlrev_b64 v[130:131], 12, v[174:175]
	v_lshl_add_u64 v[136:137], v[134:135], 0, v[130:131]
	v_cvt_pk_bf16_f32 v130, v126, v127
	v_cvt_pk_bf16_f32 v131, v128, v129
	v_cvt_pk_bf16_f32 v132, v122, v123
	v_cvt_pk_bf16_f32 v133, v124, v125
	global_store_dwordx4 v[136:137], v[130:133], off nt
	s_mov_b32 s18, 0x80000
	s_nop 0
	v_cvt_pk_bf16_f32 v130, v118, v119
	v_cvt_pk_bf16_f32 v131, v120, v121
	v_cvt_pk_bf16_f32 v132, v114, v115
	v_cvt_pk_bf16_f32 v133, v116, v117
	global_store_dwordx4 v[136:137], v[130:133], off offset:256 nt
	s_nop 1
	v_lshlrev_b64 v[130:131], 12, v[186:187]
	v_lshl_add_u64 v[138:139], v[134:135], 0, v[130:131]
	v_cvt_pk_bf16_f32 v130, v110, v111
	v_cvt_pk_bf16_f32 v131, v112, v113
	v_cvt_pk_bf16_f32 v132, v106, v107
	v_cvt_pk_bf16_f32 v133, v108, v109
	global_store_dwordx4 v[138:139], v[130:133], off nt
	s_nop 1
	v_cvt_pk_bf16_f32 v130, v102, v103
	v_cvt_pk_bf16_f32 v131, v104, v105
	v_cvt_pk_bf16_f32 v132, v98, v99
	v_cvt_pk_bf16_f32 v133, v100, v101
	global_store_dwordx4 v[138:139], v[130:133], off offset:256 nt
	s_nop 1
	v_lshlrev_b64 v[130:131], 12, v[184:185]
	v_lshl_add_u64 v[138:139], v[134:135], 0, v[130:131]
	v_cvt_pk_bf16_f32 v130, v94, v95
	v_cvt_pk_bf16_f32 v131, v96, v97
	v_cvt_pk_bf16_f32 v132, v90, v91
	v_cvt_pk_bf16_f32 v133, v92, v93
	global_store_dwordx4 v[138:139], v[130:133], off nt
	s_nop 1
	v_cvt_pk_bf16_f32 v130, v86, v87
	v_cvt_pk_bf16_f32 v131, v88, v89
	v_cvt_pk_bf16_f32 v132, v82, v83
	v_cvt_pk_bf16_f32 v133, v84, v85
	global_store_dwordx4 v[138:139], v[130:133], off offset:256 nt
	v_add_co_u32_e32 v138, vcc, s18, v136
	s_nop 0
	v_lshlrev_b64 v[130:131], 12, v[180:181]
	v_lshl_add_u64 v[134:135], v[134:135], 0, v[130:131]
	v_cvt_pk_bf16_f32 v130, v78, v79
	v_cvt_pk_bf16_f32 v131, v80, v81
	v_cvt_pk_bf16_f32 v132, v74, v75
	v_cvt_pk_bf16_f32 v133, v76, v77
	global_store_dwordx4 v[134:135], v[130:133], off nt
	v_addc_co_u32_e32 v139, vcc, 0, v137, vcc
	s_nop 0
	v_cvt_pk_bf16_f32 v130, v70, v71
	v_cvt_pk_bf16_f32 v131, v72, v73
	v_cvt_pk_bf16_f32 v132, v66, v67
	v_cvt_pk_bf16_f32 v133, v68, v69
	global_store_dwordx4 v[134:135], v[130:133], off offset:256 nt
	v_lshl_add_u64 v[134:135], v[136:137], 0, s[10:11]
	s_mov_b64 s[18:19], 0x90000
	v_cvt_pk_bf16_f32 v130, v62, v63
	v_cvt_pk_bf16_f32 v131, v64, v65
	v_cvt_pk_bf16_f32 v132, v58, v59
	v_cvt_pk_bf16_f32 v133, v60, v61
	global_store_dwordx4 v[138:139], v[130:133], off nt
	s_nop 1
	v_cvt_pk_bf16_f32 v130, v54, v55
	v_cvt_pk_bf16_f32 v131, v56, v57
	v_cvt_pk_bf16_f32 v132, v50, v51
	v_cvt_pk_bf16_f32 v133, v52, v53
	global_store_dwordx4 v[134:135], v[130:133], off offset:256 nt
	v_lshl_add_u64 v[134:135], v[136:137], 0, s[18:19]
	s_mov_b32 s18, 0x90000
	v_add_co_u32_e32 v138, vcc, s18, v136
	v_cvt_pk_bf16_f32 v130, v46, v47
	v_cvt_pk_bf16_f32 v131, v48, v49
	v_cvt_pk_bf16_f32 v132, v42, v43
	v_cvt_pk_bf16_f32 v133, v44, v45
	v_addc_co_u32_e32 v139, vcc, 0, v137, vcc
	global_store_dwordx4 v[138:139], v[130:133], off nt
	s_mov_b64 s[18:19], 0xa0000
	s_nop 0
	v_cvt_pk_bf16_f32 v130, v38, v39
	v_cvt_pk_bf16_f32 v131, v40, v41
	v_cvt_pk_bf16_f32 v132, v34, v35
	v_cvt_pk_bf16_f32 v133, v36, v37
	global_store_dwordx4 v[134:135], v[130:133], off offset:256 nt
	v_lshl_add_u64 v[134:135], v[136:137], 0, s[18:19]
	s_mov_b32 s18, 0xa0000
	v_add_co_u32_e32 v138, vcc, s18, v136
	v_cvt_pk_bf16_f32 v130, v30, v31
	v_cvt_pk_bf16_f32 v131, v32, v33
	v_cvt_pk_bf16_f32 v132, v26, v27
	v_cvt_pk_bf16_f32 v133, v28, v29
	v_addc_co_u32_e32 v139, vcc, 0, v137, vcc
	global_store_dwordx4 v[138:139], v[130:133], off nt
	s_mov_b64 s[18:19], 0xb0000
	s_nop 0
	v_cvt_pk_bf16_f32 v130, v22, v23
	v_cvt_pk_bf16_f32 v131, v24, v25
	v_cvt_pk_bf16_f32 v132, v18, v19
	v_cvt_pk_bf16_f32 v133, v20, v21
	global_store_dwordx4 v[134:135], v[130:133], off offset:256 nt
	v_lshl_add_u64 v[134:135], v[136:137], 0, s[18:19]
	s_mov_b32 s18, 0xb0000
	v_add_co_u32_e32 v136, vcc, s18, v136
	v_cvt_pk_bf16_f32 v130, v14, v15
	v_cvt_pk_bf16_f32 v131, v16, v17
	v_cvt_pk_bf16_f32 v132, v10, v11
	v_cvt_pk_bf16_f32 v133, v12, v13
	v_addc_co_u32_e32 v137, vcc, 0, v137, vcc
	global_store_dwordx4 v[136:137], v[130:133], off nt
	s_nop 1
	v_cvt_pk_bf16_f32 v130, v6, v7
	v_cvt_pk_bf16_f32 v131, v8, v9
	v_cvt_pk_bf16_f32 v132, v2, v3
	v_cvt_pk_bf16_f32 v133, v4, v5
	global_store_dwordx4 v[134:135], v[130:133], off offset:256 nt
	s_cbranch_execnz .LBB0_282
.LBB0_284:
	s_nop 0
	v_lshlrev_b32_e32 v130, 4, v174
	v_and_b32_e32 v131, 8, v146
	s_mov_b32 s18, 0xfcf0
	v_and_or_b32 v130, v130, s18, v131
	v_lshlrev_b32_e32 v130, 3, v130
	global_load_dwordx4 v[146:149], v130, s[64:65] offset:48
	global_load_dwordx4 v[150:153], v130, s[64:65] offset:32
	global_load_dwordx4 v[154:157], v130, s[64:65] offset:16
	global_load_dwordx4 v[158:161], v130, s[64:65]
	v_cmp_gt_i32_e32 vcc, 2, v0
	v_lshlrev_b32_e32 v193, 1, v131
	s_mov_b32 s18, 0x1f9e0
	v_cndmask_b32_e64 v178, 1.0, -1.0, vcc
	v_cmp_lt_i32_e32 vcc, 1, v0
	v_lshlrev_b32_e32 v0, 5, v174
	v_and_or_b32 v0, v0, s18, v193
	v_lshl_add_u64 v[182:183], v[176:177], 1, s[0:1]
	v_lshlrev_b64 v[130:131], 12, v[174:175]
	v_lshlrev_b32_e32 v0, 2, v0
	v_lshl_add_u64 v[176:177], v[182:183], 0, v[130:131]
	global_load_dwordx4 v[130:133], v0, s[64:65] offset:2096
	global_load_dwordx4 v[134:137], v0, s[64:65] offset:2080
	global_load_dwordx4 v[138:141], v0, s[64:65] offset:2064
	global_load_dwordx4 v[142:145], v0, s[64:65] offset:2048
	v_lshl_add_u64 v[188:189], s[64:65], 0, v[0:1]
	v_mov_b32_e32 v0, v126
	v_mov_b32_e32 v175, v126
	v_mov_b32_e32 v190, v127
	v_mov_b32_e32 v191, v127
	v_permlane32_swap_b32_e32 v0, v175
	s_nop 0
	v_permlane32_swap_b32_e32 v190, v191
	v_mov_b32_e32 v199, v128
	v_mov_b32_e32 v200, v128
	v_mov_b32_e32 v201, v129
	v_mov_b32_e32 v202, v129
	v_cndmask_b32_e32 v195, v191, v190, vcc
	v_cndmask_b32_e32 v194, v175, v0, vcc
	v_permlane32_swap_b32_e32 v199, v200
	v_permlane32_swap_b32_e32 v201, v202
	v_pk_mul_f32 v[194:195], v[178:179], v[194:195] op_sel_hi:[0,1]
	v_mov_b32_e32 v0, v122
	v_mov_b32_e32 v175, v123
	s_mov_b64 s[30:31], 0x1000
	s_mov_b64 s[28:29], 0x1800
	s_waitcnt vmcnt(0)
	v_mov_b32_e32 v191, v160
	v_mov_b32_e32 v160, v159
	v_mov_b32_e32 v190, v158
	v_pk_mul_f32 v[158:159], v[160:161], v[194:195]
	v_cndmask_b32_e32 v195, v202, v201, vcc
	v_cndmask_b32_e32 v194, v200, v199, vcc
	v_pk_fma_f32 v[158:159], v[126:127], v[190:191], v[158:159]
	v_mov_b32_e32 v127, v156
	v_pk_mul_f32 v[194:195], v[178:179], v[194:195] op_sel_hi:[0,1]
	v_mov_b32_e32 v156, v155
	v_mov_b32_e32 v126, v154
	v_pk_mul_f32 v[154:155], v[156:157], v[194:195]
	v_mov_b32_e32 v199, v124
	v_pk_fma_f32 v[128:129], v[128:129], v[126:127], v[154:155]
	v_mov_b32_e32 v154, v122
	v_mov_b32_e32 v155, v123
	s_nop 0
	v_permlane32_swap_b32_e32 v0, v154
	v_permlane32_swap_b32_e32 v155, v175
	v_cndmask_b32_e32 v155, v175, v155, vcc
	v_cndmask_b32_e32 v154, v154, v0, vcc
	v_mov_b32_e32 v200, v124
	v_mov_b32_e32 v201, v125
	v_mov_b32_e32 v202, v125
	v_mov_b32_e32 v195, v152
	v_pk_mul_f32 v[154:155], v[178:179], v[154:155] op_sel_hi:[0,1]
	v_mov_b32_e32 v152, v151
	v_permlane32_swap_b32_e32 v199, v200
	v_permlane32_swap_b32_e32 v201, v202
	v_mov_b32_e32 v194, v150
	v_pk_mul_f32 v[150:151], v[152:153], v[154:155]
	v_mov_b32_e32 v155, v148
	v_pk_fma_f32 v[150:151], v[122:123], v[194:195], v[150:151]
	v_cndmask_b32_e32 v123, v202, v201, vcc
	v_cndmask_b32_e32 v122, v200, v199, vcc
	v_pk_mul_f32 v[122:123], v[178:179], v[122:123] op_sel_hi:[0,1]
	v_mov_b32_e32 v148, v147
	v_mov_b32_e32 v154, v146
	v_pk_mul_f32 v[122:123], v[148:149], v[122:123]
	v_mov_b32_e32 v0, v118
	v_pk_fma_f32 v[146:147], v[124:125], v[154:155], v[122:123]
	v_cvt_pk_bf16_f32 v122, v158, v159
	v_cvt_pk_bf16_f32 v123, v128, v129
	v_cvt_pk_bf16_f32 v124, v150, v151
	v_cvt_pk_bf16_f32 v125, v146, v147
	global_store_dwordx4 v[176:177], v[122:125], off nt
	v_mov_b32_e32 v128, v120
	v_mov_b32_e32 v129, v121
	v_mov_b32_e32 v122, v118
	v_mov_b32_e32 v123, v119
	v_mov_b32_e32 v124, v119
	v_permlane32_swap_b32_e32 v0, v122
	s_nop 0
	v_permlane32_swap_b32_e32 v123, v124
	v_cndmask_b32_e32 v123, v124, v123, vcc
	v_cndmask_b32_e32 v122, v122, v0, vcc
	v_mov_b32_e32 v125, v120
	v_mov_b32_e32 v146, v121
	v_pk_mul_f32 v[122:123], v[178:179], v[122:123] op_sel_hi:[0,1]
	v_permlane32_swap_b32_e32 v125, v128
	v_permlane32_swap_b32_e32 v129, v146
	v_pk_mul_f32 v[122:123], v[160:161], v[122:123]
	v_mov_b32_e32 v0, v114
	v_pk_fma_f32 v[118:119], v[118:119], v[190:191], v[122:123]
	v_cndmask_b32_e32 v123, v146, v129, vcc
	v_cndmask_b32_e32 v122, v128, v125, vcc
	v_pk_mul_f32 v[122:123], v[178:179], v[122:123] op_sel_hi:[0,1]
	v_pk_mul_f32 v[122:123], v[156:157], v[122:123]
	v_mov_b32_e32 v124, v115
	v_pk_fma_f32 v[120:121], v[120:121], v[126:127], v[122:123]
	v_mov_b32_e32 v122, v114
	v_mov_b32_e32 v123, v115
	s_nop 0
	v_permlane32_swap_b32_e32 v0, v122
	v_permlane32_swap_b32_e32 v123, v124
	v_cndmask_b32_e32 v123, v124, v123, vcc
	v_cndmask_b32_e32 v122, v122, v0, vcc
	v_mov_b32_e32 v125, v116
	v_mov_b32_e32 v126, v116
	v_mov_b32_e32 v127, v117
	v_mov_b32_e32 v128, v117
	v_pk_mul_f32 v[122:123], v[178:179], v[122:123] op_sel_hi:[0,1]
	v_permlane32_swap_b32_e32 v125, v126
	v_permlane32_swap_b32_e32 v127, v128
	v_pk_mul_f32 v[122:123], v[152:153], v[122:123]
	v_mov_b32_e32 v0, v110
	v_pk_fma_f32 v[122:123], v[114:115], v[194:195], v[122:123]
	v_cndmask_b32_e32 v115, v128, v127, vcc
	v_cndmask_b32_e32 v114, v126, v125, vcc
	v_pk_mul_f32 v[114:115], v[178:179], v[114:115] op_sel_hi:[0,1]
	v_pk_mul_f32 v[114:115], v[148:149], v[114:115]
	v_add_co_u32_e64 v148, s[0:1], s57, v188
	v_pk_fma_f32 v[124:125], v[116:117], v[154:155], v[114:115]
	v_cvt_pk_bf16_f32 v114, v118, v119
	v_cvt_pk_bf16_f32 v115, v120, v121
	v_cvt_pk_bf16_f32 v116, v122, v123
	v_cvt_pk_bf16_f32 v117, v124, v125
	global_store_dwordx4 v[176:177], v[114:117], off offset:256 nt
	v_lshl_add_u64 v[126:127], v[188:189], 0, s[30:31]
	v_addc_co_u32_e64 v149, s[0:1], 0, v189, s[0:1]
	v_lshlrev_b64 v[114:115], 12, v[186:187]
	v_mov_b32_e32 v150, v110
	v_mov_b32_e32 v151, v111
	v_mov_b32_e32 v152, v111
	v_lshl_add_u64 v[146:147], v[182:183], 0, v[114:115]
	global_load_dwordx4 v[122:125], v[148:149], off
	global_load_dwordx4 v[114:117], v[126:127], off offset:48
	global_load_dwordx4 v[118:121], v[126:127], off offset:32
	s_nop 0
	global_load_dwordx4 v[126:129], v[126:127], off offset:16
	v_permlane32_swap_b32_e32 v0, v150
	v_permlane32_swap_b32_e32 v151, v152
	v_cndmask_b32_e32 v151, v152, v151, vcc
	v_cndmask_b32_e32 v150, v150, v0, vcc
	v_mov_b32_e32 v154, v112
	v_mov_b32_e32 v155, v112
	v_mov_b32_e32 v156, v113
	v_mov_b32_e32 v157, v113
	v_mov_b32_e32 v153, v144
	v_pk_mul_f32 v[150:151], v[178:179], v[150:151] op_sel_hi:[0,1]
	v_mov_b32_e32 v144, v143
	v_permlane32_swap_b32_e32 v154, v155
	v_permlane32_swap_b32_e32 v156, v157
	v_mov_b32_e32 v152, v142
	v_pk_mul_f32 v[142:143], v[144:145], v[150:151]
	v_mov_b32_e32 v151, v140
	v_pk_fma_f32 v[110:111], v[110:111], v[152:153], v[142:143]
	v_cndmask_b32_e32 v143, v157, v156, vcc
	v_cndmask_b32_e32 v142, v155, v154, vcc
	v_pk_mul_f32 v[142:143], v[178:179], v[142:143] op_sel_hi:[0,1]
	v_mov_b32_e32 v140, v139
	v_mov_b32_e32 v150, v138
	v_pk_mul_f32 v[138:139], v[140:141], v[142:143]
	v_mov_b32_e32 v0, v106
	v_pk_fma_f32 v[112:113], v[112:113], v[150:151], v[138:139]
	v_mov_b32_e32 v138, v106
	v_mov_b32_e32 v139, v107
	v_mov_b32_e32 v142, v107
	v_permlane32_swap_b32_e32 v0, v138
	s_nop 0
	v_permlane32_swap_b32_e32 v139, v142
	v_cndmask_b32_e32 v139, v142, v139, vcc
	v_cndmask_b32_e32 v138, v138, v0, vcc
	v_mov_b32_e32 v154, v108
	v_mov_b32_e32 v155, v108
	v_mov_b32_e32 v156, v109
	v_mov_b32_e32 v157, v109
	v_mov_b32_e32 v143, v136
	v_pk_mul_f32 v[138:139], v[178:179], v[138:139] op_sel_hi:[0,1]
	v_mov_b32_e32 v136, v135
	v_permlane32_swap_b32_e32 v154, v155
	v_permlane32_swap_b32_e32 v156, v157
	v_mov_b32_e32 v142, v134
	v_pk_mul_f32 v[134:135], v[136:137], v[138:139]
	v_mov_b32_e32 v139, v132
	v_pk_fma_f32 v[134:135], v[106:107], v[142:143], v[134:135]
	v_cndmask_b32_e32 v107, v157, v156, vcc
	v_cndmask_b32_e32 v106, v155, v154, vcc
	v_pk_mul_f32 v[106:107], v[178:179], v[106:107] op_sel_hi:[0,1]
	v_mov_b32_e32 v132, v131
	v_mov_b32_e32 v138, v130
	v_pk_mul_f32 v[106:107], v[132:133], v[106:107]
	v_mov_b32_e32 v0, v102
	v_pk_fma_f32 v[130:131], v[108:109], v[138:139], v[106:107]
	v_cvt_pk_bf16_f32 v106, v110, v111
	v_cvt_pk_bf16_f32 v107, v112, v113
	v_cvt_pk_bf16_f32 v108, v134, v135
	v_cvt_pk_bf16_f32 v109, v130, v131
	global_store_dwordx4 v[146:147], v[106:109], off nt
	v_mov_b32_e32 v110, v104
	v_mov_b32_e32 v111, v105
	v_mov_b32_e32 v106, v102
	v_mov_b32_e32 v107, v103
	v_mov_b32_e32 v108, v103
	v_permlane32_swap_b32_e32 v0, v106
	s_nop 0
	v_permlane32_swap_b32_e32 v107, v108
	v_cndmask_b32_e32 v107, v108, v107, vcc
	v_cndmask_b32_e32 v106, v106, v0, vcc
	v_mov_b32_e32 v109, v104
	v_mov_b32_e32 v112, v105
	v_pk_mul_f32 v[106:107], v[178:179], v[106:107] op_sel_hi:[0,1]
	v_permlane32_swap_b32_e32 v109, v110
	v_permlane32_swap_b32_e32 v111, v112
	v_pk_mul_f32 v[106:107], v[144:145], v[106:107]
	v_mov_b32_e32 v0, v98
	v_pk_fma_f32 v[102:103], v[102:103], v[152:153], v[106:107]
	v_cndmask_b32_e32 v107, v112, v111, vcc
	v_cndmask_b32_e32 v106, v110, v109, vcc
	v_pk_mul_f32 v[106:107], v[178:179], v[106:107] op_sel_hi:[0,1]
	v_pk_mul_f32 v[106:107], v[140:141], v[106:107]
	v_mov_b32_e32 v108, v99
	v_pk_fma_f32 v[104:105], v[104:105], v[150:151], v[106:107]
	v_mov_b32_e32 v106, v98
	v_mov_b32_e32 v107, v99
	s_nop 0
	v_permlane32_swap_b32_e32 v0, v106
	v_permlane32_swap_b32_e32 v107, v108
	v_cndmask_b32_e32 v107, v108, v107, vcc
	v_cndmask_b32_e32 v106, v106, v0, vcc
	v_mov_b32_e32 v109, v100
	v_mov_b32_e32 v110, v100
	v_mov_b32_e32 v111, v101
	v_mov_b32_e32 v112, v101
	v_pk_mul_f32 v[106:107], v[178:179], v[106:107] op_sel_hi:[0,1]
	v_permlane32_swap_b32_e32 v109, v110
	v_permlane32_swap_b32_e32 v111, v112
	v_pk_mul_f32 v[106:107], v[136:137], v[106:107]
	v_mov_b32_e32 v0, v94
	v_pk_fma_f32 v[106:107], v[98:99], v[142:143], v[106:107]
	v_cndmask_b32_e32 v99, v112, v111, vcc
	v_cndmask_b32_e32 v98, v110, v109, vcc
	v_pk_mul_f32 v[98:99], v[178:179], v[98:99] op_sel_hi:[0,1]
	v_pk_mul_f32 v[98:99], v[132:133], v[98:99]
	v_lshl_add_u64 v[110:111], v[188:189], 0, s[28:29]
	v_pk_fma_f32 v[108:109], v[100:101], v[138:139], v[98:99]
	v_cvt_pk_bf16_f32 v98, v102, v103
	v_cvt_pk_bf16_f32 v99, v104, v105
	v_cvt_pk_bf16_f32 v100, v106, v107
	v_cvt_pk_bf16_f32 v101, v108, v109
	global_store_dwordx4 v[146:147], v[98:101], off offset:256 nt
	v_mov_b32_e32 v132, v94
	v_mov_b32_e32 v133, v95
	v_lshlrev_b64 v[98:99], 12, v[184:185]
	v_lshl_add_u64 v[130:131], v[182:183], 0, v[98:99]
	global_load_dwordx4 v[106:109], v[148:149], off offset:2048
	global_load_dwordx4 v[98:101], v[110:111], off offset:48
	global_load_dwordx4 v[102:105], v[110:111], off offset:32
	s_nop 0
	global_load_dwordx4 v[110:113], v[110:111], off offset:16
	v_mov_b32_e32 v134, v95
	v_permlane32_swap_b32_e32 v0, v132
	s_nop 0
	v_permlane32_swap_b32_e32 v133, v134
	v_cndmask_b32_e32 v133, v134, v133, vcc
	v_cndmask_b32_e32 v132, v132, v0, vcc
	v_mov_b32_e32 v136, v96
	v_mov_b32_e32 v137, v96
	v_mov_b32_e32 v138, v97
	v_mov_b32_e32 v139, v97
	s_waitcnt vmcnt(9)
	v_mov_b32_e32 v135, v124
	v_pk_mul_f32 v[132:133], v[178:179], v[132:133] op_sel_hi:[0,1]
	v_mov_b32_e32 v124, v123
	v_permlane32_swap_b32_e32 v136, v137
	v_permlane32_swap_b32_e32 v138, v139
	v_mov_b32_e32 v134, v122
	v_pk_mul_f32 v[122:123], v[124:125], v[132:133]
	s_waitcnt vmcnt(6)
	v_mov_b32_e32 v133, v128
	v_pk_fma_f32 v[94:95], v[94:95], v[134:135], v[122:123]
	v_cndmask_b32_e32 v123, v139, v138, vcc
	v_cndmask_b32_e32 v122, v137, v136, vcc
	v_pk_mul_f32 v[122:123], v[178:179], v[122:123] op_sel_hi:[0,1]
	v_mov_b32_e32 v128, v127
	v_mov_b32_e32 v132, v126
	v_pk_mul_f32 v[122:123], v[128:129], v[122:123]
	v_mov_b32_e32 v0, v90
	v_pk_fma_f32 v[96:97], v[96:97], v[132:133], v[122:123]
	v_mov_b32_e32 v122, v90
	v_mov_b32_e32 v123, v91
	v_mov_b32_e32 v126, v91
	v_permlane32_swap_b32_e32 v0, v122
	s_nop 0
	v_permlane32_swap_b32_e32 v123, v126
	v_cndmask_b32_e32 v123, v126, v123, vcc
	v_cndmask_b32_e32 v122, v122, v0, vcc
	v_mov_b32_e32 v136, v92
	v_mov_b32_e32 v137, v92
	v_mov_b32_e32 v138, v93
	v_mov_b32_e32 v139, v93
	v_mov_b32_e32 v127, v120
	v_pk_mul_f32 v[122:123], v[178:179], v[122:123] op_sel_hi:[0,1]
	v_mov_b32_e32 v120, v119
	v_permlane32_swap_b32_e32 v136, v137
	v_permlane32_swap_b32_e32 v138, v139
	v_mov_b32_e32 v126, v118
	v_pk_mul_f32 v[118:119], v[120:121], v[122:123]
	v_mov_b32_e32 v123, v116
	v_pk_fma_f32 v[118:119], v[90:91], v[126:127], v[118:119]
	v_cndmask_b32_e32 v91, v139, v138, vcc
	v_cndmask_b32_e32 v90, v137, v136, vcc
	v_pk_mul_f32 v[90:91], v[178:179], v[90:91] op_sel_hi:[0,1]
	v_mov_b32_e32 v116, v115
	v_mov_b32_e32 v122, v114
	v_pk_mul_f32 v[90:91], v[116:117], v[90:91]
	v_mov_b32_e32 v0, v86
	v_pk_fma_f32 v[114:115], v[92:93], v[122:123], v[90:91]
	v_cvt_pk_bf16_f32 v90, v94, v95
	v_cvt_pk_bf16_f32 v91, v96, v97
	v_cvt_pk_bf16_f32 v92, v118, v119
	v_cvt_pk_bf16_f32 v93, v114, v115
	global_store_dwordx4 v[130:131], v[90:93], off nt
	v_mov_b32_e32 v94, v88
	v_mov_b32_e32 v95, v89
	v_mov_b32_e32 v90, v86
	v_mov_b32_e32 v91, v87
	v_mov_b32_e32 v92, v87
	v_permlane32_swap_b32_e32 v0, v90
	s_nop 0
	v_permlane32_swap_b32_e32 v91, v92
	v_cndmask_b32_e32 v91, v92, v91, vcc
	v_cndmask_b32_e32 v90, v90, v0, vcc
	v_mov_b32_e32 v93, v88
	v_mov_b32_e32 v96, v89
	v_pk_mul_f32 v[90:91], v[178:179], v[90:91] op_sel_hi:[0,1]
	v_permlane32_swap_b32_e32 v93, v94
	v_permlane32_swap_b32_e32 v95, v96
	v_pk_mul_f32 v[90:91], v[124:125], v[90:91]
	v_mov_b32_e32 v0, v82
	v_pk_fma_f32 v[86:87], v[86:87], v[134:135], v[90:91]
	v_cndmask_b32_e32 v91, v96, v95, vcc
	v_cndmask_b32_e32 v90, v94, v93, vcc
	v_pk_mul_f32 v[90:91], v[178:179], v[90:91] op_sel_hi:[0,1]
	v_pk_mul_f32 v[90:91], v[128:129], v[90:91]
	v_mov_b32_e32 v92, v83
	v_pk_fma_f32 v[88:89], v[88:89], v[132:133], v[90:91]
	v_mov_b32_e32 v90, v82
	v_mov_b32_e32 v91, v83
	s_nop 0
	v_permlane32_swap_b32_e32 v0, v90
	v_permlane32_swap_b32_e32 v91, v92
	v_cndmask_b32_e32 v91, v92, v91, vcc
	v_cndmask_b32_e32 v90, v90, v0, vcc
	v_mov_b32_e32 v93, v84
	v_mov_b32_e32 v94, v84
	v_mov_b32_e32 v95, v85
	v_mov_b32_e32 v96, v85
	v_pk_mul_f32 v[90:91], v[178:179], v[90:91] op_sel_hi:[0,1]
	v_permlane32_swap_b32_e32 v93, v94
	v_permlane32_swap_b32_e32 v95, v96
	v_pk_mul_f32 v[90:91], v[120:121], v[90:91]
	v_add_u32_e32 v118, 0x80, v174
	v_pk_fma_f32 v[90:91], v[82:83], v[126:127], v[90:91]
	v_cndmask_b32_e32 v83, v96, v95, vcc
	v_cndmask_b32_e32 v82, v94, v93, vcc
	v_pk_mul_f32 v[82:83], v[178:179], v[82:83] op_sel_hi:[0,1]
	v_pk_mul_f32 v[82:83], v[116:117], v[82:83]
	v_lshlrev_b32_e32 v0, 5, v118
	v_pk_fma_f32 v[92:93], v[84:85], v[122:123], v[82:83]
	v_cvt_pk_bf16_f32 v82, v86, v87
	v_cvt_pk_bf16_f32 v83, v88, v89
	v_cvt_pk_bf16_f32 v84, v90, v91
	v_cvt_pk_bf16_f32 v85, v92, v93
	v_and_or_b32 v0, v0, s18, v193
	global_store_dwordx4 v[130:131], v[82:85], off offset:256 nt
	v_lshlrev_b32_e32 v0, 2, v0
	v_mov_b32_e32 v119, v78
	v_lshlrev_b64 v[82:83], 12, v[180:181]
	v_mov_b32_e32 v120, v78
	v_mov_b32_e32 v121, v79
	v_mov_b32_e32 v122, v79
	v_lshl_add_u64 v[116:117], v[182:183], 0, v[82:83]
	global_load_dwordx4 v[82:85], v0, s[64:65] offset:48
	global_load_dwordx4 v[86:89], v0, s[64:65] offset:32
	global_load_dwordx4 v[90:93], v0, s[64:65] offset:16
	global_load_dwordx4 v[94:97], v0, s[64:65]
	v_permlane32_swap_b32_e32 v119, v120
	v_permlane32_swap_b32_e32 v121, v122
	v_cndmask_b32_e32 v121, v122, v121, vcc
	v_cndmask_b32_e32 v120, v120, v119, vcc
	v_mov_b32_e32 v124, v80
	v_mov_b32_e32 v125, v80
	v_mov_b32_e32 v126, v81
	v_mov_b32_e32 v127, v81
	s_waitcnt vmcnt(9)
	v_mov_b32_e32 v123, v108
	v_pk_mul_f32 v[120:121], v[178:179], v[120:121] op_sel_hi:[0,1]
	v_mov_b32_e32 v108, v107
	v_permlane32_swap_b32_e32 v124, v125
	v_permlane32_swap_b32_e32 v126, v127
	v_mov_b32_e32 v122, v106
	v_pk_mul_f32 v[106:107], v[108:109], v[120:121]
	s_waitcnt vmcnt(6)
	v_mov_b32_e32 v121, v112
	v_pk_fma_f32 v[78:79], v[78:79], v[122:123], v[106:107]
	v_cndmask_b32_e32 v107, v127, v126, vcc
	v_cndmask_b32_e32 v106, v125, v124, vcc
	v_pk_mul_f32 v[106:107], v[178:179], v[106:107] op_sel_hi:[0,1]
	v_mov_b32_e32 v112, v111
	v_mov_b32_e32 v120, v110
	v_pk_mul_f32 v[106:107], v[112:113], v[106:107]
	v_mov_b32_e32 v110, v74
	v_pk_fma_f32 v[80:81], v[80:81], v[120:121], v[106:107]
	v_mov_b32_e32 v106, v74
	v_mov_b32_e32 v107, v75
	v_mov_b32_e32 v111, v75
	v_permlane32_swap_b32_e32 v106, v110
	s_nop 0
	v_permlane32_swap_b32_e32 v107, v111
	v_cndmask_b32_e32 v107, v111, v107, vcc
	v_cndmask_b32_e32 v106, v110, v106, vcc
	v_mov_b32_e32 v119, v76
	v_mov_b32_e32 v124, v76
	v_mov_b32_e32 v125, v77
	v_mov_b32_e32 v126, v77
	v_mov_b32_e32 v111, v104
	v_pk_mul_f32 v[106:107], v[178:179], v[106:107] op_sel_hi:[0,1]
	v_mov_b32_e32 v104, v103
	v_permlane32_swap_b32_e32 v119, v124
	v_permlane32_swap_b32_e32 v125, v126
	v_mov_b32_e32 v110, v102
	v_pk_mul_f32 v[102:103], v[104:105], v[106:107]
	v_mov_b32_e32 v107, v100
	v_pk_fma_f32 v[102:103], v[74:75], v[110:111], v[102:103]
	v_cndmask_b32_e32 v75, v126, v125, vcc
	v_cndmask_b32_e32 v74, v124, v119, vcc
	v_pk_mul_f32 v[74:75], v[178:179], v[74:75] op_sel_hi:[0,1]
	v_mov_b32_e32 v100, v99
	v_mov_b32_e32 v106, v98
	v_pk_mul_f32 v[74:75], v[100:101], v[74:75]
	v_ashrrev_i32_e32 v119, 31, v118
	v_pk_fma_f32 v[98:99], v[76:77], v[106:107], v[74:75]
	v_cvt_pk_bf16_f32 v74, v78, v79
	v_cvt_pk_bf16_f32 v75, v80, v81
	v_cvt_pk_bf16_f32 v76, v102, v103
	v_cvt_pk_bf16_f32 v77, v98, v99
	global_store_dwordx4 v[116:117], v[74:77], off nt
	v_mov_b32_e32 v78, v72
	v_mov_b32_e32 v79, v72
	v_mov_b32_e32 v74, v70
	v_mov_b32_e32 v76, v70
	v_mov_b32_e32 v75, v71
	v_mov_b32_e32 v77, v71
	v_permlane32_swap_b32_e32 v74, v76
	s_nop 0
	v_permlane32_swap_b32_e32 v75, v77
	v_cndmask_b32_e32 v75, v77, v75, vcc
	v_cndmask_b32_e32 v74, v76, v74, vcc
	v_mov_b32_e32 v80, v73
	v_mov_b32_e32 v81, v73
	v_pk_mul_f32 v[74:75], v[178:179], v[74:75] op_sel_hi:[0,1]
	v_permlane32_swap_b32_e32 v78, v79
	v_permlane32_swap_b32_e32 v80, v81
	v_pk_mul_f32 v[74:75], v[108:109], v[74:75]
	v_mov_b32_e32 v76, v66
	v_pk_fma_f32 v[70:71], v[70:71], v[122:123], v[74:75]
	v_cndmask_b32_e32 v75, v81, v80, vcc
	v_cndmask_b32_e32 v74, v79, v78, vcc
	v_pk_mul_f32 v[74:75], v[178:179], v[74:75] op_sel_hi:[0,1]
	v_pk_mul_f32 v[74:75], v[112:113], v[74:75]
	v_mov_b32_e32 v77, v67
	v_pk_fma_f32 v[72:73], v[72:73], v[120:121], v[74:75]
	v_mov_b32_e32 v74, v66
	v_mov_b32_e32 v75, v67
	s_nop 0
	v_permlane32_swap_b32_e32 v74, v76
	v_permlane32_swap_b32_e32 v75, v77
	v_cndmask_b32_e32 v75, v77, v75, vcc
	v_cndmask_b32_e32 v74, v76, v74, vcc
	v_mov_b32_e32 v78, v68
	v_mov_b32_e32 v79, v68
	v_mov_b32_e32 v80, v69
	v_mov_b32_e32 v81, v69
	v_pk_mul_f32 v[74:75], v[178:179], v[74:75] op_sel_hi:[0,1]
	v_permlane32_swap_b32_e32 v78, v79
	v_permlane32_swap_b32_e32 v80, v81
	v_pk_mul_f32 v[74:75], v[104:105], v[74:75]
	v_lshl_add_u64 v[114:115], s[64:65], 0, v[0:1]
	v_pk_fma_f32 v[74:75], v[66:67], v[110:111], v[74:75]
	v_cndmask_b32_e32 v67, v81, v80, vcc
	v_cndmask_b32_e32 v66, v79, v78, vcc
	v_pk_mul_f32 v[66:67], v[178:179], v[66:67] op_sel_hi:[0,1]
	v_pk_mul_f32 v[66:67], v[100:101], v[66:67]
	v_mov_b32_e32 v100, v62
	v_pk_fma_f32 v[76:77], v[68:69], v[106:107], v[66:67]
	v_cvt_pk_bf16_f32 v66, v70, v71
	v_cvt_pk_bf16_f32 v67, v72, v73
	v_cvt_pk_bf16_f32 v68, v74, v75
	v_cvt_pk_bf16_f32 v69, v76, v77
	global_store_dwordx4 v[116:117], v[66:69], off offset:256 nt
	v_mov_b32_e32 v101, v63
	v_mov_b32_e32 v102, v63
	v_lshlrev_b64 v[66:67], 12, v[118:119]
	v_lshl_add_u64 v[98:99], v[182:183], 0, v[66:67]
	global_load_dwordx4 v[66:69], v0, s[64:65] offset:2096
	global_load_dwordx4 v[70:73], v0, s[64:65] offset:2080
	global_load_dwordx4 v[74:77], v0, s[64:65] offset:2064
	global_load_dwordx4 v[78:81], v0, s[64:65] offset:2048
	v_mov_b32_e32 v0, v62
	s_nop 1
	v_permlane32_swap_b32_e32 v0, v100
	v_permlane32_swap_b32_e32 v101, v102
	v_cndmask_b32_e32 v101, v102, v101, vcc
	v_cndmask_b32_e32 v100, v100, v0, vcc
	v_mov_b32_e32 v104, v64
	v_mov_b32_e32 v105, v64
	v_mov_b32_e32 v106, v65
	v_mov_b32_e32 v107, v65
	s_waitcnt vmcnt(6)
	v_mov_b32_e32 v103, v96
	v_pk_mul_f32 v[100:101], v[178:179], v[100:101] op_sel_hi:[0,1]
	v_mov_b32_e32 v96, v95
	v_permlane32_swap_b32_e32 v104, v105
	v_permlane32_swap_b32_e32 v106, v107
	v_mov_b32_e32 v102, v94
	v_pk_mul_f32 v[94:95], v[96:97], v[100:101]
	v_mov_b32_e32 v101, v92
	v_pk_fma_f32 v[62:63], v[62:63], v[102:103], v[94:95]
	v_cndmask_b32_e32 v95, v107, v106, vcc
	v_cndmask_b32_e32 v94, v105, v104, vcc
	v_pk_mul_f32 v[94:95], v[178:179], v[94:95] op_sel_hi:[0,1]
	v_mov_b32_e32 v92, v91
	v_mov_b32_e32 v100, v90
	v_pk_mul_f32 v[90:91], v[92:93], v[94:95]
	v_mov_b32_e32 v0, v58
	v_pk_fma_f32 v[64:65], v[64:65], v[100:101], v[90:91]
	v_mov_b32_e32 v90, v58
	v_mov_b32_e32 v91, v59
	v_mov_b32_e32 v94, v59
	v_permlane32_swap_b32_e32 v0, v90
	s_nop 0
	v_permlane32_swap_b32_e32 v91, v94
	v_cndmask_b32_e32 v91, v94, v91, vcc
	v_cndmask_b32_e32 v90, v90, v0, vcc
	v_mov_b32_e32 v104, v60
	v_mov_b32_e32 v105, v60
	v_mov_b32_e32 v106, v61
	v_mov_b32_e32 v107, v61
	v_mov_b32_e32 v95, v88
	v_pk_mul_f32 v[90:91], v[178:179], v[90:91] op_sel_hi:[0,1]
	v_mov_b32_e32 v88, v87
	v_permlane32_swap_b32_e32 v104, v105
	v_permlane32_swap_b32_e32 v106, v107
	v_mov_b32_e32 v94, v86
	v_pk_mul_f32 v[86:87], v[88:89], v[90:91]
	v_mov_b32_e32 v91, v84
	v_pk_fma_f32 v[86:87], v[58:59], v[94:95], v[86:87]
	v_cndmask_b32_e32 v59, v107, v106, vcc
	v_cndmask_b32_e32 v58, v105, v104, vcc
	v_pk_mul_f32 v[58:59], v[178:179], v[58:59] op_sel_hi:[0,1]
	v_mov_b32_e32 v84, v83
	v_mov_b32_e32 v90, v82
	v_pk_mul_f32 v[58:59], v[84:85], v[58:59]
	v_mov_b32_e32 v0, v54
	v_pk_fma_f32 v[82:83], v[60:61], v[90:91], v[58:59]
	v_cvt_pk_bf16_f32 v58, v62, v63
	v_cvt_pk_bf16_f32 v59, v64, v65
	v_cvt_pk_bf16_f32 v60, v86, v87
	v_cvt_pk_bf16_f32 v61, v82, v83
	global_store_dwordx4 v[98:99], v[58:61], off nt
	v_mov_b32_e32 v62, v56
	v_mov_b32_e32 v63, v57
	v_mov_b32_e32 v58, v54
	v_mov_b32_e32 v59, v55
	v_mov_b32_e32 v60, v55
	v_permlane32_swap_b32_e32 v0, v58
	s_nop 0
	v_permlane32_swap_b32_e32 v59, v60
	v_cndmask_b32_e32 v59, v60, v59, vcc
	v_cndmask_b32_e32 v58, v58, v0, vcc
	v_mov_b32_e32 v61, v56
	v_mov_b32_e32 v64, v57
	v_pk_mul_f32 v[58:59], v[178:179], v[58:59] op_sel_hi:[0,1]
	v_permlane32_swap_b32_e32 v61, v62
	v_permlane32_swap_b32_e32 v63, v64
	v_pk_mul_f32 v[58:59], v[96:97], v[58:59]
	v_mov_b32_e32 v0, v50
	v_pk_fma_f32 v[54:55], v[54:55], v[102:103], v[58:59]
	v_cndmask_b32_e32 v59, v64, v63, vcc
	v_cndmask_b32_e32 v58, v62, v61, vcc
	v_pk_mul_f32 v[58:59], v[178:179], v[58:59] op_sel_hi:[0,1]
	v_pk_mul_f32 v[58:59], v[92:93], v[58:59]
	v_mov_b32_e32 v60, v51
	v_pk_fma_f32 v[56:57], v[56:57], v[100:101], v[58:59]
	v_mov_b32_e32 v58, v50
	v_mov_b32_e32 v59, v51
	s_nop 0
	v_permlane32_swap_b32_e32 v0, v58
	v_permlane32_swap_b32_e32 v59, v60
	v_cndmask_b32_e32 v59, v60, v59, vcc
	v_cndmask_b32_e32 v58, v58, v0, vcc
	v_mov_b32_e32 v61, v52
	v_mov_b32_e32 v62, v52
	v_mov_b32_e32 v63, v53
	v_mov_b32_e32 v64, v53
	v_pk_mul_f32 v[58:59], v[178:179], v[58:59] op_sel_hi:[0,1]
	v_permlane32_swap_b32_e32 v61, v62
	v_permlane32_swap_b32_e32 v63, v64
	v_pk_mul_f32 v[58:59], v[88:89], v[58:59]
	s_mov_b64 s[0:1], 0x90000
	v_pk_fma_f32 v[58:59], v[50:51], v[94:95], v[58:59]
	v_cndmask_b32_e32 v51, v64, v63, vcc
	v_cndmask_b32_e32 v50, v62, v61, vcc
	v_pk_mul_f32 v[50:51], v[178:179], v[50:51] op_sel_hi:[0,1]
	v_pk_mul_f32 v[50:51], v[84:85], v[50:51]
	v_lshl_add_u64 v[82:83], v[176:177], 0, s[0:1]
	v_pk_fma_f32 v[60:61], v[52:53], v[90:91], v[50:51]
	v_cvt_pk_bf16_f32 v50, v54, v55
	v_cvt_pk_bf16_f32 v51, v56, v57
	v_cvt_pk_bf16_f32 v52, v58, v59
	v_cvt_pk_bf16_f32 v53, v60, v61
	v_add_co_u32_e64 v84, s[0:1], s57, v114
	global_store_dwordx4 v[98:99], v[50:53], off offset:256 nt
	v_lshl_add_u64 v[62:63], v[114:115], 0, s[30:31]
	v_addc_co_u32_e64 v85, s[0:1], 0, v115, s[0:1]
	v_mov_b32_e32 v0, v46
	v_mov_b32_e32 v86, v46
	v_mov_b32_e32 v87, v47
	v_mov_b32_e32 v88, v47
	global_load_dwordx4 v[58:61], v[84:85], off
	global_load_dwordx4 v[50:53], v[62:63], off offset:48
	global_load_dwordx4 v[54:57], v[62:63], off offset:32
	s_nop 0
	global_load_dwordx4 v[62:65], v[62:63], off offset:16
	v_permlane32_swap_b32_e32 v0, v86
	v_permlane32_swap_b32_e32 v87, v88
	v_cndmask_b32_e32 v87, v88, v87, vcc
	v_cndmask_b32_e32 v86, v86, v0, vcc
	v_mov_b32_e32 v90, v48
	v_mov_b32_e32 v91, v48
	v_mov_b32_e32 v92, v49
	v_mov_b32_e32 v93, v49
	s_waitcnt vmcnt(6)
	v_mov_b32_e32 v89, v80
	v_pk_mul_f32 v[86:87], v[178:179], v[86:87] op_sel_hi:[0,1]
	v_mov_b32_e32 v80, v79
	v_permlane32_swap_b32_e32 v90, v91
	v_permlane32_swap_b32_e32 v92, v93
	v_mov_b32_e32 v88, v78
	v_pk_mul_f32 v[78:79], v[80:81], v[86:87]
	v_mov_b32_e32 v87, v76
	v_pk_fma_f32 v[46:47], v[46:47], v[88:89], v[78:79]
	v_cndmask_b32_e32 v79, v93, v92, vcc
	v_cndmask_b32_e32 v78, v91, v90, vcc
	v_pk_mul_f32 v[78:79], v[178:179], v[78:79] op_sel_hi:[0,1]
	v_mov_b32_e32 v76, v75
	v_mov_b32_e32 v86, v74
	v_pk_mul_f32 v[74:75], v[76:77], v[78:79]
	v_mov_b32_e32 v0, v42
	v_pk_fma_f32 v[48:49], v[48:49], v[86:87], v[74:75]
	v_mov_b32_e32 v74, v42
	v_mov_b32_e32 v75, v43
	v_mov_b32_e32 v78, v43
	v_permlane32_swap_b32_e32 v0, v74
	s_nop 0
	v_permlane32_swap_b32_e32 v75, v78
	v_cndmask_b32_e32 v75, v78, v75, vcc
	v_cndmask_b32_e32 v74, v74, v0, vcc
	v_mov_b32_e32 v90, v44
	v_mov_b32_e32 v91, v44
	v_mov_b32_e32 v92, v45
	v_mov_b32_e32 v93, v45
	v_mov_b32_e32 v79, v72
	v_pk_mul_f32 v[74:75], v[178:179], v[74:75] op_sel_hi:[0,1]
	v_mov_b32_e32 v72, v71
	v_permlane32_swap_b32_e32 v90, v91
	v_permlane32_swap_b32_e32 v92, v93
	v_mov_b32_e32 v78, v70
	v_pk_mul_f32 v[70:71], v[72:73], v[74:75]
	v_mov_b32_e32 v75, v68
	v_pk_fma_f32 v[70:71], v[42:43], v[78:79], v[70:71]
	v_cndmask_b32_e32 v43, v93, v92, vcc
	v_cndmask_b32_e32 v42, v91, v90, vcc
	v_pk_mul_f32 v[42:43], v[178:179], v[42:43] op_sel_hi:[0,1]
	v_mov_b32_e32 v68, v67
	v_mov_b32_e32 v74, v66
	v_pk_mul_f32 v[42:43], v[68:69], v[42:43]
	s_mov_b32 s0, 0x90000
	v_pk_fma_f32 v[66:67], v[44:45], v[74:75], v[42:43]
	v_cvt_pk_bf16_f32 v42, v46, v47
	v_add_co_u32_e64 v46, s[0:1], s0, v176
	v_cvt_pk_bf16_f32 v43, v48, v49
	v_cvt_pk_bf16_f32 v44, v70, v71
	v_cvt_pk_bf16_f32 v45, v66, v67
	v_addc_co_u32_e64 v47, s[0:1], 0, v177, s[0:1]
	global_store_dwordx4 v[46:47], v[42:45], off nt
	v_mov_b32_e32 v0, v38
	v_mov_b32_e32 v46, v40
	v_mov_b32_e32 v42, v38
	v_mov_b32_e32 v43, v39
	v_mov_b32_e32 v44, v39
	v_permlane32_swap_b32_e32 v0, v42
	s_nop 0
	v_permlane32_swap_b32_e32 v43, v44
	v_cndmask_b32_e32 v43, v44, v43, vcc
	v_cndmask_b32_e32 v42, v42, v0, vcc
	v_mov_b32_e32 v45, v40
	v_mov_b32_e32 v47, v41
	v_mov_b32_e32 v48, v41
	v_pk_mul_f32 v[42:43], v[178:179], v[42:43] op_sel_hi:[0,1]
	v_permlane32_swap_b32_e32 v45, v46
	v_permlane32_swap_b32_e32 v47, v48
	v_pk_mul_f32 v[42:43], v[80:81], v[42:43]
	v_mov_b32_e32 v0, v34
	v_pk_fma_f32 v[38:39], v[38:39], v[88:89], v[42:43]
	v_cndmask_b32_e32 v43, v48, v47, vcc
	v_cndmask_b32_e32 v42, v46, v45, vcc
	v_pk_mul_f32 v[42:43], v[178:179], v[42:43] op_sel_hi:[0,1]
	v_pk_mul_f32 v[42:43], v[76:77], v[42:43]
	v_mov_b32_e32 v44, v35
	v_pk_fma_f32 v[40:41], v[40:41], v[86:87], v[42:43]
	v_mov_b32_e32 v42, v34
	v_mov_b32_e32 v43, v35
	s_nop 0
	v_permlane32_swap_b32_e32 v0, v42
	v_permlane32_swap_b32_e32 v43, v44
	v_cndmask_b32_e32 v43, v44, v43, vcc
	v_cndmask_b32_e32 v42, v42, v0, vcc
	v_mov_b32_e32 v45, v36
	v_mov_b32_e32 v46, v36
	v_mov_b32_e32 v47, v37
	v_mov_b32_e32 v48, v37
	v_pk_mul_f32 v[42:43], v[178:179], v[42:43] op_sel_hi:[0,1]
	v_permlane32_swap_b32_e32 v45, v46
	v_permlane32_swap_b32_e32 v47, v48
	v_pk_mul_f32 v[42:43], v[72:73], v[42:43]
	v_mov_b32_e32 v0, v30
	v_pk_fma_f32 v[42:43], v[34:35], v[78:79], v[42:43]
	v_cndmask_b32_e32 v35, v48, v47, vcc
	v_cndmask_b32_e32 v34, v46, v45, vcc
	v_pk_mul_f32 v[34:35], v[178:179], v[34:35] op_sel_hi:[0,1]
	v_pk_mul_f32 v[34:35], v[68:69], v[34:35]
	v_lshl_add_u64 v[46:47], v[114:115], 0, s[28:29]
	v_pk_fma_f32 v[44:45], v[36:37], v[74:75], v[34:35]
	v_cvt_pk_bf16_f32 v34, v38, v39
	v_cvt_pk_bf16_f32 v35, v40, v41
	v_cvt_pk_bf16_f32 v36, v42, v43
	v_cvt_pk_bf16_f32 v37, v44, v45
	global_store_dwordx4 v[82:83], v[34:37], off offset:256 nt
	global_load_dwordx4 v[42:45], v[84:85], off offset:2048
	s_nop 0
	global_load_dwordx4 v[34:37], v[46:47], off offset:48
	global_load_dwordx4 v[38:41], v[46:47], off offset:32
	s_nop 0
	global_load_dwordx4 v[46:49], v[46:47], off offset:16
	v_mov_b32_e32 v68, v30
	v_mov_b32_e32 v69, v31
	v_mov_b32_e32 v70, v31
	v_permlane32_swap_b32_e32 v0, v68
	s_nop 0
	v_permlane32_swap_b32_e32 v69, v70
	v_cndmask_b32_e32 v69, v70, v69, vcc
	v_cndmask_b32_e32 v68, v68, v0, vcc
	v_mov_b32_e32 v72, v32
	v_mov_b32_e32 v73, v32
	v_mov_b32_e32 v74, v33
	v_mov_b32_e32 v75, v33
	s_waitcnt vmcnt(9)
	v_mov_b32_e32 v71, v60
	v_pk_mul_f32 v[68:69], v[178:179], v[68:69] op_sel_hi:[0,1]
	v_mov_b32_e32 v60, v59
	v_permlane32_swap_b32_e32 v72, v73
	v_permlane32_swap_b32_e32 v74, v75
	v_mov_b32_e32 v70, v58
	v_pk_mul_f32 v[58:59], v[60:61], v[68:69]
	s_waitcnt vmcnt(6)
	v_mov_b32_e32 v69, v64
	v_pk_fma_f32 v[30:31], v[30:31], v[70:71], v[58:59]
	v_cndmask_b32_e32 v59, v75, v74, vcc
	v_cndmask_b32_e32 v58, v73, v72, vcc
	v_pk_mul_f32 v[58:59], v[178:179], v[58:59] op_sel_hi:[0,1]
	v_mov_b32_e32 v64, v63
	v_mov_b32_e32 v68, v62
	v_pk_mul_f32 v[58:59], v[64:65], v[58:59]
	v_mov_b32_e32 v0, v26
	v_pk_fma_f32 v[32:33], v[32:33], v[68:69], v[58:59]
	v_mov_b32_e32 v58, v26
	v_mov_b32_e32 v59, v27
	v_mov_b32_e32 v62, v27
	v_permlane32_swap_b32_e32 v0, v58
	s_nop 0
	v_permlane32_swap_b32_e32 v59, v62
	v_cndmask_b32_e32 v59, v62, v59, vcc
	v_cndmask_b32_e32 v58, v58, v0, vcc
	v_mov_b32_e32 v72, v28
	v_mov_b32_e32 v73, v28
	v_mov_b32_e32 v74, v29
	v_mov_b32_e32 v75, v29
	v_mov_b32_e32 v63, v56
	v_pk_mul_f32 v[58:59], v[178:179], v[58:59] op_sel_hi:[0,1]
	v_mov_b32_e32 v56, v55
	v_permlane32_swap_b32_e32 v72, v73
	v_permlane32_swap_b32_e32 v74, v75
	v_mov_b32_e32 v62, v54
	v_pk_mul_f32 v[54:55], v[56:57], v[58:59]
	s_mov_b64 s[0:1], 0xa0000
	v_pk_fma_f32 v[54:55], v[26:27], v[62:63], v[54:55]
	v_cndmask_b32_e32 v27, v75, v74, vcc
	v_cndmask_b32_e32 v26, v73, v72, vcc
	v_mov_b32_e32 v59, v52
	v_pk_mul_f32 v[26:27], v[178:179], v[26:27] op_sel_hi:[0,1]
	v_mov_b32_e32 v52, v51
	v_lshl_add_u64 v[66:67], v[176:177], 0, s[0:1]
	v_mov_b32_e32 v58, v50
	v_pk_mul_f32 v[26:27], v[52:53], v[26:27]
	s_mov_b32 s0, 0xa0000
	v_pk_fma_f32 v[50:51], v[28:29], v[58:59], v[26:27]
	v_cvt_pk_bf16_f32 v26, v30, v31
	v_add_co_u32_e64 v30, s[0:1], s0, v176
	v_cvt_pk_bf16_f32 v27, v32, v33
	v_cvt_pk_bf16_f32 v28, v54, v55
	v_cvt_pk_bf16_f32 v29, v50, v51
	v_addc_co_u32_e64 v31, s[0:1], 0, v177, s[0:1]
	global_store_dwordx4 v[30:31], v[26:29], off nt
	v_mov_b32_e32 v0, v22
	v_mov_b32_e32 v30, v24
	v_mov_b32_e32 v26, v22
	v_mov_b32_e32 v27, v23
	v_mov_b32_e32 v28, v23
	v_permlane32_swap_b32_e32 v0, v26
	s_nop 0
	v_permlane32_swap_b32_e32 v27, v28
	v_cndmask_b32_e32 v27, v28, v27, vcc
	v_cndmask_b32_e32 v26, v26, v0, vcc
	v_mov_b32_e32 v29, v24
	v_mov_b32_e32 v31, v25
	v_mov_b32_e32 v32, v25
	v_pk_mul_f32 v[26:27], v[178:179], v[26:27] op_sel_hi:[0,1]
	v_permlane32_swap_b32_e32 v29, v30
	v_permlane32_swap_b32_e32 v31, v32
	v_pk_mul_f32 v[26:27], v[60:61], v[26:27]
	v_mov_b32_e32 v0, v18
	v_pk_fma_f32 v[22:23], v[22:23], v[70:71], v[26:27]
	v_cndmask_b32_e32 v27, v32, v31, vcc
	v_cndmask_b32_e32 v26, v30, v29, vcc
	v_pk_mul_f32 v[26:27], v[178:179], v[26:27] op_sel_hi:[0,1]
	v_pk_mul_f32 v[26:27], v[64:65], v[26:27]
	v_mov_b32_e32 v28, v19
	v_pk_fma_f32 v[24:25], v[24:25], v[68:69], v[26:27]
	v_mov_b32_e32 v26, v18
	v_mov_b32_e32 v27, v19
	s_nop 0
	v_permlane32_swap_b32_e32 v0, v26
	v_permlane32_swap_b32_e32 v27, v28
	v_cndmask_b32_e32 v27, v28, v27, vcc
	v_cndmask_b32_e32 v26, v26, v0, vcc
	v_mov_b32_e32 v29, v20
	v_mov_b32_e32 v30, v20
	v_mov_b32_e32 v31, v21
	v_mov_b32_e32 v32, v21
	v_pk_mul_f32 v[26:27], v[178:179], v[26:27] op_sel_hi:[0,1]
	v_permlane32_swap_b32_e32 v29, v30
	v_permlane32_swap_b32_e32 v31, v32
	v_pk_mul_f32 v[26:27], v[56:57], v[26:27]
	v_mov_b32_e32 v0, v14
	v_pk_fma_f32 v[26:27], v[18:19], v[62:63], v[26:27]
	v_cndmask_b32_e32 v19, v32, v31, vcc
	v_cndmask_b32_e32 v18, v30, v29, vcc
	v_pk_mul_f32 v[18:19], v[178:179], v[18:19] op_sel_hi:[0,1]
	v_pk_mul_f32 v[18:19], v[52:53], v[18:19]
	v_mov_b32_e32 v30, v13
	v_pk_fma_f32 v[28:29], v[20:21], v[58:59], v[18:19]
	v_cvt_pk_bf16_f32 v18, v22, v23
	v_cvt_pk_bf16_f32 v19, v24, v25
	v_cvt_pk_bf16_f32 v20, v26, v27
	v_cvt_pk_bf16_f32 v21, v28, v29
	global_store_dwordx4 v[66:67], v[18:21], off offset:256 nt
	v_mov_b32_e32 v22, v15
	v_mov_b32_e32 v24, v16
	v_mov_b32_e32 v20, v14
	v_mov_b32_e32 v21, v15
	s_nop 0
	v_permlane32_swap_b32_e32 v0, v20
	v_permlane32_swap_b32_e32 v21, v22
	v_cndmask_b32_e32 v21, v22, v21, vcc
	v_cndmask_b32_e32 v20, v20, v0, vcc
	v_mov_b32_e32 v25, v16
	v_mov_b32_e32 v26, v17
	v_mov_b32_e32 v27, v17
	s_waitcnt vmcnt(5)
	v_mov_b32_e32 v23, v44
	v_pk_mul_f32 v[20:21], v[178:179], v[20:21] op_sel_hi:[0,1]
	v_mov_b32_e32 v44, v43
	v_permlane32_swap_b32_e32 v24, v25
	v_permlane32_swap_b32_e32 v26, v27
	v_mov_b32_e32 v22, v42
	v_pk_mul_f32 v[20:21], v[44:45], v[20:21]
	v_mov_b32_e32 v0, v10
	v_pk_fma_f32 v[14:15], v[14:15], v[22:23], v[20:21]
	v_cndmask_b32_e32 v21, v27, v26, vcc
	v_cndmask_b32_e32 v20, v25, v24, vcc
	s_waitcnt vmcnt(2)
	v_mov_b32_e32 v25, v48
	v_pk_mul_f32 v[20:21], v[178:179], v[20:21] op_sel_hi:[0,1]
	v_mov_b32_e32 v48, v47
	v_mov_b32_e32 v24, v46
	v_pk_mul_f32 v[20:21], v[48:49], v[20:21]
	v_mov_b32_e32 v26, v11
	v_pk_fma_f32 v[16:17], v[16:17], v[24:25], v[20:21]
	v_mov_b32_e32 v20, v10
	v_mov_b32_e32 v21, v11
	s_nop 0
	v_permlane32_swap_b32_e32 v0, v20
	v_permlane32_swap_b32_e32 v21, v26
	v_cndmask_b32_e32 v21, v26, v21, vcc
	v_cndmask_b32_e32 v20, v20, v0, vcc
	v_mov_b32_e32 v28, v12
	v_mov_b32_e32 v29, v12
	v_mov_b32_e32 v31, v13
	v_mov_b32_e32 v27, v40
	v_pk_mul_f32 v[20:21], v[178:179], v[20:21] op_sel_hi:[0,1]
	v_mov_b32_e32 v40, v39
	v_permlane32_swap_b32_e32 v28, v29
	v_permlane32_swap_b32_e32 v30, v31
	v_mov_b32_e32 v26, v38
	v_pk_mul_f32 v[20:21], v[40:41], v[20:21]
	s_mov_b64 s[0:1], 0xb0000
	v_pk_fma_f32 v[20:21], v[10:11], v[26:27], v[20:21]
	v_cndmask_b32_e32 v11, v31, v30, vcc
	v_cndmask_b32_e32 v10, v29, v28, vcc
	v_mov_b32_e32 v29, v36
	v_pk_mul_f32 v[10:11], v[178:179], v[10:11] op_sel_hi:[0,1]
	v_mov_b32_e32 v36, v35
	v_lshl_add_u64 v[18:19], v[176:177], 0, s[0:1]
	v_mov_b32_e32 v28, v34
	v_pk_mul_f32 v[10:11], v[36:37], v[10:11]
	s_mov_b32 s0, 0xb0000
	v_pk_fma_f32 v[30:31], v[12:13], v[28:29], v[10:11]
	v_cvt_pk_bf16_f32 v10, v14, v15
	v_add_co_u32_e64 v14, s[0:1], s0, v176
	v_cvt_pk_bf16_f32 v11, v16, v17
	v_cvt_pk_bf16_f32 v12, v20, v21
	v_cvt_pk_bf16_f32 v13, v30, v31
	v_addc_co_u32_e64 v15, s[0:1], 0, v177, s[0:1]
	global_store_dwordx4 v[14:15], v[10:13], off nt
	v_mov_b32_e32 v0, v6
	v_mov_b32_e32 v14, v8
	v_mov_b32_e32 v10, v6
	v_mov_b32_e32 v11, v7
	v_mov_b32_e32 v12, v7
	v_permlane32_swap_b32_e32 v0, v10
	s_nop 0
	v_permlane32_swap_b32_e32 v11, v12
	v_cndmask_b32_e32 v11, v12, v11, vcc
	v_cndmask_b32_e32 v10, v10, v0, vcc
	v_mov_b32_e32 v13, v8
	v_mov_b32_e32 v15, v9
	v_mov_b32_e32 v16, v9
	v_pk_mul_f32 v[10:11], v[178:179], v[10:11] op_sel_hi:[0,1]
	v_permlane32_swap_b32_e32 v13, v14
	v_permlane32_swap_b32_e32 v15, v16
	v_pk_mul_f32 v[10:11], v[44:45], v[10:11]
	v_mov_b32_e32 v0, v2
	v_pk_fma_f32 v[6:7], v[6:7], v[22:23], v[10:11]
	v_cndmask_b32_e32 v11, v16, v15, vcc
	v_cndmask_b32_e32 v10, v14, v13, vcc
	v_pk_mul_f32 v[10:11], v[178:179], v[10:11] op_sel_hi:[0,1]
	v_pk_mul_f32 v[10:11], v[48:49], v[10:11]
	v_mov_b32_e32 v12, v3
	v_pk_fma_f32 v[8:9], v[8:9], v[24:25], v[10:11]
	v_mov_b32_e32 v10, v2
	v_mov_b32_e32 v11, v3
	s_nop 0
	v_permlane32_swap_b32_e32 v0, v10
	v_permlane32_swap_b32_e32 v11, v12
	v_cndmask_b32_e32 v11, v12, v11, vcc
	v_cndmask_b32_e32 v10, v10, v0, vcc
	v_mov_b32_e32 v13, v4
	v_mov_b32_e32 v14, v4
	v_mov_b32_e32 v15, v5
	v_mov_b32_e32 v16, v5
	v_pk_mul_f32 v[10:11], v[178:179], v[10:11] op_sel_hi:[0,1]
	v_permlane32_swap_b32_e32 v13, v14
	v_permlane32_swap_b32_e32 v15, v16
	v_pk_mul_f32 v[10:11], v[40:41], v[10:11]
	s_nop 0
	v_pk_fma_f32 v[10:11], v[2:3], v[26:27], v[10:11]
	v_cndmask_b32_e32 v3, v16, v15, vcc
	v_cndmask_b32_e32 v2, v14, v13, vcc
	v_pk_mul_f32 v[2:3], v[178:179], v[2:3] op_sel_hi:[0,1]
	v_pk_mul_f32 v[2:3], v[36:37], v[2:3]
	s_nop 0
	v_pk_fma_f32 v[12:13], v[4:5], v[28:29], v[2:3]
	v_cvt_pk_bf16_f32 v2, v6, v7
	v_cvt_pk_bf16_f32 v3, v8, v9
	v_cvt_pk_bf16_f32 v4, v10, v11
	v_cvt_pk_bf16_f32 v5, v12, v13
	global_store_dwordx4 v[18:19], v[2:5], off offset:256 nt
	s_andn2_b64 vcc, exec, s[88:89]
	s_mov_b64 s[0:1], -1
	s_cbranch_vccnz .LBB0_222

.LBB0_314:
	v_cvt_f32_i32_e32 v155, v145
	v_cvt_f32_i32_e32 v157, v143
	v_cvt_f32_i32_e32 v156, v142
	v_cvt_f32_i32_e32 v154, v144
	v_pk_mul_f32 v[158:159], v[190:191], v[16:17] op_sel_hi:[0,1]
	v_pk_mul_f32 v[160:161], v[190:191], v[14:15] op_sel_hi:[0,1]
	v_pk_mul_f32 v[156:157], v[160:161], v[156:157]
	v_pk_mul_f32 v[154:155], v[158:159], v[154:155]
	s_lshl_b32 s18, s18, 6
	v_pk_mul_f32 v[154:155], v[154:155], v[148:149]
	v_pk_mul_f32 v[148:149], v[156:157], v[146:147]
	v_cvt_f32_i32_e32 v147, v141
	v_cvt_f32_i32_e32 v157, v139
	v_cvt_f32_i32_e32 v156, v138
	v_cvt_f32_i32_e32 v146, v140
	s_addk_i32 s18, 0xf800
	s_ashr_i32 s19, s18, 31
	v_pk_mul_f32 v[158:159], v[190:191], v[12:13] op_sel_hi:[0,1]
	v_pk_mul_f32 v[160:161], v[190:191], v[10:11] op_sel_hi:[0,1]
	s_lshl_b64 s[18:19], s[18:19], 1
	v_readlane_b32 s31, v255, 16
	v_pk_mul_f32 v[156:157], v[160:161], v[156:157]
	v_pk_mul_f32 v[158:159], v[158:159], v[146:147]
	s_add_u32 s18, s31, s18
	v_readlane_b32 s31, v255, 17
	s_addc_u32 s19, s31, s19
	v_pk_mul_f32 v[152:153], v[158:159], v[152:153]
	v_pk_mul_f32 v[150:151], v[156:157], v[150:151]
	v_lshl_add_u64 v[146:147], v[194:195], 1, s[18:19]
	v_cvt_pk_bf16_f32 v150, v150, v151
	v_cvt_pk_bf16_f32 v151, v152, v153
	v_lshlrev_b64 v[152:153], 12, v[192:193]
	v_cvt_pk_bf16_f32 v148, v148, v149
	v_cvt_pk_bf16_f32 v149, v154, v155
	v_lshl_add_u64 v[152:153], v[146:147], 0, v[152:153]
	global_store_dwordx4 v[152:153], v[148:151], off nt
	v_cvt_f32_i32_e32 v153, v113
	v_cvt_f32_i32_e32 v152, v112
	v_cvt_f32_i32_e32 v149, v111
	v_cvt_f32_i32_e32 v148, v110
	v_pk_mul_f32 v[150:151], v[188:189], v[6:7] op_sel_hi:[0,1]
	s_and_b64 vcc, exec, s[42:43]
	v_pk_mul_f32 v[148:149], v[150:151], v[148:149]
	v_pk_mul_f32 v[150:151], v[188:189], v[8:9] op_sel_hi:[0,1]
	v_pk_mul_f32 v[150:151], v[150:151], v[152:153]
	s_cbranch_vccnz .LBB0_316
	v_mul_f32_e32 v152, 0xbfb8aa3b, v148
	v_mul_f32_e32 v153, 0xbfb8aa3b, v149
	v_mul_f32_e32 v154, 0xbfb8aa3b, v150
	v_mul_f32_e32 v155, 0xbfb8aa3b, v151
	v_exp_f32_e32 v152, v152
	v_exp_f32_e32 v153, v153
	v_exp_f32_e32 v154, v154
	v_exp_f32_e32 v155, v155
	v_add_f32_e32 v152, 1.0, v152
	v_add_f32_e32 v153, 1.0, v153
	v_add_f32_e32 v154, 1.0, v154
	v_add_f32_e32 v155, 1.0, v155
	v_rcp_f32_e32 v152, v152
	v_rcp_f32_e32 v153, v153
	v_rcp_f32_e32 v154, v154
	v_rcp_f32_e32 v155, v155
	v_pk_mul_f32 v[148:149], v[148:149], v[152:153]
	v_pk_mul_f32 v[150:151], v[150:151], v[154:155]

.LBB0_318:
	v_cvt_f32_i32_e32 v159, v135
	v_cvt_f32_i32_e32 v158, v134
	v_cvt_f32_i32_e32 v157, v137
	v_cvt_f32_i32_e32 v156, v136
	v_pk_mul_f32 v[214:215], v[188:189], v[14:15] op_sel_hi:[0,1]
	v_pk_mul_f32 v[160:161], v[188:189], v[16:17] op_sel_hi:[0,1]
	v_pk_mul_f32 v[158:159], v[214:215], v[158:159]
	v_pk_mul_f32 v[156:157], v[160:161], v[156:157]
	v_pk_mul_f32 v[148:149], v[158:159], v[148:149]
	v_cvt_f32_i32_e32 v159, v131
	v_cvt_f32_i32_e32 v158, v130
	v_pk_mul_f32 v[150:151], v[156:157], v[150:151]
	v_cvt_f32_i32_e32 v157, v133
	v_cvt_f32_i32_e32 v156, v132
	v_pk_mul_f32 v[214:215], v[188:189], v[10:11] op_sel_hi:[0,1]
	v_pk_mul_f32 v[160:161], v[188:189], v[12:13] op_sel_hi:[0,1]
	v_pk_mul_f32 v[158:159], v[214:215], v[158:159]
	v_pk_mul_f32 v[156:157], v[160:161], v[156:157]
	v_pk_mul_f32 v[152:153], v[158:159], v[152:153]
	v_pk_mul_f32 v[154:155], v[156:157], v[154:155]
	v_cvt_pk_bf16_f32 v148, v148, v149
	v_cvt_pk_bf16_f32 v149, v150, v151
	v_cvt_pk_bf16_f32 v150, v152, v153
	v_lshlrev_b64 v[152:153], 12, v[206:207]
	v_cvt_pk_bf16_f32 v151, v154, v155
	v_lshl_add_u64 v[152:153], v[146:147], 0, v[152:153]
	global_store_dwordx4 v[152:153], v[148:151], off nt
	v_cvt_f32_i32_e32 v153, v97
	v_cvt_f32_i32_e32 v152, v96
	v_cvt_f32_i32_e32 v149, v95
	v_cvt_f32_i32_e32 v148, v94
	v_pk_mul_f32 v[150:151], v[186:187], v[6:7] op_sel_hi:[0,1]
	s_and_b64 vcc, exec, s[42:43]
	v_pk_mul_f32 v[148:149], v[150:151], v[148:149]
	v_pk_mul_f32 v[150:151], v[186:187], v[8:9] op_sel_hi:[0,1]
	v_pk_mul_f32 v[150:151], v[150:151], v[152:153]
	s_cbranch_vccnz .LBB0_320
	v_mul_f32_e32 v152, 0xbfb8aa3b, v148
	v_mul_f32_e32 v153, 0xbfb8aa3b, v149
	v_mul_f32_e32 v154, 0xbfb8aa3b, v150
	v_mul_f32_e32 v155, 0xbfb8aa3b, v151
	v_exp_f32_e32 v152, v152
	v_exp_f32_e32 v153, v153
	v_exp_f32_e32 v154, v154
	v_exp_f32_e32 v155, v155
	v_add_f32_e32 v152, 1.0, v152
	v_add_f32_e32 v153, 1.0, v153
	v_add_f32_e32 v154, 1.0, v154
	v_add_f32_e32 v155, 1.0, v155
	v_rcp_f32_e32 v152, v152
	v_rcp_f32_e32 v153, v153
	v_rcp_f32_e32 v154, v154
	v_rcp_f32_e32 v155, v155
	v_pk_mul_f32 v[148:149], v[148:149], v[152:153]
	v_pk_mul_f32 v[150:151], v[150:151], v[154:155]

.LBB0_322:
	v_cvt_f32_i32_e32 v159, v123
	v_cvt_f32_i32_e32 v158, v122
	v_cvt_f32_i32_e32 v157, v125
	v_cvt_f32_i32_e32 v156, v124
	v_pk_mul_f32 v[214:215], v[186:187], v[14:15] op_sel_hi:[0,1]
	v_pk_mul_f32 v[160:161], v[186:187], v[16:17] op_sel_hi:[0,1]
	v_pk_mul_f32 v[158:159], v[214:215], v[158:159]
	v_pk_mul_f32 v[156:157], v[160:161], v[156:157]
	v_pk_mul_f32 v[148:149], v[158:159], v[148:149]
	v_cvt_f32_i32_e32 v159, v115
	v_cvt_f32_i32_e32 v158, v114
	v_pk_mul_f32 v[150:151], v[156:157], v[150:151]
	v_cvt_f32_i32_e32 v157, v117
	v_cvt_f32_i32_e32 v156, v116
	v_pk_mul_f32 v[214:215], v[186:187], v[10:11] op_sel_hi:[0,1]
	v_pk_mul_f32 v[160:161], v[186:187], v[12:13] op_sel_hi:[0,1]
	v_pk_mul_f32 v[158:159], v[214:215], v[158:159]
	v_pk_mul_f32 v[156:157], v[160:161], v[156:157]
	v_pk_mul_f32 v[152:153], v[158:159], v[152:153]
	v_pk_mul_f32 v[154:155], v[156:157], v[154:155]
	v_cvt_pk_bf16_f32 v148, v148, v149
	v_cvt_pk_bf16_f32 v149, v150, v151
	v_cvt_pk_bf16_f32 v150, v152, v153
	v_lshlrev_b64 v[152:153], 12, v[208:209]
	v_cvt_pk_bf16_f32 v151, v154, v155
	v_lshl_add_u64 v[152:153], v[146:147], 0, v[152:153]
	global_store_dwordx4 v[152:153], v[148:151], off nt
	v_cvt_f32_i32_e32 v153, v89
	v_cvt_f32_i32_e32 v152, v88
	v_cvt_f32_i32_e32 v149, v87
	v_cvt_f32_i32_e32 v148, v86
	v_pk_mul_f32 v[150:151], v[182:183], v[6:7] op_sel_hi:[0,1]
	s_and_b64 vcc, exec, s[42:43]
	v_pk_mul_f32 v[148:149], v[150:151], v[148:149]
	v_pk_mul_f32 v[150:151], v[182:183], v[8:9] op_sel_hi:[0,1]
	v_pk_mul_f32 v[150:151], v[150:151], v[152:153]
	s_cbranch_vccnz .LBB0_324
	v_mul_f32_e32 v152, 0xbfb8aa3b, v148
	v_mul_f32_e32 v153, 0xbfb8aa3b, v149
	v_mul_f32_e32 v154, 0xbfb8aa3b, v150
	v_mul_f32_e32 v155, 0xbfb8aa3b, v151
	v_exp_f32_e32 v152, v152
	v_exp_f32_e32 v153, v153
	v_exp_f32_e32 v154, v154
	v_exp_f32_e32 v155, v155
	v_add_f32_e32 v152, 1.0, v152
	v_add_f32_e32 v153, 1.0, v153
	v_add_f32_e32 v154, 1.0, v154
	v_add_f32_e32 v155, 1.0, v155
	v_rcp_f32_e32 v152, v152
	v_rcp_f32_e32 v153, v153
	v_rcp_f32_e32 v154, v154
	v_rcp_f32_e32 v155, v155
	v_pk_mul_f32 v[148:149], v[148:149], v[152:153]
	v_pk_mul_f32 v[150:151], v[150:151], v[154:155]

.LBB0_326:
	v_cvt_f32_i32_e32 v159, v107
	v_cvt_f32_i32_e32 v158, v106
	v_cvt_f32_i32_e32 v157, v109
	v_cvt_f32_i32_e32 v156, v108
	v_pk_mul_f32 v[214:215], v[182:183], v[14:15] op_sel_hi:[0,1]
	v_pk_mul_f32 v[160:161], v[182:183], v[16:17] op_sel_hi:[0,1]
	v_pk_mul_f32 v[158:159], v[214:215], v[158:159]
	v_pk_mul_f32 v[156:157], v[160:161], v[156:157]
	v_pk_mul_f32 v[148:149], v[158:159], v[148:149]
	v_cvt_f32_i32_e32 v159, v99
	v_cvt_f32_i32_e32 v158, v98
	v_pk_mul_f32 v[150:151], v[156:157], v[150:151]
	v_cvt_f32_i32_e32 v157, v101
	v_cvt_f32_i32_e32 v156, v100
	v_pk_mul_f32 v[214:215], v[182:183], v[10:11] op_sel_hi:[0,1]
	v_pk_mul_f32 v[160:161], v[182:183], v[12:13] op_sel_hi:[0,1]
	v_pk_mul_f32 v[158:159], v[214:215], v[158:159]
	v_pk_mul_f32 v[156:157], v[160:161], v[156:157]
	v_pk_mul_f32 v[152:153], v[158:159], v[152:153]
	v_pk_mul_f32 v[154:155], v[156:157], v[154:155]
	v_cvt_pk_bf16_f32 v148, v148, v149
	v_cvt_pk_bf16_f32 v149, v150, v151
	v_cvt_pk_bf16_f32 v150, v152, v153
	v_lshlrev_b64 v[152:153], 12, v[210:211]
	v_cvt_pk_bf16_f32 v151, v154, v155
	v_lshl_add_u64 v[152:153], v[146:147], 0, v[152:153]
	global_store_dwordx4 v[152:153], v[148:151], off nt
	v_cvt_f32_i32_e32 v153, v65
	v_cvt_f32_i32_e32 v152, v64
	v_cvt_f32_i32_e32 v149, v63
	v_cvt_f32_i32_e32 v148, v62
	v_pk_mul_f32 v[150:151], v[180:181], v[6:7] op_sel_hi:[0,1]
	s_and_b64 vcc, exec, s[42:43]
	v_pk_mul_f32 v[148:149], v[150:151], v[148:149]
	v_pk_mul_f32 v[150:151], v[180:181], v[8:9] op_sel_hi:[0,1]
	v_pk_mul_f32 v[150:151], v[150:151], v[152:153]
	s_cbranch_vccnz .LBB0_328
	v_mul_f32_e32 v152, 0xbfb8aa3b, v148
	v_mul_f32_e32 v153, 0xbfb8aa3b, v149
	v_mul_f32_e32 v154, 0xbfb8aa3b, v150
	v_mul_f32_e32 v155, 0xbfb8aa3b, v151
	v_exp_f32_e32 v152, v152
	v_exp_f32_e32 v153, v153
	v_exp_f32_e32 v154, v154
	v_exp_f32_e32 v155, v155
	v_add_f32_e32 v152, 1.0, v152
	v_add_f32_e32 v153, 1.0, v153
	v_add_f32_e32 v154, 1.0, v154
	v_add_f32_e32 v155, 1.0, v155
	v_rcp_f32_e32 v152, v152
	v_rcp_f32_e32 v153, v153
	v_rcp_f32_e32 v154, v154
	v_rcp_f32_e32 v155, v155
	v_pk_mul_f32 v[148:149], v[148:149], v[152:153]
	v_pk_mul_f32 v[150:151], v[150:151], v[154:155]

.LBB0_330:
	v_cvt_f32_i32_e32 v159, v79
	v_cvt_f32_i32_e32 v158, v78
	v_cvt_f32_i32_e32 v157, v81
	v_cvt_f32_i32_e32 v156, v80
	v_pk_mul_f32 v[214:215], v[180:181], v[14:15] op_sel_hi:[0,1]
	v_pk_mul_f32 v[160:161], v[180:181], v[16:17] op_sel_hi:[0,1]
	v_pk_mul_f32 v[158:159], v[214:215], v[158:159]
	v_pk_mul_f32 v[156:157], v[160:161], v[156:157]
	v_pk_mul_f32 v[148:149], v[158:159], v[148:149]
	v_cvt_f32_i32_e32 v159, v75
	v_cvt_f32_i32_e32 v158, v74
	v_pk_mul_f32 v[150:151], v[156:157], v[150:151]
	v_cvt_f32_i32_e32 v157, v77
	v_cvt_f32_i32_e32 v156, v76
	v_pk_mul_f32 v[214:215], v[180:181], v[10:11] op_sel_hi:[0,1]
	v_pk_mul_f32 v[160:161], v[180:181], v[12:13] op_sel_hi:[0,1]
	v_pk_mul_f32 v[158:159], v[214:215], v[158:159]
	v_pk_mul_f32 v[156:157], v[160:161], v[156:157]
	v_pk_mul_f32 v[152:153], v[158:159], v[152:153]
	v_pk_mul_f32 v[154:155], v[156:157], v[154:155]
	v_cvt_pk_bf16_f32 v148, v148, v149
	v_cvt_pk_bf16_f32 v149, v150, v151
	v_cvt_pk_bf16_f32 v150, v152, v153
	v_lshlrev_b64 v[152:153], 12, v[184:185]
	v_cvt_pk_bf16_f32 v151, v154, v155
	v_lshl_add_u64 v[152:153], v[146:147], 0, v[152:153]
	global_store_dwordx4 v[152:153], v[148:151], off nt
	v_cvt_f32_i32_e32 v153, v49
	v_cvt_f32_i32_e32 v152, v48
	v_cvt_f32_i32_e32 v149, v47
	v_cvt_f32_i32_e32 v148, v46
	v_pk_mul_f32 v[150:151], v[178:179], v[6:7] op_sel_hi:[0,1]
	s_and_b64 vcc, exec, s[42:43]
	v_pk_mul_f32 v[148:149], v[150:151], v[148:149]
	v_pk_mul_f32 v[150:151], v[178:179], v[8:9] op_sel_hi:[0,1]
	v_pk_mul_f32 v[150:151], v[150:151], v[152:153]
	s_cbranch_vccnz .LBB0_332
	v_mul_f32_e32 v152, 0xbfb8aa3b, v148
	v_mul_f32_e32 v153, 0xbfb8aa3b, v149
	v_mul_f32_e32 v154, 0xbfb8aa3b, v150
	v_mul_f32_e32 v155, 0xbfb8aa3b, v151
	v_exp_f32_e32 v152, v152
	v_exp_f32_e32 v153, v153
	v_exp_f32_e32 v154, v154
	v_exp_f32_e32 v155, v155
	v_add_f32_e32 v152, 1.0, v152
	v_add_f32_e32 v153, 1.0, v153
	v_add_f32_e32 v154, 1.0, v154
	v_add_f32_e32 v155, 1.0, v155
	v_rcp_f32_e32 v152, v152
	v_rcp_f32_e32 v153, v153
	v_rcp_f32_e32 v154, v154
	v_rcp_f32_e32 v155, v155
	v_pk_mul_f32 v[148:149], v[148:149], v[152:153]
	v_pk_mul_f32 v[150:151], v[150:151], v[154:155]

.LBB0_334:
	v_cvt_f32_i32_e32 v159, v71
	v_cvt_f32_i32_e32 v158, v70
	v_cvt_f32_i32_e32 v157, v73
	v_cvt_f32_i32_e32 v156, v72
	v_pk_mul_f32 v[214:215], v[178:179], v[14:15] op_sel_hi:[0,1]
	v_pk_mul_f32 v[160:161], v[178:179], v[16:17] op_sel_hi:[0,1]
	v_pk_mul_f32 v[158:159], v[214:215], v[158:159]
	v_pk_mul_f32 v[156:157], v[160:161], v[156:157]
	v_pk_mul_f32 v[148:149], v[158:159], v[148:149]
	v_cvt_f32_i32_e32 v159, v67
	v_cvt_f32_i32_e32 v158, v66
	v_pk_mul_f32 v[150:151], v[156:157], v[150:151]
	v_cvt_f32_i32_e32 v157, v69
	v_cvt_f32_i32_e32 v156, v68
	v_pk_mul_f32 v[214:215], v[178:179], v[10:11] op_sel_hi:[0,1]
	v_pk_mul_f32 v[160:161], v[178:179], v[12:13] op_sel_hi:[0,1]
	v_pk_mul_f32 v[158:159], v[214:215], v[158:159]
	v_pk_mul_f32 v[156:157], v[160:161], v[156:157]
	v_pk_mul_f32 v[152:153], v[158:159], v[152:153]
	v_pk_mul_f32 v[154:155], v[156:157], v[154:155]
	v_cvt_pk_bf16_f32 v148, v148, v149
	v_cvt_pk_bf16_f32 v149, v150, v151
	v_cvt_pk_bf16_f32 v150, v152, v153
	v_lshlrev_b64 v[152:153], 12, v[212:213]
	v_cvt_pk_bf16_f32 v151, v154, v155
	v_lshl_add_u64 v[152:153], v[146:147], 0, v[152:153]
	global_store_dwordx4 v[152:153], v[148:151], off nt
	v_cvt_f32_i32_e32 v153, v33
	v_cvt_f32_i32_e32 v152, v32
	v_cvt_f32_i32_e32 v149, v31
	v_cvt_f32_i32_e32 v148, v30
	v_pk_mul_f32 v[150:151], v[176:177], v[6:7] op_sel_hi:[0,1]
	s_and_b64 vcc, exec, s[42:43]
	v_pk_mul_f32 v[148:149], v[150:151], v[148:149]
	v_pk_mul_f32 v[150:151], v[176:177], v[8:9] op_sel_hi:[0,1]
	v_pk_mul_f32 v[150:151], v[150:151], v[152:153]
	s_cbranch_vccnz .LBB0_336
	v_mul_f32_e32 v152, 0xbfb8aa3b, v148
	v_mul_f32_e32 v153, 0xbfb8aa3b, v149
	v_mul_f32_e32 v154, 0xbfb8aa3b, v150
	v_mul_f32_e32 v155, 0xbfb8aa3b, v151
	v_exp_f32_e32 v152, v152
	v_exp_f32_e32 v153, v153
	v_exp_f32_e32 v154, v154
	v_exp_f32_e32 v155, v155
	v_add_f32_e32 v152, 1.0, v152
	v_add_f32_e32 v153, 1.0, v153
	v_add_f32_e32 v154, 1.0, v154
	v_add_f32_e32 v155, 1.0, v155
	v_rcp_f32_e32 v152, v152
	v_rcp_f32_e32 v153, v153
	v_rcp_f32_e32 v154, v154
	v_rcp_f32_e32 v155, v155
	v_pk_mul_f32 v[148:149], v[148:149], v[152:153]
	v_pk_mul_f32 v[150:151], v[150:151], v[154:155]

.LBB0_338:
	v_cvt_f32_i32_e32 v159, v55
	v_cvt_f32_i32_e32 v158, v54
	v_cvt_f32_i32_e32 v157, v57
	v_cvt_f32_i32_e32 v156, v56
	v_pk_mul_f32 v[214:215], v[176:177], v[14:15] op_sel_hi:[0,1]
	v_pk_mul_f32 v[160:161], v[176:177], v[16:17] op_sel_hi:[0,1]
	v_pk_mul_f32 v[158:159], v[214:215], v[158:159]
	v_pk_mul_f32 v[156:157], v[160:161], v[156:157]
	v_pk_mul_f32 v[148:149], v[158:159], v[148:149]
	v_cvt_f32_i32_e32 v159, v51
	v_cvt_f32_i32_e32 v158, v50
	v_pk_mul_f32 v[150:151], v[156:157], v[150:151]
	v_cvt_f32_i32_e32 v157, v53
	v_cvt_f32_i32_e32 v156, v52
	v_pk_mul_f32 v[214:215], v[176:177], v[10:11] op_sel_hi:[0,1]
	v_pk_mul_f32 v[160:161], v[176:177], v[12:13] op_sel_hi:[0,1]
	v_pk_mul_f32 v[158:159], v[214:215], v[158:159]
	v_pk_mul_f32 v[156:157], v[160:161], v[156:157]
	v_pk_mul_f32 v[152:153], v[158:159], v[152:153]
	v_pk_mul_f32 v[154:155], v[156:157], v[154:155]
	v_cvt_pk_bf16_f32 v148, v148, v149
	v_cvt_pk_bf16_f32 v149, v150, v151
	v_cvt_pk_bf16_f32 v150, v152, v153
	v_lshlrev_b64 v[152:153], 12, v[204:205]
	v_cvt_pk_bf16_f32 v151, v154, v155
	v_lshl_add_u64 v[152:153], v[146:147], 0, v[152:153]
	global_store_dwordx4 v[152:153], v[148:151], off nt
	v_cvt_f32_i32_e32 v153, v25
	v_cvt_f32_i32_e32 v152, v24
	v_cvt_f32_i32_e32 v149, v23
	v_cvt_f32_i32_e32 v148, v22
	v_pk_mul_f32 v[150:151], v[174:175], v[6:7] op_sel_hi:[0,1]
	s_and_b64 vcc, exec, s[42:43]
	v_pk_mul_f32 v[148:149], v[150:151], v[148:149]
	v_pk_mul_f32 v[150:151], v[174:175], v[8:9] op_sel_hi:[0,1]
	v_pk_mul_f32 v[150:151], v[150:151], v[152:153]
	s_cbranch_vccnz .LBB0_340
	v_mul_f32_e32 v152, 0xbfb8aa3b, v148
	v_mul_f32_e32 v153, 0xbfb8aa3b, v149
	v_mul_f32_e32 v154, 0xbfb8aa3b, v150
	v_mul_f32_e32 v155, 0xbfb8aa3b, v151
	v_exp_f32_e32 v152, v152
	v_exp_f32_e32 v153, v153
	v_exp_f32_e32 v154, v154
	v_exp_f32_e32 v155, v155
	v_add_f32_e32 v152, 1.0, v152
	v_add_f32_e32 v153, 1.0, v153
	v_add_f32_e32 v154, 1.0, v154
	v_add_f32_e32 v155, 1.0, v155
	v_rcp_f32_e32 v152, v152
	v_rcp_f32_e32 v153, v153
	v_rcp_f32_e32 v154, v154
	v_rcp_f32_e32 v155, v155
	v_pk_mul_f32 v[148:149], v[148:149], v[152:153]
	v_pk_mul_f32 v[150:151], v[150:151], v[154:155]

.LBB0_342:
	v_cvt_f32_i32_e32 v159, v39
	v_cvt_f32_i32_e32 v158, v38
	v_cvt_f32_i32_e32 v157, v41
	v_cvt_f32_i32_e32 v156, v40
	v_pk_mul_f32 v[214:215], v[174:175], v[14:15] op_sel_hi:[0,1]
	v_pk_mul_f32 v[160:161], v[174:175], v[16:17] op_sel_hi:[0,1]
	v_pk_mul_f32 v[158:159], v[214:215], v[158:159]
	v_pk_mul_f32 v[156:157], v[160:161], v[156:157]
	v_pk_mul_f32 v[148:149], v[158:159], v[148:149]
	v_cvt_f32_i32_e32 v159, v35
	v_cvt_f32_i32_e32 v158, v34
	v_pk_mul_f32 v[150:151], v[156:157], v[150:151]
	v_cvt_f32_i32_e32 v157, v37
	v_cvt_f32_i32_e32 v156, v36
	v_pk_mul_f32 v[214:215], v[174:175], v[10:11] op_sel_hi:[0,1]
	v_pk_mul_f32 v[160:161], v[174:175], v[12:13] op_sel_hi:[0,1]
	v_pk_mul_f32 v[158:159], v[214:215], v[158:159]
	v_pk_mul_f32 v[156:157], v[160:161], v[156:157]
	v_pk_mul_f32 v[152:153], v[158:159], v[152:153]
	v_pk_mul_f32 v[154:155], v[156:157], v[154:155]
	v_cvt_pk_bf16_f32 v148, v148, v149
	v_cvt_pk_bf16_f32 v149, v150, v151
	v_cvt_pk_bf16_f32 v150, v152, v153
	v_lshlrev_b64 v[152:153], 12, v[202:203]
	v_cvt_pk_bf16_f32 v151, v154, v155
	v_lshl_add_u64 v[146:147], v[146:147], 0, v[152:153]
	s_mov_b64 s[42:43], 0
	global_store_dwordx4 v[146:147], v[148:151], off nt

.LBB0_344:
	s_and_b64 vcc, exec, s[34:35]
	s_cbranch_vccz .LBB0_346
	s_lshl_b32 s18, s30, 11
	s_addk_i32 s18, 0xa000
	s_ashr_i32 s19, s18, 31
	s_lshl_b64 s[18:19], s[18:19], 2
	s_add_u32 s18, s55, s18
	v_readlane_b32 s30, v255, 12
	s_addc_u32 s19, s30, s19
	v_ashrrev_i32_e32 v201, 31, v200
	v_lshl_add_u64 v[150:151], v[200:201], 2, s[18:19]
	global_load_dwordx4 v[154:157], v[150:151], off offset:16
	global_load_dwordx4 v[158:161], v[150:151], off
	global_load_dwordx4 v[146:149], v[150:151], off offset:528
	s_nop 0
	global_load_dwordx4 v[150:153], v[150:151], off offset:512
	v_cvt_f32_i32_e32 v223, v143
	v_cvt_f32_i32_e32 v222, v142
	v_cvt_f32_i32_e32 v225, v145
	v_cvt_f32_i32_e32 v224, v144
	v_pk_mul_f32 v[218:219], v[190:191], v[16:17] op_sel_hi:[0,1]
	v_pk_mul_f32 v[220:221], v[190:191], v[14:15] op_sel_hi:[0,1]
	v_lshl_add_u64 v[214:215], v[200:201], 1, s[0:1]
	v_lshlrev_b64 v[216:217], 12, v[192:193]
	v_lshl_add_u64 v[216:217], v[214:215], 0, v[216:217]
	s_waitcnt vmcnt(2)
	v_pk_fma_f32 v[218:219], v[218:219], v[224:225], v[160:161]
	v_pk_fma_f32 v[220:221], v[220:221], v[222:223], v[158:159]
	v_cvt_f32_i32_e32 v223, v139
	v_cvt_f32_i32_e32 v222, v138
	v_cvt_f32_i32_e32 v225, v141
	v_cvt_f32_i32_e32 v224, v140
	v_mul_f32_e32 v175, 0xbfb8aa3b, v220
	v_mul_f32_e32 v177, 0xbfb8aa3b, v221
	v_mul_f32_e32 v179, 0xbfb8aa3b, v218
	v_mul_f32_e32 v181, 0xbfb8aa3b, v219
	v_pk_mul_f32 v[218:219], v[190:191], v[12:13] op_sel_hi:[0,1]
	v_pk_mul_f32 v[220:221], v[190:191], v[10:11] op_sel_hi:[0,1]
	v_pk_fma_f32 v[218:219], v[218:219], v[224:225], v[156:157]
	v_pk_fma_f32 v[220:221], v[220:221], v[222:223], v[154:155]
	v_mul_f32_e32 v189, 0xbfb8aa3b, v218
	v_mul_f32_e32 v183, 0xbfb8aa3b, v220
	v_mul_f32_e32 v187, 0xbfb8aa3b, v221
	v_mul_f32_e32 v191, 0xbfb8aa3b, v219
	v_exp_f32_e32 v175, v175
	v_exp_f32_e32 v177, v177
	v_exp_f32_e32 v179, v179
	v_exp_f32_e32 v181, v181
	v_exp_f32_e32 v183, v183
	v_exp_f32_e32 v187, v187
	v_exp_f32_e32 v189, v189
	v_exp_f32_e32 v191, v191
	v_add_f32_e32 v175, 1.0, v175
	v_add_f32_e32 v177, 1.0, v177
	v_add_f32_e32 v179, 1.0, v179
	v_add_f32_e32 v181, 1.0, v181
	v_add_f32_e32 v183, 1.0, v183
	v_add_f32_e32 v187, 1.0, v187
	v_add_f32_e32 v189, 1.0, v189
	v_add_f32_e32 v191, 1.0, v191
	v_rcp_f32_e32 v175, v175
	v_rcp_f32_e32 v177, v177
	v_rcp_f32_e32 v179, v179
	v_rcp_f32_e32 v181, v181
	v_rcp_f32_e32 v183, v183
	v_rcp_f32_e32 v187, v187
	v_rcp_f32_e32 v189, v189
	v_rcp_f32_e32 v191, v191
	v_cvt_f32_i32_e32 v223, v127
	v_cvt_f32_i32_e32 v222, v126
	v_cvt_f32_i32_e32 v225, v129
	v_cvt_f32_i32_e32 v224, v128
	v_cvt_pk_bf16_f32 v218, v175, v177
	v_cvt_pk_bf16_f32 v219, v179, v181
	v_cvt_pk_bf16_f32 v220, v183, v187
	v_cvt_pk_bf16_f32 v221, v189, v191
	global_store_dwordx4 v[216:217], v[218:221], off nt
	s_nop 1
	v_pk_mul_f32 v[218:219], v[190:191], v[8:9] op_sel_hi:[0,1]
	v_pk_mul_f32 v[220:221], v[190:191], v[6:7] op_sel_hi:[0,1]
	s_waitcnt vmcnt(1)
	v_pk_fma_f32 v[218:219], v[218:219], v[224:225], v[152:153]
	v_pk_fma_f32 v[220:221], v[220:221], v[222:223], v[150:151]
	v_cvt_f32_i32_e32 v223, v119
	v_cvt_f32_i32_e32 v222, v118
	v_cvt_f32_i32_e32 v225, v121
	v_cvt_f32_i32_e32 v224, v120
	v_mul_f32_e32 v175, 0xbfb8aa3b, v220
	v_mul_f32_e32 v177, 0xbfb8aa3b, v221
	v_mul_f32_e32 v179, 0xbfb8aa3b, v218
	v_mul_f32_e32 v181, 0xbfb8aa3b, v219
	v_pk_mul_f32 v[218:219], v[190:191], v[4:5] op_sel_hi:[0,1]
	v_pk_mul_f32 v[220:221], v[190:191], v[2:3] op_sel_hi:[0,1]
	v_pk_fma_f32 v[218:219], v[218:219], v[224:225], v[148:149]
	v_pk_fma_f32 v[220:221], v[220:221], v[222:223], v[146:147]
	v_mul_f32_e32 v189, 0xbfb8aa3b, v218
	v_mul_f32_e32 v183, 0xbfb8aa3b, v220
	v_mul_f32_e32 v187, 0xbfb8aa3b, v221
	v_mul_f32_e32 v191, 0xbfb8aa3b, v219
	v_exp_f32_e32 v175, v175
	v_exp_f32_e32 v177, v177
	v_exp_f32_e32 v179, v179
	v_exp_f32_e32 v181, v181
	v_exp_f32_e32 v183, v183
	v_exp_f32_e32 v187, v187
	v_exp_f32_e32 v189, v189
	v_exp_f32_e32 v191, v191
	v_add_f32_e32 v175, 1.0, v175
	v_add_f32_e32 v177, 1.0, v177
	v_add_f32_e32 v179, 1.0, v179
	v_add_f32_e32 v181, 1.0, v181
	v_add_f32_e32 v183, 1.0, v183
	v_add_f32_e32 v187, 1.0, v187
	v_add_f32_e32 v189, 1.0, v189
	v_add_f32_e32 v191, 1.0, v191
	v_rcp_f32_e32 v175, v175
	v_rcp_f32_e32 v177, v177
	v_rcp_f32_e32 v179, v179
	v_rcp_f32_e32 v181, v181
	v_rcp_f32_e32 v183, v183
	v_rcp_f32_e32 v187, v187
	v_rcp_f32_e32 v189, v189
	v_rcp_f32_e32 v191, v191
	v_cvt_f32_i32_e32 v223, v135
	v_cvt_f32_i32_e32 v222, v134
	v_cvt_f32_i32_e32 v225, v137
	v_cvt_f32_i32_e32 v224, v136
	v_cvt_pk_bf16_f32 v218, v175, v177
	v_cvt_pk_bf16_f32 v219, v179, v181
	v_cvt_pk_bf16_f32 v220, v183, v187
	v_cvt_pk_bf16_f32 v221, v189, v191
	global_store_dwordx4 v[216:217], v[218:221], off offset:256 nt
	v_lshlrev_b64 v[216:217], 12, v[206:207]
	v_lshl_add_u64 v[216:217], v[214:215], 0, v[216:217]
	v_pk_mul_f32 v[218:219], v[188:189], v[16:17] op_sel_hi:[0,1]
	v_pk_mul_f32 v[220:221], v[188:189], v[14:15] op_sel_hi:[0,1]
	v_pk_fma_f32 v[218:219], v[218:219], v[224:225], v[160:161]
	v_pk_fma_f32 v[220:221], v[220:221], v[222:223], v[158:159]
	v_cvt_f32_i32_e32 v223, v131
	v_cvt_f32_i32_e32 v222, v130
	v_cvt_f32_i32_e32 v225, v133
	v_cvt_f32_i32_e32 v224, v132
	v_mul_f32_e32 v175, 0xbfb8aa3b, v220
	v_mul_f32_e32 v177, 0xbfb8aa3b, v221
	v_mul_f32_e32 v179, 0xbfb8aa3b, v218
	v_mul_f32_e32 v181, 0xbfb8aa3b, v219
	v_pk_mul_f32 v[218:219], v[188:189], v[12:13] op_sel_hi:[0,1]
	v_pk_mul_f32 v[220:221], v[188:189], v[10:11] op_sel_hi:[0,1]
	v_pk_fma_f32 v[218:219], v[218:219], v[224:225], v[156:157]
	v_pk_fma_f32 v[220:221], v[220:221], v[222:223], v[154:155]
	v_mul_f32_e32 v189, 0xbfb8aa3b, v218
	v_mul_f32_e32 v183, 0xbfb8aa3b, v220
	v_mul_f32_e32 v187, 0xbfb8aa3b, v221
	v_mul_f32_e32 v191, 0xbfb8aa3b, v219
	v_exp_f32_e32 v175, v175
	v_exp_f32_e32 v177, v177
	v_exp_f32_e32 v179, v179
	v_exp_f32_e32 v181, v181
	v_exp_f32_e32 v183, v183
	v_exp_f32_e32 v187, v187
	v_exp_f32_e32 v189, v189
	v_exp_f32_e32 v191, v191
	v_add_f32_e32 v175, 1.0, v175
	v_add_f32_e32 v177, 1.0, v177
	v_add_f32_e32 v179, 1.0, v179
	v_add_f32_e32 v181, 1.0, v181
	v_add_f32_e32 v183, 1.0, v183
	v_add_f32_e32 v187, 1.0, v187
	v_add_f32_e32 v189, 1.0, v189
	v_add_f32_e32 v191, 1.0, v191
	v_rcp_f32_e32 v175, v175
	v_rcp_f32_e32 v177, v177
	v_rcp_f32_e32 v179, v179
	v_rcp_f32_e32 v181, v181
	v_rcp_f32_e32 v183, v183
	v_rcp_f32_e32 v187, v187
	v_rcp_f32_e32 v189, v189
	v_rcp_f32_e32 v191, v191
	v_cvt_f32_i32_e32 v223, v111
	v_cvt_f32_i32_e32 v222, v110
	v_cvt_f32_i32_e32 v225, v113
	v_cvt_f32_i32_e32 v224, v112
	v_cvt_pk_bf16_f32 v218, v175, v177
	v_cvt_pk_bf16_f32 v219, v179, v181
	v_cvt_pk_bf16_f32 v220, v183, v187
	v_cvt_pk_bf16_f32 v221, v189, v191
	global_store_dwordx4 v[216:217], v[218:221], off nt
	s_nop 1
	v_pk_mul_f32 v[218:219], v[188:189], v[8:9] op_sel_hi:[0,1]
	v_pk_mul_f32 v[220:221], v[188:189], v[6:7] op_sel_hi:[0,1]
	v_pk_fma_f32 v[218:219], v[218:219], v[224:225], v[152:153]
	v_pk_fma_f32 v[220:221], v[220:221], v[222:223], v[150:151]
	v_cvt_f32_i32_e32 v223, v103
	v_cvt_f32_i32_e32 v222, v102
	v_cvt_f32_i32_e32 v225, v105
	v_cvt_f32_i32_e32 v224, v104
	v_mul_f32_e32 v175, 0xbfb8aa3b, v220
	v_mul_f32_e32 v177, 0xbfb8aa3b, v221
	v_mul_f32_e32 v179, 0xbfb8aa3b, v218
	v_mul_f32_e32 v181, 0xbfb8aa3b, v219
	v_pk_mul_f32 v[218:219], v[188:189], v[4:5] op_sel_hi:[0,1]
	v_pk_mul_f32 v[220:221], v[188:189], v[2:3] op_sel_hi:[0,1]
	v_pk_fma_f32 v[218:219], v[218:219], v[224:225], v[148:149]
	v_pk_fma_f32 v[220:221], v[220:221], v[222:223], v[146:147]
	v_mul_f32_e32 v189, 0xbfb8aa3b, v218
	v_mul_f32_e32 v183, 0xbfb8aa3b, v220
	v_mul_f32_e32 v187, 0xbfb8aa3b, v221
	v_mul_f32_e32 v191, 0xbfb8aa3b, v219
	v_exp_f32_e32 v175, v175
	v_exp_f32_e32 v177, v177
	v_exp_f32_e32 v179, v179
	v_exp_f32_e32 v181, v181
	v_exp_f32_e32 v183, v183
	v_exp_f32_e32 v187, v187
	v_exp_f32_e32 v189, v189
	v_exp_f32_e32 v191, v191
	v_add_f32_e32 v175, 1.0, v175
	v_add_f32_e32 v177, 1.0, v177
	v_add_f32_e32 v179, 1.0, v179
	v_add_f32_e32 v181, 1.0, v181
	v_add_f32_e32 v183, 1.0, v183
	v_add_f32_e32 v187, 1.0, v187
	v_add_f32_e32 v189, 1.0, v189
	v_add_f32_e32 v191, 1.0, v191
	v_rcp_f32_e32 v175, v175
	v_rcp_f32_e32 v177, v177
	v_rcp_f32_e32 v179, v179
	v_rcp_f32_e32 v181, v181
	v_rcp_f32_e32 v183, v183
	v_rcp_f32_e32 v187, v187
	v_rcp_f32_e32 v189, v189
	v_rcp_f32_e32 v191, v191
	v_cvt_f32_i32_e32 v223, v123
	v_cvt_f32_i32_e32 v222, v122
	v_cvt_f32_i32_e32 v225, v125
	v_cvt_f32_i32_e32 v224, v124
	v_cvt_pk_bf16_f32 v218, v175, v177
	v_cvt_pk_bf16_f32 v219, v179, v181
	v_cvt_pk_bf16_f32 v220, v183, v187
	v_cvt_pk_bf16_f32 v221, v189, v191
	global_store_dwordx4 v[216:217], v[218:221], off offset:256 nt
	v_lshlrev_b64 v[216:217], 12, v[208:209]
	v_lshl_add_u64 v[216:217], v[214:215], 0, v[216:217]
	v_pk_mul_f32 v[218:219], v[186:187], v[16:17] op_sel_hi:[0,1]
	v_pk_mul_f32 v[220:221], v[186:187], v[14:15] op_sel_hi:[0,1]
	v_pk_fma_f32 v[218:219], v[218:219], v[224:225], v[160:161]
	v_pk_fma_f32 v[220:221], v[220:221], v[222:223], v[158:159]
	v_cvt_f32_i32_e32 v223, v115
	v_cvt_f32_i32_e32 v222, v114
	v_cvt_f32_i32_e32 v225, v117
	v_cvt_f32_i32_e32 v224, v116
	v_mul_f32_e32 v175, 0xbfb8aa3b, v220
	v_mul_f32_e32 v177, 0xbfb8aa3b, v221
	v_mul_f32_e32 v179, 0xbfb8aa3b, v218
	v_mul_f32_e32 v181, 0xbfb8aa3b, v219
	v_pk_mul_f32 v[218:219], v[186:187], v[12:13] op_sel_hi:[0,1]
	v_pk_mul_f32 v[220:221], v[186:187], v[10:11] op_sel_hi:[0,1]
	v_pk_fma_f32 v[218:219], v[218:219], v[224:225], v[156:157]
	v_pk_fma_f32 v[220:221], v[220:221], v[222:223], v[154:155]
	v_mul_f32_e32 v189, 0xbfb8aa3b, v218
	v_mul_f32_e32 v183, 0xbfb8aa3b, v220
	v_mul_f32_e32 v187, 0xbfb8aa3b, v221
	v_mul_f32_e32 v191, 0xbfb8aa3b, v219
	v_exp_f32_e32 v175, v175
	v_exp_f32_e32 v177, v177
	v_exp_f32_e32 v179, v179
	v_exp_f32_e32 v181, v181
	v_exp_f32_e32 v183, v183
	v_exp_f32_e32 v187, v187
	v_exp_f32_e32 v189, v189
	v_exp_f32_e32 v191, v191
	v_add_f32_e32 v175, 1.0, v175
	v_add_f32_e32 v177, 1.0, v177
	v_add_f32_e32 v179, 1.0, v179
	v_add_f32_e32 v181, 1.0, v181
	v_add_f32_e32 v183, 1.0, v183
	v_add_f32_e32 v187, 1.0, v187
	v_add_f32_e32 v189, 1.0, v189
	v_add_f32_e32 v191, 1.0, v191
	v_rcp_f32_e32 v175, v175
	v_rcp_f32_e32 v177, v177
	v_rcp_f32_e32 v179, v179
	v_rcp_f32_e32 v181, v181
	v_rcp_f32_e32 v183, v183
	v_rcp_f32_e32 v187, v187
	v_rcp_f32_e32 v189, v189
	v_rcp_f32_e32 v191, v191
	v_cvt_f32_i32_e32 v223, v95
	v_cvt_f32_i32_e32 v222, v94
	v_cvt_f32_i32_e32 v225, v97
	v_cvt_f32_i32_e32 v224, v96
	v_cvt_pk_bf16_f32 v218, v175, v177
	v_cvt_pk_bf16_f32 v219, v179, v181
	v_cvt_pk_bf16_f32 v220, v183, v187
	v_cvt_pk_bf16_f32 v221, v189, v191
	global_store_dwordx4 v[216:217], v[218:221], off nt
	s_nop 1
	v_pk_mul_f32 v[218:219], v[186:187], v[8:9] op_sel_hi:[0,1]
	v_pk_mul_f32 v[220:221], v[186:187], v[6:7] op_sel_hi:[0,1]
	v_pk_fma_f32 v[218:219], v[218:219], v[224:225], v[152:153]
	v_pk_fma_f32 v[220:221], v[220:221], v[222:223], v[150:151]
	v_cvt_f32_i32_e32 v223, v91
	v_cvt_f32_i32_e32 v222, v90
	v_cvt_f32_i32_e32 v225, v93
	v_cvt_f32_i32_e32 v224, v92
	v_mul_f32_e32 v175, 0xbfb8aa3b, v220
	v_mul_f32_e32 v177, 0xbfb8aa3b, v221
	v_mul_f32_e32 v179, 0xbfb8aa3b, v218
	v_mul_f32_e32 v181, 0xbfb8aa3b, v219
	v_pk_mul_f32 v[218:219], v[186:187], v[4:5] op_sel_hi:[0,1]
	v_pk_mul_f32 v[220:221], v[186:187], v[2:3] op_sel_hi:[0,1]
	v_pk_fma_f32 v[218:219], v[218:219], v[224:225], v[148:149]
	v_pk_fma_f32 v[220:221], v[220:221], v[222:223], v[146:147]
	v_mul_f32_e32 v189, 0xbfb8aa3b, v218
	v_mul_f32_e32 v183, 0xbfb8aa3b, v220
	v_mul_f32_e32 v187, 0xbfb8aa3b, v221
	v_mul_f32_e32 v191, 0xbfb8aa3b, v219
	v_exp_f32_e32 v175, v175
	v_exp_f32_e32 v177, v177
	v_exp_f32_e32 v179, v179
	v_exp_f32_e32 v181, v181
	v_exp_f32_e32 v183, v183
	v_exp_f32_e32 v187, v187
	v_exp_f32_e32 v189, v189
	v_exp_f32_e32 v191, v191
	v_add_f32_e32 v175, 1.0, v175
	v_add_f32_e32 v177, 1.0, v177
	v_add_f32_e32 v179, 1.0, v179
	v_add_f32_e32 v181, 1.0, v181
	v_add_f32_e32 v183, 1.0, v183
	v_add_f32_e32 v187, 1.0, v187
	v_add_f32_e32 v189, 1.0, v189
	v_add_f32_e32 v191, 1.0, v191
	v_rcp_f32_e32 v175, v175
	v_rcp_f32_e32 v177, v177
	v_rcp_f32_e32 v179, v179
	v_rcp_f32_e32 v181, v181
	v_rcp_f32_e32 v183, v183
	v_rcp_f32_e32 v187, v187
	v_rcp_f32_e32 v189, v189
	v_rcp_f32_e32 v191, v191
	v_cvt_f32_i32_e32 v223, v107
	v_cvt_f32_i32_e32 v222, v106
	v_cvt_f32_i32_e32 v225, v109
	v_cvt_f32_i32_e32 v224, v108
	v_cvt_pk_bf16_f32 v218, v175, v177
	v_cvt_pk_bf16_f32 v219, v179, v181
	v_cvt_pk_bf16_f32 v220, v183, v187
	v_cvt_pk_bf16_f32 v221, v189, v191
	global_store_dwordx4 v[216:217], v[218:221], off offset:256 nt
	v_lshlrev_b64 v[216:217], 12, v[210:211]
	v_lshl_add_u64 v[216:217], v[214:215], 0, v[216:217]
	v_pk_mul_f32 v[218:219], v[182:183], v[16:17] op_sel_hi:[0,1]
	v_pk_mul_f32 v[220:221], v[182:183], v[14:15] op_sel_hi:[0,1]
	v_pk_fma_f32 v[218:219], v[218:219], v[224:225], v[160:161]
	v_pk_fma_f32 v[220:221], v[220:221], v[222:223], v[158:159]
	v_cvt_f32_i32_e32 v223, v99
	v_cvt_f32_i32_e32 v222, v98
	v_cvt_f32_i32_e32 v225, v101
	v_cvt_f32_i32_e32 v224, v100
	v_mul_f32_e32 v175, 0xbfb8aa3b, v220
	v_mul_f32_e32 v177, 0xbfb8aa3b, v221
	v_mul_f32_e32 v179, 0xbfb8aa3b, v218
	v_mul_f32_e32 v181, 0xbfb8aa3b, v219
	v_pk_mul_f32 v[218:219], v[182:183], v[12:13] op_sel_hi:[0,1]
	v_pk_mul_f32 v[220:221], v[182:183], v[10:11] op_sel_hi:[0,1]
	v_pk_fma_f32 v[218:219], v[218:219], v[224:225], v[156:157]
	v_pk_fma_f32 v[220:221], v[220:221], v[222:223], v[154:155]
	v_mul_f32_e32 v189, 0xbfb8aa3b, v218
	v_mul_f32_e32 v183, 0xbfb8aa3b, v220
	v_mul_f32_e32 v187, 0xbfb8aa3b, v221
	v_mul_f32_e32 v191, 0xbfb8aa3b, v219
	v_exp_f32_e32 v175, v175
	v_exp_f32_e32 v177, v177
	v_exp_f32_e32 v179, v179
	v_exp_f32_e32 v181, v181
	v_exp_f32_e32 v183, v183
	v_exp_f32_e32 v187, v187
	v_exp_f32_e32 v189, v189
	v_exp_f32_e32 v191, v191
	v_add_f32_e32 v175, 1.0, v175
	v_add_f32_e32 v177, 1.0, v177
	v_add_f32_e32 v179, 1.0, v179
	v_add_f32_e32 v181, 1.0, v181
	v_add_f32_e32 v183, 1.0, v183
	v_add_f32_e32 v187, 1.0, v187
	v_add_f32_e32 v189, 1.0, v189
	v_add_f32_e32 v191, 1.0, v191
	v_rcp_f32_e32 v175, v175
	v_rcp_f32_e32 v177, v177
	v_rcp_f32_e32 v179, v179
	v_rcp_f32_e32 v181, v181
	v_rcp_f32_e32 v183, v183
	v_rcp_f32_e32 v187, v187
	v_rcp_f32_e32 v189, v189
	v_rcp_f32_e32 v191, v191
	v_cvt_f32_i32_e32 v223, v87
	v_cvt_f32_i32_e32 v222, v86
	v_cvt_f32_i32_e32 v225, v89
	v_cvt_f32_i32_e32 v224, v88
	v_cvt_pk_bf16_f32 v218, v175, v177
	v_cvt_pk_bf16_f32 v219, v179, v181
	v_cvt_pk_bf16_f32 v220, v183, v187
	v_cvt_pk_bf16_f32 v221, v189, v191
	global_store_dwordx4 v[216:217], v[218:221], off nt
	s_nop 1
	v_pk_mul_f32 v[218:219], v[182:183], v[8:9] op_sel_hi:[0,1]
	v_pk_mul_f32 v[220:221], v[182:183], v[6:7] op_sel_hi:[0,1]
	v_pk_fma_f32 v[218:219], v[218:219], v[224:225], v[152:153]
	v_pk_fma_f32 v[220:221], v[220:221], v[222:223], v[150:151]
	v_cvt_f32_i32_e32 v223, v83
	v_cvt_f32_i32_e32 v222, v82
	v_cvt_f32_i32_e32 v225, v85
	v_cvt_f32_i32_e32 v224, v84
	v_mul_f32_e32 v175, 0xbfb8aa3b, v220
	v_mul_f32_e32 v177, 0xbfb8aa3b, v221
	v_mul_f32_e32 v179, 0xbfb8aa3b, v218
	v_mul_f32_e32 v181, 0xbfb8aa3b, v219
	v_pk_mul_f32 v[218:219], v[182:183], v[4:5] op_sel_hi:[0,1]
	v_pk_mul_f32 v[220:221], v[182:183], v[2:3] op_sel_hi:[0,1]
	v_pk_fma_f32 v[218:219], v[218:219], v[224:225], v[148:149]
	v_pk_fma_f32 v[220:221], v[220:221], v[222:223], v[146:147]
	v_mul_f32_e32 v189, 0xbfb8aa3b, v218
	v_mul_f32_e32 v183, 0xbfb8aa3b, v220
	v_mul_f32_e32 v187, 0xbfb8aa3b, v221
	v_mul_f32_e32 v191, 0xbfb8aa3b, v219
	v_exp_f32_e32 v175, v175
	v_exp_f32_e32 v177, v177
	v_exp_f32_e32 v179, v179
	v_exp_f32_e32 v181, v181
	v_exp_f32_e32 v183, v183
	v_exp_f32_e32 v187, v187
	v_exp_f32_e32 v189, v189
	v_exp_f32_e32 v191, v191
	v_add_f32_e32 v175, 1.0, v175
	v_add_f32_e32 v177, 1.0, v177
	v_add_f32_e32 v179, 1.0, v179
	v_add_f32_e32 v181, 1.0, v181
	v_add_f32_e32 v183, 1.0, v183
	v_add_f32_e32 v187, 1.0, v187
	v_add_f32_e32 v189, 1.0, v189
	v_add_f32_e32 v191, 1.0, v191
	v_rcp_f32_e32 v175, v175
	v_rcp_f32_e32 v177, v177
	v_rcp_f32_e32 v179, v179
	v_rcp_f32_e32 v181, v181
	v_rcp_f32_e32 v183, v183
	v_rcp_f32_e32 v187, v187
	v_rcp_f32_e32 v189, v189
	v_rcp_f32_e32 v191, v191
	v_cvt_f32_i32_e32 v225, v81
	v_cvt_f32_i32_e32 v224, v80
	v_cvt_pk_bf16_f32 v218, v175, v177
	v_cvt_pk_bf16_f32 v219, v179, v181
	v_cvt_pk_bf16_f32 v220, v183, v187
	v_cvt_pk_bf16_f32 v221, v189, v191
	global_store_dwordx4 v[216:217], v[218:221], off offset:256 nt
	v_cvt_f32_i32_e32 v223, v79
	v_cvt_f32_i32_e32 v222, v78
	v_pk_mul_f32 v[218:219], v[180:181], v[16:17] op_sel_hi:[0,1]
	v_pk_fma_f32 v[218:219], v[218:219], v[224:225], v[160:161]
	v_pk_mul_f32 v[220:221], v[180:181], v[14:15] op_sel_hi:[0,1]
	v_mul_f32_e32 v181, 0xbfb8aa3b, v219
	v_exp_f32_e32 v181, v181
	v_pk_fma_f32 v[220:221], v[220:221], v[222:223], v[158:159]
	v_cvt_f32_i32_e32 v223, v75
	v_cvt_f32_i32_e32 v222, v74
	v_add_f32_e32 v181, 1.0, v181
	v_rcp_f32_e32 v181, v181
	v_cvt_f32_i32_e32 v225, v77
	v_cvt_f32_i32_e32 v224, v76
	v_mul_f32_e32 v175, 0xbfb8aa3b, v220
	v_mul_f32_e32 v177, 0xbfb8aa3b, v221
	v_mul_f32_e32 v179, 0xbfb8aa3b, v218
	v_pk_mul_f32 v[218:219], v[180:181], v[12:13] op_sel_hi:[0,1]
	v_pk_mul_f32 v[220:221], v[180:181], v[10:11] op_sel_hi:[0,1]
	v_pk_fma_f32 v[218:219], v[218:219], v[224:225], v[156:157]
	v_pk_fma_f32 v[220:221], v[220:221], v[222:223], v[154:155]
	v_mul_f32_e32 v189, 0xbfb8aa3b, v218
	v_mul_f32_e32 v183, 0xbfb8aa3b, v220
	v_mul_f32_e32 v187, 0xbfb8aa3b, v221
	v_mul_f32_e32 v191, 0xbfb8aa3b, v219
	v_exp_f32_e32 v175, v175
	v_exp_f32_e32 v177, v177
	v_exp_f32_e32 v179, v179
	v_exp_f32_e32 v183, v183
	v_exp_f32_e32 v187, v187
	v_exp_f32_e32 v189, v189
	v_exp_f32_e32 v191, v191
	v_add_f32_e32 v175, 1.0, v175
	v_add_f32_e32 v177, 1.0, v177
	v_add_f32_e32 v179, 1.0, v179
	v_add_f32_e32 v183, 1.0, v183
	v_add_f32_e32 v187, 1.0, v187
	v_add_f32_e32 v189, 1.0, v189
	v_add_f32_e32 v191, 1.0, v191
	v_rcp_f32_e32 v175, v175
	v_rcp_f32_e32 v177, v177
	v_rcp_f32_e32 v179, v179
	v_rcp_f32_e32 v183, v183
	v_rcp_f32_e32 v187, v187
	v_rcp_f32_e32 v189, v189
	v_rcp_f32_e32 v191, v191
	v_cvt_f32_i32_e32 v225, v65
	v_cvt_f32_i32_e32 v224, v64
	v_lshlrev_b64 v[216:217], 12, v[184:185]
	v_lshl_add_u64 v[216:217], v[214:215], 0, v[216:217]
	v_cvt_pk_bf16_f32 v218, v175, v177
	v_cvt_pk_bf16_f32 v219, v179, v181
	v_cvt_pk_bf16_f32 v220, v183, v187
	v_cvt_pk_bf16_f32 v221, v189, v191
	global_store_dwordx4 v[216:217], v[218:221], off nt
	v_cvt_f32_i32_e32 v223, v63
	v_cvt_f32_i32_e32 v222, v62
	v_pk_mul_f32 v[218:219], v[180:181], v[8:9] op_sel_hi:[0,1]
	v_pk_fma_f32 v[218:219], v[218:219], v[224:225], v[152:153]
	v_pk_mul_f32 v[220:221], v[180:181], v[6:7] op_sel_hi:[0,1]
	v_mul_f32_e32 v181, 0xbfb8aa3b, v219
	v_exp_f32_e32 v181, v181
	v_pk_fma_f32 v[220:221], v[220:221], v[222:223], v[150:151]
	v_cvt_f32_i32_e32 v223, v59
	v_cvt_f32_i32_e32 v222, v58
	v_add_f32_e32 v181, 1.0, v181
	v_rcp_f32_e32 v181, v181
	v_cvt_f32_i32_e32 v225, v61
	v_cvt_f32_i32_e32 v224, v60
	v_mul_f32_e32 v175, 0xbfb8aa3b, v220
	v_mul_f32_e32 v177, 0xbfb8aa3b, v221
	v_mul_f32_e32 v179, 0xbfb8aa3b, v218
	v_pk_mul_f32 v[218:219], v[180:181], v[4:5] op_sel_hi:[0,1]
	v_pk_mul_f32 v[220:221], v[180:181], v[2:3] op_sel_hi:[0,1]
	v_pk_fma_f32 v[218:219], v[218:219], v[224:225], v[148:149]
	v_pk_fma_f32 v[220:221], v[220:221], v[222:223], v[146:147]
	v_mul_f32_e32 v189, 0xbfb8aa3b, v218
	v_mul_f32_e32 v183, 0xbfb8aa3b, v220
	v_mul_f32_e32 v187, 0xbfb8aa3b, v221
	v_mul_f32_e32 v191, 0xbfb8aa3b, v219
	v_exp_f32_e32 v175, v175
	v_exp_f32_e32 v177, v177
	v_exp_f32_e32 v179, v179
	v_exp_f32_e32 v183, v183
	v_exp_f32_e32 v187, v187
	v_exp_f32_e32 v189, v189
	v_exp_f32_e32 v191, v191
	v_add_f32_e32 v175, 1.0, v175
	v_add_f32_e32 v177, 1.0, v177
	v_add_f32_e32 v179, 1.0, v179
	v_add_f32_e32 v183, 1.0, v183
	v_add_f32_e32 v187, 1.0, v187
	v_add_f32_e32 v189, 1.0, v189
	v_add_f32_e32 v191, 1.0, v191
	v_rcp_f32_e32 v175, v175
	v_rcp_f32_e32 v177, v177
	v_rcp_f32_e32 v179, v179
	v_rcp_f32_e32 v183, v183
	v_rcp_f32_e32 v187, v187
	v_rcp_f32_e32 v189, v189
	v_rcp_f32_e32 v191, v191
	v_cvt_f32_i32_e32 v225, v73
	v_cvt_f32_i32_e32 v224, v72
	v_cvt_pk_bf16_f32 v218, v175, v177
	v_cvt_pk_bf16_f32 v219, v179, v181
	v_cvt_pk_bf16_f32 v220, v183, v187
	v_cvt_pk_bf16_f32 v221, v189, v191
	global_store_dwordx4 v[216:217], v[218:221], off offset:256 nt
	v_cvt_f32_i32_e32 v223, v71
	v_cvt_f32_i32_e32 v222, v70
	v_pk_mul_f32 v[218:219], v[178:179], v[16:17] op_sel_hi:[0,1]
	v_pk_fma_f32 v[218:219], v[218:219], v[224:225], v[160:161]
	v_pk_mul_f32 v[220:221], v[178:179], v[14:15] op_sel_hi:[0,1]
	v_mul_f32_e32 v179, 0xbfb8aa3b, v218
	v_exp_f32_e32 v179, v179
	v_pk_fma_f32 v[220:221], v[220:221], v[222:223], v[158:159]
	v_cvt_f32_i32_e32 v223, v67
	v_cvt_f32_i32_e32 v222, v66
	v_add_f32_e32 v179, 1.0, v179
	v_rcp_f32_e32 v179, v179
	v_cvt_f32_i32_e32 v225, v69
	v_cvt_f32_i32_e32 v224, v68
	v_mul_f32_e32 v175, 0xbfb8aa3b, v220
	v_mul_f32_e32 v177, 0xbfb8aa3b, v221
	v_mul_f32_e32 v181, 0xbfb8aa3b, v219
	v_pk_mul_f32 v[218:219], v[178:179], v[12:13] op_sel_hi:[0,1]
	v_pk_mul_f32 v[220:221], v[178:179], v[10:11] op_sel_hi:[0,1]
	v_pk_fma_f32 v[218:219], v[218:219], v[224:225], v[156:157]
	v_pk_fma_f32 v[220:221], v[220:221], v[222:223], v[154:155]
	v_mul_f32_e32 v189, 0xbfb8aa3b, v218
	v_mul_f32_e32 v183, 0xbfb8aa3b, v220
	v_mul_f32_e32 v187, 0xbfb8aa3b, v221
	v_mul_f32_e32 v191, 0xbfb8aa3b, v219
	v_exp_f32_e32 v175, v175
	v_exp_f32_e32 v177, v177
	v_exp_f32_e32 v181, v181
	v_exp_f32_e32 v183, v183
	v_exp_f32_e32 v187, v187
	v_exp_f32_e32 v189, v189
	v_exp_f32_e32 v191, v191
	v_add_f32_e32 v175, 1.0, v175
	v_add_f32_e32 v177, 1.0, v177
	v_add_f32_e32 v181, 1.0, v181
	v_add_f32_e32 v183, 1.0, v183
	v_add_f32_e32 v187, 1.0, v187
	v_add_f32_e32 v189, 1.0, v189
	v_add_f32_e32 v191, 1.0, v191
	v_rcp_f32_e32 v175, v175
	v_rcp_f32_e32 v177, v177
	v_rcp_f32_e32 v181, v181
	v_rcp_f32_e32 v183, v183
	v_rcp_f32_e32 v187, v187
	v_rcp_f32_e32 v189, v189
	v_rcp_f32_e32 v191, v191
	v_cvt_f32_i32_e32 v225, v49
	v_cvt_f32_i32_e32 v224, v48
	v_lshlrev_b64 v[216:217], 12, v[212:213]
	v_lshl_add_u64 v[216:217], v[214:215], 0, v[216:217]
	v_cvt_pk_bf16_f32 v218, v175, v177
	v_cvt_pk_bf16_f32 v219, v179, v181
	v_cvt_pk_bf16_f32 v220, v183, v187
	v_cvt_pk_bf16_f32 v221, v189, v191
	global_store_dwordx4 v[216:217], v[218:221], off nt
	v_cvt_f32_i32_e32 v223, v47
	v_cvt_f32_i32_e32 v222, v46
	v_pk_mul_f32 v[218:219], v[178:179], v[8:9] op_sel_hi:[0,1]
	v_pk_fma_f32 v[218:219], v[218:219], v[224:225], v[152:153]
	v_pk_mul_f32 v[220:221], v[178:179], v[6:7] op_sel_hi:[0,1]
	v_mul_f32_e32 v179, 0xbfb8aa3b, v218
	v_exp_f32_e32 v179, v179
	v_pk_fma_f32 v[220:221], v[220:221], v[222:223], v[150:151]
	v_cvt_f32_i32_e32 v223, v43
	v_cvt_f32_i32_e32 v222, v42
	v_add_f32_e32 v179, 1.0, v179
	v_rcp_f32_e32 v179, v179
	v_cvt_f32_i32_e32 v225, v45
	v_cvt_f32_i32_e32 v224, v44
	v_mul_f32_e32 v175, 0xbfb8aa3b, v220
	v_mul_f32_e32 v177, 0xbfb8aa3b, v221
	v_mul_f32_e32 v181, 0xbfb8aa3b, v219
	v_pk_mul_f32 v[218:219], v[178:179], v[4:5] op_sel_hi:[0,1]
	v_pk_mul_f32 v[220:221], v[178:179], v[2:3] op_sel_hi:[0,1]
	v_pk_fma_f32 v[218:219], v[218:219], v[224:225], v[148:149]
	v_pk_fma_f32 v[220:221], v[220:221], v[222:223], v[146:147]
	v_mul_f32_e32 v189, 0xbfb8aa3b, v218
	v_mul_f32_e32 v183, 0xbfb8aa3b, v220
	v_mul_f32_e32 v187, 0xbfb8aa3b, v221
	v_mul_f32_e32 v191, 0xbfb8aa3b, v219
	v_exp_f32_e32 v175, v175
	v_exp_f32_e32 v177, v177
	v_exp_f32_e32 v181, v181
	v_exp_f32_e32 v183, v183
	v_exp_f32_e32 v187, v187
	v_exp_f32_e32 v189, v189
	v_exp_f32_e32 v191, v191
	v_add_f32_e32 v175, 1.0, v175
	v_add_f32_e32 v177, 1.0, v177
	v_add_f32_e32 v181, 1.0, v181
	v_add_f32_e32 v183, 1.0, v183
	v_add_f32_e32 v187, 1.0, v187
	v_add_f32_e32 v189, 1.0, v189
	v_add_f32_e32 v191, 1.0, v191
	v_rcp_f32_e32 v175, v175
	v_rcp_f32_e32 v177, v177
	v_rcp_f32_e32 v181, v181
	v_rcp_f32_e32 v183, v183
	v_rcp_f32_e32 v187, v187
	v_rcp_f32_e32 v189, v189
	v_rcp_f32_e32 v191, v191
	v_cvt_f32_i32_e32 v223, v55
	v_cvt_f32_i32_e32 v222, v54
	v_cvt_pk_bf16_f32 v218, v175, v177
	v_cvt_pk_bf16_f32 v219, v179, v181
	v_cvt_pk_bf16_f32 v220, v183, v187
	v_cvt_pk_bf16_f32 v221, v189, v191
	global_store_dwordx4 v[216:217], v[218:221], off offset:256 nt
	v_cvt_f32_i32_e32 v225, v57
	v_cvt_f32_i32_e32 v224, v56
	v_pk_mul_f32 v[220:221], v[176:177], v[14:15] op_sel_hi:[0,1]
	v_pk_fma_f32 v[220:221], v[220:221], v[222:223], v[158:159]
	v_pk_mul_f32 v[218:219], v[176:177], v[16:17] op_sel_hi:[0,1]
	v_mul_f32_e32 v177, 0xbfb8aa3b, v221
	v_exp_f32_e32 v177, v177
	v_pk_fma_f32 v[218:219], v[218:219], v[224:225], v[160:161]
	v_cvt_f32_i32_e32 v223, v51
	v_cvt_f32_i32_e32 v222, v50
	v_add_f32_e32 v177, 1.0, v177
	v_rcp_f32_e32 v177, v177
	v_cvt_f32_i32_e32 v225, v53
	v_cvt_f32_i32_e32 v224, v52
	v_mul_f32_e32 v175, 0xbfb8aa3b, v220
	v_mul_f32_e32 v179, 0xbfb8aa3b, v218
	v_mul_f32_e32 v181, 0xbfb8aa3b, v219
	v_pk_mul_f32 v[218:219], v[176:177], v[12:13] op_sel_hi:[0,1]
	v_pk_mul_f32 v[220:221], v[176:177], v[10:11] op_sel_hi:[0,1]
	v_pk_fma_f32 v[218:219], v[218:219], v[224:225], v[156:157]
	v_pk_fma_f32 v[220:221], v[220:221], v[222:223], v[154:155]
	v_mul_f32_e32 v189, 0xbfb8aa3b, v218
	v_mul_f32_e32 v183, 0xbfb8aa3b, v220
	v_mul_f32_e32 v187, 0xbfb8aa3b, v221
	v_mul_f32_e32 v191, 0xbfb8aa3b, v219
	v_exp_f32_e32 v175, v175
	v_exp_f32_e32 v179, v179
	v_exp_f32_e32 v181, v181
	v_exp_f32_e32 v183, v183
	v_exp_f32_e32 v187, v187
	v_exp_f32_e32 v189, v189
	v_exp_f32_e32 v191, v191
	v_add_f32_e32 v175, 1.0, v175
	v_add_f32_e32 v179, 1.0, v179
	v_add_f32_e32 v181, 1.0, v181
	v_add_f32_e32 v183, 1.0, v183
	v_add_f32_e32 v187, 1.0, v187
	v_add_f32_e32 v189, 1.0, v189
	v_add_f32_e32 v191, 1.0, v191
	v_rcp_f32_e32 v175, v175
	v_rcp_f32_e32 v179, v179
	v_rcp_f32_e32 v181, v181
	v_rcp_f32_e32 v183, v183
	v_rcp_f32_e32 v187, v187
	v_rcp_f32_e32 v189, v189
	v_rcp_f32_e32 v191, v191
	v_cvt_f32_i32_e32 v223, v31
	v_cvt_f32_i32_e32 v222, v30
	v_lshlrev_b64 v[216:217], 12, v[204:205]
	v_lshl_add_u64 v[216:217], v[214:215], 0, v[216:217]
	v_cvt_pk_bf16_f32 v218, v175, v177
	v_cvt_pk_bf16_f32 v219, v179, v181
	v_cvt_pk_bf16_f32 v220, v183, v187
	v_cvt_pk_bf16_f32 v221, v189, v191
	global_store_dwordx4 v[216:217], v[218:221], off nt
	v_cvt_f32_i32_e32 v225, v33
	v_cvt_f32_i32_e32 v224, v32
	v_pk_mul_f32 v[220:221], v[176:177], v[6:7] op_sel_hi:[0,1]
	v_pk_fma_f32 v[220:221], v[220:221], v[222:223], v[150:151]
	v_pk_mul_f32 v[218:219], v[176:177], v[8:9] op_sel_hi:[0,1]
	v_mul_f32_e32 v177, 0xbfb8aa3b, v221
	v_exp_f32_e32 v177, v177
	v_pk_fma_f32 v[218:219], v[218:219], v[224:225], v[152:153]
	v_cvt_f32_i32_e32 v223, v27
	v_cvt_f32_i32_e32 v222, v26
	v_add_f32_e32 v177, 1.0, v177
	v_rcp_f32_e32 v177, v177
	v_cvt_f32_i32_e32 v225, v29
	v_cvt_f32_i32_e32 v224, v28
	v_mul_f32_e32 v175, 0xbfb8aa3b, v220
	v_mul_f32_e32 v179, 0xbfb8aa3b, v218
	v_mul_f32_e32 v181, 0xbfb8aa3b, v219
	v_pk_mul_f32 v[218:219], v[176:177], v[4:5] op_sel_hi:[0,1]
	v_pk_mul_f32 v[220:221], v[176:177], v[2:3] op_sel_hi:[0,1]
	v_pk_fma_f32 v[218:219], v[218:219], v[224:225], v[148:149]
	v_pk_fma_f32 v[220:221], v[220:221], v[222:223], v[146:147]
	v_mul_f32_e32 v189, 0xbfb8aa3b, v218
	v_mul_f32_e32 v183, 0xbfb8aa3b, v220
	v_mul_f32_e32 v187, 0xbfb8aa3b, v221
	v_mul_f32_e32 v191, 0xbfb8aa3b, v219
	v_exp_f32_e32 v175, v175
	v_exp_f32_e32 v179, v179
	v_exp_f32_e32 v181, v181
	v_exp_f32_e32 v183, v183
	v_exp_f32_e32 v187, v187
	v_exp_f32_e32 v189, v189
	v_exp_f32_e32 v191, v191
	v_add_f32_e32 v175, 1.0, v175
	v_add_f32_e32 v179, 1.0, v179
	v_add_f32_e32 v181, 1.0, v181
	v_add_f32_e32 v183, 1.0, v183
	v_add_f32_e32 v187, 1.0, v187
	v_add_f32_e32 v189, 1.0, v189
	v_add_f32_e32 v191, 1.0, v191
	v_rcp_f32_e32 v175, v175
	v_rcp_f32_e32 v179, v179
	v_rcp_f32_e32 v181, v181
	v_rcp_f32_e32 v183, v183
	v_rcp_f32_e32 v187, v187
	v_rcp_f32_e32 v189, v189
	v_rcp_f32_e32 v191, v191
	v_cvt_pk_bf16_f32 v218, v175, v177
	v_cvt_pk_bf16_f32 v219, v179, v181
	v_cvt_pk_bf16_f32 v220, v183, v187
	v_cvt_pk_bf16_f32 v221, v189, v191
	global_store_dwordx4 v[216:217], v[218:221], off offset:256 nt
	v_lshlrev_b64 v[216:217], 12, v[202:203]
	v_lshl_add_u64 v[214:215], v[214:215], 0, v[216:217]
	v_cvt_f32_i32_e32 v221, v39
	v_cvt_f32_i32_e32 v220, v38
	v_pk_mul_f32 v[218:219], v[174:175], v[14:15] op_sel_hi:[0,1]
	v_pk_mul_f32 v[216:217], v[174:175], v[16:17] op_sel_hi:[0,1]
	v_cvt_f32_i32_e32 v223, v41
	v_pk_fma_f32 v[158:159], v[218:219], v[220:221], v[158:159]
	v_cvt_f32_i32_e32 v222, v40
	v_mul_f32_e32 v158, 0xbfb8aa3b, v158
	v_exp_f32_e32 v158, v158
	v_cvt_f32_i32_e32 v219, v37
	v_pk_fma_f32 v[160:161], v[216:217], v[222:223], v[160:161]
	v_cvt_f32_i32_e32 v217, v35
	v_add_f32_e32 v158, 1.0, v158
	v_rcp_f32_e32 v175, v158
	v_mul_f32_e32 v158, 0xbfb8aa3b, v159
	v_exp_f32_e32 v158, v158
	v_cvt_f32_i32_e32 v216, v34
	v_cvt_f32_i32_e32 v218, v36
	v_add_f32_e32 v158, 1.0, v158
	v_rcp_f32_e32 v177, v158
	v_mul_f32_e32 v158, 0xbfb8aa3b, v160
	v_exp_f32_e32 v158, v158
	s_nop 0
	v_add_f32_e32 v158, 1.0, v158
	v_rcp_f32_e32 v179, v158
	v_mul_f32_e32 v158, 0xbfb8aa3b, v161
	v_pk_mul_f32 v[160:161], v[174:175], v[10:11] op_sel_hi:[0,1]
	v_pk_fma_f32 v[154:155], v[160:161], v[216:217], v[154:155]
	v_exp_f32_e32 v158, v158
	v_mul_f32_e32 v154, 0xbfb8aa3b, v154
	v_exp_f32_e32 v154, v154
	v_cvt_f32_i32_e32 v161, v25
	v_add_f32_e32 v158, 1.0, v158
	v_rcp_f32_e32 v181, v158
	v_pk_mul_f32 v[158:159], v[174:175], v[12:13] op_sel_hi:[0,1]
	v_add_f32_e32 v154, 1.0, v154
	v_pk_fma_f32 v[156:157], v[158:159], v[218:219], v[156:157]
	v_rcp_f32_e32 v158, v154
	v_mul_f32_e32 v154, 0xbfb8aa3b, v155
	v_exp_f32_e32 v154, v154
	v_cvt_pk_bf16_f32 v155, v179, v181
	v_add_f32_e32 v154, 1.0, v154
	v_rcp_f32_e32 v159, v154
	v_mul_f32_e32 v154, 0xbfb8aa3b, v156
	v_exp_f32_e32 v154, v154
	v_cvt_pk_bf16_f32 v156, v158, v159
	v_cvt_f32_i32_e32 v159, v23
	v_add_f32_e32 v154, 1.0, v154
	v_rcp_f32_e32 v160, v154
	v_mul_f32_e32 v154, 0xbfb8aa3b, v157
	v_exp_f32_e32 v154, v154
	v_cvt_f32_i32_e32 v158, v22
	v_add_f32_e32 v154, 1.0, v154
	v_rcp_f32_e32 v157, v154
	v_cvt_pk_bf16_f32 v154, v175, v177
	v_cvt_pk_bf16_f32 v157, v160, v157
	global_store_dwordx4 v[214:215], v[154:157], off nt
	v_cvt_f32_i32_e32 v160, v24
	s_nop 0
	v_pk_mul_f32 v[156:157], v[174:175], v[6:7] op_sel_hi:[0,1]
	v_pk_fma_f32 v[150:151], v[156:157], v[158:159], v[150:151]
	v_pk_mul_f32 v[154:155], v[174:175], v[8:9] op_sel_hi:[0,1]
	v_mul_f32_e32 v150, 0xbfb8aa3b, v150
	v_exp_f32_e32 v150, v150
	v_pk_fma_f32 v[152:153], v[154:155], v[160:161], v[152:153]
	v_cvt_f32_i32_e32 v155, v19
	v_cvt_f32_i32_e32 v154, v18
	v_add_f32_e32 v150, 1.0, v150
	v_rcp_f32_e32 v158, v150
	v_mul_f32_e32 v150, 0xbfb8aa3b, v151
	v_exp_f32_e32 v150, v150
	v_cvt_f32_i32_e32 v157, v21
	v_cvt_f32_i32_e32 v156, v20
	v_add_f32_e32 v150, 1.0, v150
	v_rcp_f32_e32 v159, v150
	v_mul_f32_e32 v150, 0xbfb8aa3b, v152
	v_exp_f32_e32 v150, v150
	s_nop 0
	v_add_f32_e32 v150, 1.0, v150
	v_rcp_f32_e32 v160, v150
	v_mul_f32_e32 v150, 0xbfb8aa3b, v153
	v_pk_mul_f32 v[152:153], v[174:175], v[2:3] op_sel_hi:[0,1]
	v_pk_fma_f32 v[146:147], v[152:153], v[154:155], v[146:147]
	v_exp_f32_e32 v150, v150
	v_mul_f32_e32 v146, 0xbfb8aa3b, v146
	v_exp_f32_e32 v146, v146
	v_add_f32_e32 v150, 1.0, v150
	v_rcp_f32_e32 v161, v150
	v_pk_mul_f32 v[150:151], v[174:175], v[4:5] op_sel_hi:[0,1]
	v_add_f32_e32 v146, 1.0, v146
	v_pk_fma_f32 v[148:149], v[150:151], v[156:157], v[148:149]
	v_rcp_f32_e32 v150, v146
	v_mul_f32_e32 v146, 0xbfb8aa3b, v147
	v_exp_f32_e32 v146, v146
	v_cvt_pk_bf16_f32 v147, v160, v161
	v_add_f32_e32 v146, 1.0, v146
	v_rcp_f32_e32 v151, v146
	v_mul_f32_e32 v146, 0xbfb8aa3b, v148
	v_exp_f32_e32 v146, v146
	v_cvt_pk_bf16_f32 v148, v150, v151
	v_add_f32_e32 v146, 1.0, v146
	v_rcp_f32_e32 v152, v146
	v_mul_f32_e32 v146, 0xbfb8aa3b, v149
	v_exp_f32_e32 v146, v146
	s_nop 0
	v_add_f32_e32 v146, 1.0, v146
	v_rcp_f32_e32 v149, v146
	v_cvt_pk_bf16_f32 v146, v158, v159
	v_cvt_pk_bf16_f32 v149, v152, v149
	global_store_dwordx4 v[214:215], v[146:149], off offset:256 nt

.LBB0_347:
	s_and_b64 vcc, exec, s[34:35]
	s_cbranch_vccz .LBB0_352
	s_cmp_gt_i32 s49, 1
	s_mov_b64 s[28:29], -1
	s_cbranch_scc0 .LBB0_350
	v_cvt_f32_i32_e32 v151, v143
	v_cvt_f32_i32_e32 v150, v142
	v_pk_mul_f32 v[152:153], v[190:191], v[14:15] op_sel_hi:[0,1]
	v_pk_mul_f32 v[154:155], v[190:191], v[16:17] op_sel_hi:[0,1]
	v_pk_mul_f32 v[156:157], v[190:191], v[10:11] op_sel_hi:[0,1]
	v_pk_mul_f32 v[150:151], v[152:153], v[150:151]
	v_pk_mul_f32 v[158:159], v[190:191], v[12:13] op_sel_hi:[0,1]
	v_mul_f32_e32 v152, 0xbfb8aa3b, v150
	v_mul_f32_e32 v153, 0xbfb8aa3b, v151
	v_exp_f32_e32 v152, v152
	v_exp_f32_e32 v153, v153
	v_ashrrev_i32_e32 v201, 31, v200
	v_lshl_add_u64 v[146:147], v[200:201], 1, s[0:1]
	v_add_f32_e32 v152, 1.0, v152
	v_add_f32_e32 v153, 1.0, v153
	v_rcp_f32_e32 v152, v152
	v_rcp_f32_e32 v153, v153
	v_lshlrev_b64 v[148:149], 12, v[192:193]
	v_lshl_add_u64 v[148:149], v[146:147], 0, v[148:149]
	s_mov_b64 s[28:29], 0
	v_pk_mul_f32 v[150:151], v[150:151], v[152:153]
	v_cvt_f32_i32_e32 v153, v145
	v_cvt_f32_i32_e32 v152, v144
	v_cvt_pk_bf16_f32 v150, v150, v151
	v_pk_mul_f32 v[152:153], v[154:155], v[152:153]
	s_nop 0
	v_mul_f32_e32 v154, 0xbfb8aa3b, v152
	v_mul_f32_e32 v155, 0xbfb8aa3b, v153
	v_exp_f32_e32 v154, v154
	v_exp_f32_e32 v155, v155
	v_add_f32_e32 v154, 1.0, v154
	v_add_f32_e32 v155, 1.0, v155
	v_rcp_f32_e32 v154, v154
	v_rcp_f32_e32 v155, v155
	s_nop 0
	v_pk_mul_f32 v[152:153], v[152:153], v[154:155]
	v_cvt_f32_i32_e32 v155, v139
	v_cvt_f32_i32_e32 v154, v138
	v_cvt_pk_bf16_f32 v151, v152, v153
	v_pk_mul_f32 v[154:155], v[156:157], v[154:155]
	s_nop 0
	v_mul_f32_e32 v156, 0xbfb8aa3b, v154
	v_mul_f32_e32 v157, 0xbfb8aa3b, v155
	v_exp_f32_e32 v156, v156
	v_exp_f32_e32 v157, v157
	v_add_f32_e32 v156, 1.0, v156
	v_add_f32_e32 v157, 1.0, v157
	v_rcp_f32_e32 v156, v156
	v_rcp_f32_e32 v157, v157
	s_nop 0
	v_pk_mul_f32 v[154:155], v[154:155], v[156:157]
	v_cvt_f32_i32_e32 v157, v141
	v_cvt_f32_i32_e32 v156, v140
	v_cvt_pk_bf16_f32 v152, v154, v155
	v_pk_mul_f32 v[154:155], v[190:191], v[8:9] op_sel_hi:[0,1]
	v_pk_mul_f32 v[156:157], v[158:159], v[156:157]
	s_nop 0
	v_mul_f32_e32 v158, 0xbfb8aa3b, v156
	v_mul_f32_e32 v159, 0xbfb8aa3b, v157
	v_exp_f32_e32 v158, v158
	v_exp_f32_e32 v159, v159
	v_add_f32_e32 v158, 1.0, v158
	v_add_f32_e32 v159, 1.0, v159
	v_rcp_f32_e32 v158, v158
	v_rcp_f32_e32 v159, v159
	s_nop 0
	v_pk_mul_f32 v[156:157], v[156:157], v[158:159]
	s_nop 0
	v_cvt_pk_bf16_f32 v153, v156, v157
	global_store_dwordx4 v[148:149], v[150:153], off nt
	v_pk_mul_f32 v[156:157], v[190:191], v[2:3] op_sel_hi:[0,1]
	v_pk_mul_f32 v[158:159], v[190:191], v[4:5] op_sel_hi:[0,1]
	v_cvt_f32_i32_e32 v151, v127
	v_cvt_f32_i32_e32 v150, v126
	v_pk_mul_f32 v[152:153], v[190:191], v[6:7] op_sel_hi:[0,1]
	v_pk_mul_f32 v[150:151], v[152:153], v[150:151]
	s_nop 0
	v_mul_f32_e32 v152, 0xbfb8aa3b, v150
	v_mul_f32_e32 v153, 0xbfb8aa3b, v151
	v_exp_f32_e32 v152, v152
	v_exp_f32_e32 v153, v153
	v_add_f32_e32 v152, 1.0, v152
	v_add_f32_e32 v153, 1.0, v153
	v_rcp_f32_e32 v152, v152
	v_rcp_f32_e32 v153, v153
	s_nop 0
	v_pk_mul_f32 v[150:151], v[150:151], v[152:153]
	v_cvt_f32_i32_e32 v153, v129
	v_cvt_f32_i32_e32 v152, v128
	v_cvt_pk_bf16_f32 v150, v150, v151
	v_pk_mul_f32 v[152:153], v[154:155], v[152:153]
	s_nop 0
	v_mul_f32_e32 v154, 0xbfb8aa3b, v152
	v_mul_f32_e32 v155, 0xbfb8aa3b, v153
	v_exp_f32_e32 v154, v154
	v_exp_f32_e32 v155, v155
	v_add_f32_e32 v154, 1.0, v154
	v_add_f32_e32 v155, 1.0, v155
	v_rcp_f32_e32 v154, v154
	v_rcp_f32_e32 v155, v155
	s_nop 0
	v_pk_mul_f32 v[152:153], v[152:153], v[154:155]
	v_cvt_f32_i32_e32 v155, v119
	v_cvt_f32_i32_e32 v154, v118
	v_cvt_pk_bf16_f32 v151, v152, v153
	v_pk_mul_f32 v[154:155], v[156:157], v[154:155]
	s_nop 0
	v_mul_f32_e32 v156, 0xbfb8aa3b, v154
	v_mul_f32_e32 v157, 0xbfb8aa3b, v155
	v_exp_f32_e32 v156, v156
	v_exp_f32_e32 v157, v157
	v_add_f32_e32 v156, 1.0, v156
	v_add_f32_e32 v157, 1.0, v157
	v_rcp_f32_e32 v156, v156
	v_rcp_f32_e32 v157, v157
	s_nop 0
	v_pk_mul_f32 v[154:155], v[154:155], v[156:157]
	v_cvt_f32_i32_e32 v157, v121
	v_cvt_f32_i32_e32 v156, v120
	v_cvt_pk_bf16_f32 v152, v154, v155
	v_pk_mul_f32 v[154:155], v[188:189], v[16:17] op_sel_hi:[0,1]
	v_pk_mul_f32 v[156:157], v[158:159], v[156:157]
	s_nop 0
	v_mul_f32_e32 v158, 0xbfb8aa3b, v156
	v_mul_f32_e32 v159, 0xbfb8aa3b, v157
	v_exp_f32_e32 v158, v158
	v_exp_f32_e32 v159, v159
	v_add_f32_e32 v158, 1.0, v158
	v_add_f32_e32 v159, 1.0, v159
	v_rcp_f32_e32 v158, v158
	v_rcp_f32_e32 v159, v159
	s_nop 0
	v_pk_mul_f32 v[156:157], v[156:157], v[158:159]
	s_nop 0
	v_cvt_pk_bf16_f32 v153, v156, v157
	global_store_dwordx4 v[148:149], v[150:153], off offset:256 nt
	v_pk_mul_f32 v[156:157], v[188:189], v[10:11] op_sel_hi:[0,1]
	v_pk_mul_f32 v[158:159], v[188:189], v[12:13] op_sel_hi:[0,1]
	v_cvt_f32_i32_e32 v151, v135
	v_cvt_f32_i32_e32 v150, v134
	v_pk_mul_f32 v[152:153], v[188:189], v[14:15] op_sel_hi:[0,1]
	v_lshlrev_b64 v[148:149], 12, v[206:207]
	v_lshl_add_u64 v[148:149], v[146:147], 0, v[148:149]
	v_pk_mul_f32 v[150:151], v[152:153], v[150:151]
	s_nop 0
	v_mul_f32_e32 v152, 0xbfb8aa3b, v150
	v_mul_f32_e32 v153, 0xbfb8aa3b, v151
	v_exp_f32_e32 v152, v152
	v_exp_f32_e32 v153, v153
	v_add_f32_e32 v152, 1.0, v152
	v_add_f32_e32 v153, 1.0, v153
	v_rcp_f32_e32 v152, v152
	v_rcp_f32_e32 v153, v153
	s_nop 0
	v_pk_mul_f32 v[150:151], v[150:151], v[152:153]
	v_cvt_f32_i32_e32 v153, v137
	v_cvt_f32_i32_e32 v152, v136
	v_cvt_pk_bf16_f32 v150, v150, v151
	v_pk_mul_f32 v[152:153], v[154:155], v[152:153]
	s_nop 0
	v_mul_f32_e32 v154, 0xbfb8aa3b, v152
	v_mul_f32_e32 v155, 0xbfb8aa3b, v153
	v_exp_f32_e32 v154, v154
	v_exp_f32_e32 v155, v155
	v_add_f32_e32 v154, 1.0, v154
	v_add_f32_e32 v155, 1.0, v155
	v_rcp_f32_e32 v154, v154
	v_rcp_f32_e32 v155, v155
	s_nop 0
	v_pk_mul_f32 v[152:153], v[152:153], v[154:155]
	v_cvt_f32_i32_e32 v155, v131
	v_cvt_f32_i32_e32 v154, v130
	v_cvt_pk_bf16_f32 v151, v152, v153
	v_pk_mul_f32 v[154:155], v[156:157], v[154:155]
	s_nop 0
	v_mul_f32_e32 v156, 0xbfb8aa3b, v154
	v_mul_f32_e32 v157, 0xbfb8aa3b, v155
	v_exp_f32_e32 v156, v156
	v_exp_f32_e32 v157, v157
	v_add_f32_e32 v156, 1.0, v156
	v_add_f32_e32 v157, 1.0, v157
	v_rcp_f32_e32 v156, v156
	v_rcp_f32_e32 v157, v157
	s_nop 0
	v_pk_mul_f32 v[154:155], v[154:155], v[156:157]
	v_cvt_f32_i32_e32 v157, v133
	v_cvt_f32_i32_e32 v156, v132
	v_cvt_pk_bf16_f32 v152, v154, v155
	v_pk_mul_f32 v[154:155], v[188:189], v[8:9] op_sel_hi:[0,1]
	v_pk_mul_f32 v[156:157], v[158:159], v[156:157]
	s_nop 0
	v_mul_f32_e32 v158, 0xbfb8aa3b, v156
	v_mul_f32_e32 v159, 0xbfb8aa3b, v157
	v_exp_f32_e32 v158, v158
	v_exp_f32_e32 v159, v159
	v_add_f32_e32 v158, 1.0, v158
	v_add_f32_e32 v159, 1.0, v159
	v_rcp_f32_e32 v158, v158
	v_rcp_f32_e32 v159, v159
	s_nop 0
	v_pk_mul_f32 v[156:157], v[156:157], v[158:159]
	s_nop 0
	v_cvt_pk_bf16_f32 v153, v156, v157
	global_store_dwordx4 v[148:149], v[150:153], off nt
	v_pk_mul_f32 v[156:157], v[188:189], v[2:3] op_sel_hi:[0,1]
	v_pk_mul_f32 v[158:159], v[188:189], v[4:5] op_sel_hi:[0,1]
	v_cvt_f32_i32_e32 v151, v111
	v_cvt_f32_i32_e32 v150, v110
	v_pk_mul_f32 v[152:153], v[188:189], v[6:7] op_sel_hi:[0,1]
	v_pk_mul_f32 v[150:151], v[152:153], v[150:151]
	s_nop 0
	v_mul_f32_e32 v152, 0xbfb8aa3b, v150
	v_mul_f32_e32 v153, 0xbfb8aa3b, v151
	v_exp_f32_e32 v152, v152
	v_exp_f32_e32 v153, v153
	v_add_f32_e32 v152, 1.0, v152
	v_add_f32_e32 v153, 1.0, v153
	v_rcp_f32_e32 v152, v152
	v_rcp_f32_e32 v153, v153
	s_nop 0
	v_pk_mul_f32 v[150:151], v[150:151], v[152:153]
	v_cvt_f32_i32_e32 v153, v113
	v_cvt_f32_i32_e32 v152, v112
	v_cvt_pk_bf16_f32 v150, v150, v151
	v_pk_mul_f32 v[152:153], v[154:155], v[152:153]
	s_nop 0
	v_mul_f32_e32 v154, 0xbfb8aa3b, v152
	v_mul_f32_e32 v155, 0xbfb8aa3b, v153
	v_exp_f32_e32 v154, v154
	v_exp_f32_e32 v155, v155
	v_add_f32_e32 v154, 1.0, v154
	v_add_f32_e32 v155, 1.0, v155
	v_rcp_f32_e32 v154, v154
	v_rcp_f32_e32 v155, v155
	s_nop 0
	v_pk_mul_f32 v[152:153], v[152:153], v[154:155]
	v_cvt_f32_i32_e32 v155, v103
	v_cvt_f32_i32_e32 v154, v102
	v_cvt_pk_bf16_f32 v151, v152, v153
	v_pk_mul_f32 v[154:155], v[156:157], v[154:155]
	s_nop 0
	v_mul_f32_e32 v156, 0xbfb8aa3b, v154
	v_mul_f32_e32 v157, 0xbfb8aa3b, v155
	v_exp_f32_e32 v156, v156
	v_exp_f32_e32 v157, v157
	v_add_f32_e32 v156, 1.0, v156
	v_add_f32_e32 v157, 1.0, v157
	v_rcp_f32_e32 v156, v156
	v_rcp_f32_e32 v157, v157
	s_nop 0
	v_pk_mul_f32 v[154:155], v[154:155], v[156:157]
	v_cvt_f32_i32_e32 v157, v105
	v_cvt_f32_i32_e32 v156, v104
	v_cvt_pk_bf16_f32 v152, v154, v155
	v_pk_mul_f32 v[154:155], v[186:187], v[16:17] op_sel_hi:[0,1]
	v_pk_mul_f32 v[156:157], v[158:159], v[156:157]
	s_nop 0
	v_mul_f32_e32 v158, 0xbfb8aa3b, v156
	v_mul_f32_e32 v159, 0xbfb8aa3b, v157
	v_exp_f32_e32 v158, v158
	v_exp_f32_e32 v159, v159
	v_add_f32_e32 v158, 1.0, v158
	v_add_f32_e32 v159, 1.0, v159
	v_rcp_f32_e32 v158, v158
	v_rcp_f32_e32 v159, v159
	s_nop 0
	v_pk_mul_f32 v[156:157], v[156:157], v[158:159]
	s_nop 0
	v_cvt_pk_bf16_f32 v153, v156, v157
	global_store_dwordx4 v[148:149], v[150:153], off offset:256 nt
	v_pk_mul_f32 v[156:157], v[186:187], v[10:11] op_sel_hi:[0,1]
	v_pk_mul_f32 v[158:159], v[186:187], v[12:13] op_sel_hi:[0,1]
	v_cvt_f32_i32_e32 v151, v123
	v_cvt_f32_i32_e32 v150, v122
	v_pk_mul_f32 v[152:153], v[186:187], v[14:15] op_sel_hi:[0,1]
	v_lshlrev_b64 v[148:149], 12, v[208:209]
	v_lshl_add_u64 v[148:149], v[146:147], 0, v[148:149]
	v_pk_mul_f32 v[150:151], v[152:153], v[150:151]
	s_nop 0
	v_mul_f32_e32 v152, 0xbfb8aa3b, v150
	v_mul_f32_e32 v153, 0xbfb8aa3b, v151
	v_exp_f32_e32 v152, v152
	v_exp_f32_e32 v153, v153
	v_add_f32_e32 v152, 1.0, v152
	v_add_f32_e32 v153, 1.0, v153
	v_rcp_f32_e32 v152, v152
	v_rcp_f32_e32 v153, v153
	s_nop 0
	v_pk_mul_f32 v[150:151], v[150:151], v[152:153]
	v_cvt_f32_i32_e32 v153, v125
	v_cvt_f32_i32_e32 v152, v124
	v_cvt_pk_bf16_f32 v150, v150, v151
	v_pk_mul_f32 v[152:153], v[154:155], v[152:153]
	s_nop 0
	v_mul_f32_e32 v154, 0xbfb8aa3b, v152
	v_mul_f32_e32 v155, 0xbfb8aa3b, v153
	v_exp_f32_e32 v154, v154
	v_exp_f32_e32 v155, v155
	v_add_f32_e32 v154, 1.0, v154
	v_add_f32_e32 v155, 1.0, v155
	v_rcp_f32_e32 v154, v154
	v_rcp_f32_e32 v155, v155
	s_nop 0
	v_pk_mul_f32 v[152:153], v[152:153], v[154:155]
	v_cvt_f32_i32_e32 v155, v115
	v_cvt_f32_i32_e32 v154, v114
	v_cvt_pk_bf16_f32 v151, v152, v153
	v_pk_mul_f32 v[154:155], v[156:157], v[154:155]
	s_nop 0
	v_mul_f32_e32 v156, 0xbfb8aa3b, v154
	v_mul_f32_e32 v157, 0xbfb8aa3b, v155
	v_exp_f32_e32 v156, v156
	v_exp_f32_e32 v157, v157
	v_add_f32_e32 v156, 1.0, v156
	v_add_f32_e32 v157, 1.0, v157
	v_rcp_f32_e32 v156, v156
	v_rcp_f32_e32 v157, v157
	s_nop 0
	v_pk_mul_f32 v[154:155], v[154:155], v[156:157]
	v_cvt_f32_i32_e32 v157, v117
	v_cvt_f32_i32_e32 v156, v116
	v_cvt_pk_bf16_f32 v152, v154, v155
	v_pk_mul_f32 v[154:155], v[186:187], v[8:9] op_sel_hi:[0,1]
	v_pk_mul_f32 v[156:157], v[158:159], v[156:157]
	s_nop 0
	v_mul_f32_e32 v158, 0xbfb8aa3b, v156
	v_mul_f32_e32 v159, 0xbfb8aa3b, v157
	v_exp_f32_e32 v158, v158
	v_exp_f32_e32 v159, v159
	v_add_f32_e32 v158, 1.0, v158
	v_add_f32_e32 v159, 1.0, v159
	v_rcp_f32_e32 v158, v158
	v_rcp_f32_e32 v159, v159
	s_nop 0
	v_pk_mul_f32 v[156:157], v[156:157], v[158:159]
	s_nop 0
	v_cvt_pk_bf16_f32 v153, v156, v157
	global_store_dwordx4 v[148:149], v[150:153], off nt
	v_pk_mul_f32 v[156:157], v[186:187], v[2:3] op_sel_hi:[0,1]
	v_pk_mul_f32 v[158:159], v[186:187], v[4:5] op_sel_hi:[0,1]
	v_cvt_f32_i32_e32 v151, v95
	v_cvt_f32_i32_e32 v150, v94
	v_pk_mul_f32 v[152:153], v[186:187], v[6:7] op_sel_hi:[0,1]
	v_pk_mul_f32 v[150:151], v[152:153], v[150:151]
	s_nop 0
	v_mul_f32_e32 v152, 0xbfb8aa3b, v150
	v_mul_f32_e32 v153, 0xbfb8aa3b, v151
	v_exp_f32_e32 v152, v152
	v_exp_f32_e32 v153, v153
	v_add_f32_e32 v152, 1.0, v152
	v_add_f32_e32 v153, 1.0, v153
	v_rcp_f32_e32 v152, v152
	v_rcp_f32_e32 v153, v153
	s_nop 0
	v_pk_mul_f32 v[150:151], v[150:151], v[152:153]
	v_cvt_f32_i32_e32 v153, v97
	v_cvt_f32_i32_e32 v152, v96
	v_cvt_pk_bf16_f32 v150, v150, v151
	v_pk_mul_f32 v[152:153], v[154:155], v[152:153]
	s_nop 0
	v_mul_f32_e32 v154, 0xbfb8aa3b, v152
	v_mul_f32_e32 v155, 0xbfb8aa3b, v153
	v_exp_f32_e32 v154, v154
	v_exp_f32_e32 v155, v155
	v_add_f32_e32 v154, 1.0, v154
	v_add_f32_e32 v155, 1.0, v155
	v_rcp_f32_e32 v154, v154
	v_rcp_f32_e32 v155, v155
	s_nop 0
	v_pk_mul_f32 v[152:153], v[152:153], v[154:155]
	v_cvt_f32_i32_e32 v155, v91
	v_cvt_f32_i32_e32 v154, v90
	v_cvt_pk_bf16_f32 v151, v152, v153
	v_pk_mul_f32 v[154:155], v[156:157], v[154:155]
	s_nop 0
	v_mul_f32_e32 v156, 0xbfb8aa3b, v154
	v_mul_f32_e32 v157, 0xbfb8aa3b, v155
	v_exp_f32_e32 v156, v156
	v_exp_f32_e32 v157, v157
	v_add_f32_e32 v156, 1.0, v156
	v_add_f32_e32 v157, 1.0, v157
	v_rcp_f32_e32 v156, v156
	v_rcp_f32_e32 v157, v157
	s_nop 0
	v_pk_mul_f32 v[154:155], v[154:155], v[156:157]
	v_cvt_f32_i32_e32 v157, v93
	v_cvt_f32_i32_e32 v156, v92
	v_cvt_pk_bf16_f32 v152, v154, v155
	v_pk_mul_f32 v[154:155], v[182:183], v[16:17] op_sel_hi:[0,1]
	v_pk_mul_f32 v[156:157], v[158:159], v[156:157]
	s_nop 0
	v_mul_f32_e32 v158, 0xbfb8aa3b, v156
	v_mul_f32_e32 v159, 0xbfb8aa3b, v157
	v_exp_f32_e32 v158, v158
	v_exp_f32_e32 v159, v159
	v_add_f32_e32 v158, 1.0, v158
	v_add_f32_e32 v159, 1.0, v159
	v_rcp_f32_e32 v158, v158
	v_rcp_f32_e32 v159, v159
	s_nop 0
	v_pk_mul_f32 v[156:157], v[156:157], v[158:159]
	s_nop 0
	v_cvt_pk_bf16_f32 v153, v156, v157
	global_store_dwordx4 v[148:149], v[150:153], off offset:256 nt
	v_pk_mul_f32 v[156:157], v[182:183], v[10:11] op_sel_hi:[0,1]
	v_pk_mul_f32 v[158:159], v[182:183], v[12:13] op_sel_hi:[0,1]
	v_cvt_f32_i32_e32 v151, v107
	v_cvt_f32_i32_e32 v150, v106
	v_pk_mul_f32 v[152:153], v[182:183], v[14:15] op_sel_hi:[0,1]
	v_lshlrev_b64 v[148:149], 12, v[210:211]
	v_lshl_add_u64 v[148:149], v[146:147], 0, v[148:149]
	v_pk_mul_f32 v[150:151], v[152:153], v[150:151]
	s_nop 0
	v_mul_f32_e32 v152, 0xbfb8aa3b, v150
	v_mul_f32_e32 v153, 0xbfb8aa3b, v151
	v_exp_f32_e32 v152, v152
	v_exp_f32_e32 v153, v153
	v_add_f32_e32 v152, 1.0, v152
	v_add_f32_e32 v153, 1.0, v153
	v_rcp_f32_e32 v152, v152
	v_rcp_f32_e32 v153, v153
	s_nop 0
	v_pk_mul_f32 v[150:151], v[150:151], v[152:153]
	v_cvt_f32_i32_e32 v153, v109
	v_cvt_f32_i32_e32 v152, v108
	v_cvt_pk_bf16_f32 v150, v150, v151
	v_pk_mul_f32 v[152:153], v[154:155], v[152:153]
	s_nop 0
	v_mul_f32_e32 v154, 0xbfb8aa3b, v152
	v_mul_f32_e32 v155, 0xbfb8aa3b, v153
	v_exp_f32_e32 v154, v154
	v_exp_f32_e32 v155, v155
	v_add_f32_e32 v154, 1.0, v154
	v_add_f32_e32 v155, 1.0, v155
	v_rcp_f32_e32 v154, v154
	v_rcp_f32_e32 v155, v155
	s_nop 0
	v_pk_mul_f32 v[152:153], v[152:153], v[154:155]
	v_cvt_f32_i32_e32 v155, v99
	v_cvt_f32_i32_e32 v154, v98
	v_cvt_pk_bf16_f32 v151, v152, v153
	v_pk_mul_f32 v[154:155], v[156:157], v[154:155]
	s_nop 0
	v_mul_f32_e32 v156, 0xbfb8aa3b, v154
	v_mul_f32_e32 v157, 0xbfb8aa3b, v155
	v_exp_f32_e32 v156, v156
	v_exp_f32_e32 v157, v157
	v_add_f32_e32 v156, 1.0, v156
	v_add_f32_e32 v157, 1.0, v157
	v_rcp_f32_e32 v156, v156
	v_rcp_f32_e32 v157, v157
	s_nop 0
	v_pk_mul_f32 v[154:155], v[154:155], v[156:157]
	v_cvt_f32_i32_e32 v157, v101
	v_cvt_f32_i32_e32 v156, v100
	v_cvt_pk_bf16_f32 v152, v154, v155
	v_pk_mul_f32 v[154:155], v[182:183], v[8:9] op_sel_hi:[0,1]
	v_pk_mul_f32 v[156:157], v[158:159], v[156:157]
	s_nop 0
	v_mul_f32_e32 v158, 0xbfb8aa3b, v156
	v_mul_f32_e32 v159, 0xbfb8aa3b, v157
	v_exp_f32_e32 v158, v158
	v_exp_f32_e32 v159, v159
	v_add_f32_e32 v158, 1.0, v158
	v_add_f32_e32 v159, 1.0, v159
	v_rcp_f32_e32 v158, v158
	v_rcp_f32_e32 v159, v159
	s_nop 0
	v_pk_mul_f32 v[156:157], v[156:157], v[158:159]
	s_nop 0
	v_cvt_pk_bf16_f32 v153, v156, v157
	global_store_dwordx4 v[148:149], v[150:153], off nt
	v_pk_mul_f32 v[156:157], v[182:183], v[2:3] op_sel_hi:[0,1]
	v_pk_mul_f32 v[158:159], v[182:183], v[4:5] op_sel_hi:[0,1]
	v_cvt_f32_i32_e32 v151, v87
	v_cvt_f32_i32_e32 v150, v86
	v_pk_mul_f32 v[152:153], v[182:183], v[6:7] op_sel_hi:[0,1]
	v_pk_mul_f32 v[150:151], v[152:153], v[150:151]
	s_nop 0
	v_mul_f32_e32 v152, 0xbfb8aa3b, v150
	v_mul_f32_e32 v153, 0xbfb8aa3b, v151
	v_exp_f32_e32 v152, v152
	v_exp_f32_e32 v153, v153
	v_add_f32_e32 v152, 1.0, v152
	v_add_f32_e32 v153, 1.0, v153
	v_rcp_f32_e32 v152, v152
	v_rcp_f32_e32 v153, v153
	s_nop 0
	v_pk_mul_f32 v[150:151], v[150:151], v[152:153]
	v_cvt_f32_i32_e32 v153, v89
	v_cvt_f32_i32_e32 v152, v88
	v_cvt_pk_bf16_f32 v150, v150, v151
	v_pk_mul_f32 v[152:153], v[154:155], v[152:153]
	s_nop 0
	v_mul_f32_e32 v154, 0xbfb8aa3b, v152
	v_mul_f32_e32 v155, 0xbfb8aa3b, v153
	v_exp_f32_e32 v154, v154
	v_exp_f32_e32 v155, v155
	v_add_f32_e32 v154, 1.0, v154
	v_add_f32_e32 v155, 1.0, v155
	v_rcp_f32_e32 v154, v154
	v_rcp_f32_e32 v155, v155
	s_nop 0
	v_pk_mul_f32 v[152:153], v[152:153], v[154:155]
	v_cvt_f32_i32_e32 v155, v83
	v_cvt_f32_i32_e32 v154, v82
	v_cvt_pk_bf16_f32 v151, v152, v153
	v_pk_mul_f32 v[154:155], v[156:157], v[154:155]
	s_nop 0
	v_mul_f32_e32 v156, 0xbfb8aa3b, v154
	v_mul_f32_e32 v157, 0xbfb8aa3b, v155
	v_exp_f32_e32 v156, v156
	v_exp_f32_e32 v157, v157
	v_add_f32_e32 v156, 1.0, v156
	v_add_f32_e32 v157, 1.0, v157
	v_rcp_f32_e32 v156, v156
	v_rcp_f32_e32 v157, v157
	s_nop 0
	v_pk_mul_f32 v[154:155], v[154:155], v[156:157]
	v_cvt_f32_i32_e32 v157, v85
	v_cvt_f32_i32_e32 v156, v84
	v_cvt_pk_bf16_f32 v152, v154, v155
	v_pk_mul_f32 v[154:155], v[180:181], v[16:17] op_sel_hi:[0,1]
	v_pk_mul_f32 v[156:157], v[158:159], v[156:157]
	s_nop 0
	v_mul_f32_e32 v158, 0xbfb8aa3b, v156
	v_mul_f32_e32 v159, 0xbfb8aa3b, v157
	v_exp_f32_e32 v158, v158
	v_exp_f32_e32 v159, v159
	v_add_f32_e32 v158, 1.0, v158
	v_add_f32_e32 v159, 1.0, v159
	v_rcp_f32_e32 v158, v158
	v_rcp_f32_e32 v159, v159
	s_nop 0
	v_pk_mul_f32 v[156:157], v[156:157], v[158:159]
	s_nop 0
	v_cvt_pk_bf16_f32 v153, v156, v157
	global_store_dwordx4 v[148:149], v[150:153], off offset:256 nt
	v_pk_mul_f32 v[156:157], v[180:181], v[10:11] op_sel_hi:[0,1]
	v_pk_mul_f32 v[158:159], v[180:181], v[12:13] op_sel_hi:[0,1]
	v_cvt_f32_i32_e32 v151, v79
	v_cvt_f32_i32_e32 v150, v78
	v_pk_mul_f32 v[152:153], v[180:181], v[14:15] op_sel_hi:[0,1]
	v_lshlrev_b64 v[148:149], 12, v[184:185]
	v_lshl_add_u64 v[148:149], v[146:147], 0, v[148:149]
	v_pk_mul_f32 v[150:151], v[152:153], v[150:151]
	s_nop 0
	v_mul_f32_e32 v152, 0xbfb8aa3b, v150
	v_mul_f32_e32 v153, 0xbfb8aa3b, v151
	v_exp_f32_e32 v152, v152
	v_exp_f32_e32 v153, v153
	v_add_f32_e32 v152, 1.0, v152
	v_add_f32_e32 v153, 1.0, v153
	v_rcp_f32_e32 v152, v152
	v_rcp_f32_e32 v153, v153
	s_nop 0
	v_pk_mul_f32 v[150:151], v[150:151], v[152:153]
	v_cvt_f32_i32_e32 v153, v81
	v_cvt_f32_i32_e32 v152, v80
	v_cvt_pk_bf16_f32 v150, v150, v151
	v_pk_mul_f32 v[152:153], v[154:155], v[152:153]
	s_nop 0
	v_mul_f32_e32 v154, 0xbfb8aa3b, v152
	v_mul_f32_e32 v155, 0xbfb8aa3b, v153
	v_exp_f32_e32 v154, v154
	v_exp_f32_e32 v155, v155
	v_add_f32_e32 v154, 1.0, v154
	v_add_f32_e32 v155, 1.0, v155
	v_rcp_f32_e32 v154, v154
	v_rcp_f32_e32 v155, v155
	s_nop 0
	v_pk_mul_f32 v[152:153], v[152:153], v[154:155]
	v_cvt_f32_i32_e32 v155, v75
	v_cvt_f32_i32_e32 v154, v74
	v_cvt_pk_bf16_f32 v151, v152, v153
	v_pk_mul_f32 v[154:155], v[156:157], v[154:155]
	s_nop 0
	v_mul_f32_e32 v156, 0xbfb8aa3b, v154
	v_mul_f32_e32 v157, 0xbfb8aa3b, v155
	v_exp_f32_e32 v156, v156
	v_exp_f32_e32 v157, v157
	v_add_f32_e32 v156, 1.0, v156
	v_add_f32_e32 v157, 1.0, v157
	v_rcp_f32_e32 v156, v156
	v_rcp_f32_e32 v157, v157
	s_nop 0
	v_pk_mul_f32 v[154:155], v[154:155], v[156:157]
	v_cvt_f32_i32_e32 v157, v77
	v_cvt_f32_i32_e32 v156, v76
	v_cvt_pk_bf16_f32 v152, v154, v155
	v_pk_mul_f32 v[154:155], v[180:181], v[8:9] op_sel_hi:[0,1]
	v_pk_mul_f32 v[156:157], v[158:159], v[156:157]
	s_nop 0
	v_mul_f32_e32 v158, 0xbfb8aa3b, v156
	v_mul_f32_e32 v159, 0xbfb8aa3b, v157
	v_exp_f32_e32 v158, v158
	v_exp_f32_e32 v159, v159
	v_add_f32_e32 v158, 1.0, v158
	v_add_f32_e32 v159, 1.0, v159
	v_rcp_f32_e32 v158, v158
	v_rcp_f32_e32 v159, v159
	s_nop 0
	v_pk_mul_f32 v[156:157], v[156:157], v[158:159]
	s_nop 0
	v_cvt_pk_bf16_f32 v153, v156, v157
	global_store_dwordx4 v[148:149], v[150:153], off nt
	v_pk_mul_f32 v[156:157], v[180:181], v[2:3] op_sel_hi:[0,1]
	v_pk_mul_f32 v[158:159], v[180:181], v[4:5] op_sel_hi:[0,1]
	v_cvt_f32_i32_e32 v151, v63
	v_cvt_f32_i32_e32 v150, v62
	v_pk_mul_f32 v[152:153], v[180:181], v[6:7] op_sel_hi:[0,1]
	v_pk_mul_f32 v[150:151], v[152:153], v[150:151]
	s_nop 0
	v_mul_f32_e32 v152, 0xbfb8aa3b, v150
	v_mul_f32_e32 v153, 0xbfb8aa3b, v151
	v_exp_f32_e32 v152, v152
	v_exp_f32_e32 v153, v153
	v_add_f32_e32 v152, 1.0, v152
	v_add_f32_e32 v153, 1.0, v153
	v_rcp_f32_e32 v152, v152
	v_rcp_f32_e32 v153, v153
	s_nop 0
	v_pk_mul_f32 v[150:151], v[150:151], v[152:153]
	v_cvt_f32_i32_e32 v153, v65
	v_cvt_f32_i32_e32 v152, v64
	v_cvt_pk_bf16_f32 v150, v150, v151
	v_pk_mul_f32 v[152:153], v[154:155], v[152:153]
	s_nop 0
	v_mul_f32_e32 v154, 0xbfb8aa3b, v152
	v_mul_f32_e32 v155, 0xbfb8aa3b, v153
	v_exp_f32_e32 v154, v154
	v_exp_f32_e32 v155, v155
	v_add_f32_e32 v154, 1.0, v154
	v_add_f32_e32 v155, 1.0, v155
	v_rcp_f32_e32 v154, v154
	v_rcp_f32_e32 v155, v155
	s_nop 0
	v_pk_mul_f32 v[152:153], v[152:153], v[154:155]
	v_cvt_f32_i32_e32 v155, v59
	v_cvt_f32_i32_e32 v154, v58
	v_cvt_pk_bf16_f32 v151, v152, v153
	v_pk_mul_f32 v[154:155], v[156:157], v[154:155]
	s_nop 0
	v_mul_f32_e32 v156, 0xbfb8aa3b, v154
	v_mul_f32_e32 v157, 0xbfb8aa3b, v155
	v_exp_f32_e32 v156, v156
	v_exp_f32_e32 v157, v157
	v_add_f32_e32 v156, 1.0, v156
	v_add_f32_e32 v157, 1.0, v157
	v_rcp_f32_e32 v156, v156
	v_rcp_f32_e32 v157, v157
	s_nop 0
	v_pk_mul_f32 v[154:155], v[154:155], v[156:157]
	v_cvt_f32_i32_e32 v157, v61
	v_cvt_f32_i32_e32 v156, v60
	v_cvt_pk_bf16_f32 v152, v154, v155
	v_pk_mul_f32 v[154:155], v[178:179], v[16:17] op_sel_hi:[0,1]
	v_pk_mul_f32 v[156:157], v[158:159], v[156:157]
	s_nop 0
	v_mul_f32_e32 v158, 0xbfb8aa3b, v156
	v_mul_f32_e32 v159, 0xbfb8aa3b, v157
	v_exp_f32_e32 v158, v158
	v_exp_f32_e32 v159, v159
	v_add_f32_e32 v158, 1.0, v158
	v_add_f32_e32 v159, 1.0, v159
	v_rcp_f32_e32 v158, v158
	v_rcp_f32_e32 v159, v159
	s_nop 0
	v_pk_mul_f32 v[156:157], v[156:157], v[158:159]
	s_nop 0
	v_cvt_pk_bf16_f32 v153, v156, v157
	global_store_dwordx4 v[148:149], v[150:153], off offset:256 nt
	v_pk_mul_f32 v[156:157], v[178:179], v[10:11] op_sel_hi:[0,1]
	v_pk_mul_f32 v[158:159], v[178:179], v[12:13] op_sel_hi:[0,1]
	v_cvt_f32_i32_e32 v151, v71
	v_cvt_f32_i32_e32 v150, v70
	v_pk_mul_f32 v[152:153], v[178:179], v[14:15] op_sel_hi:[0,1]
	v_lshlrev_b64 v[148:149], 12, v[212:213]
	v_lshl_add_u64 v[148:149], v[146:147], 0, v[148:149]
	v_pk_mul_f32 v[150:151], v[152:153], v[150:151]
	s_nop 0
	v_mul_f32_e32 v152, 0xbfb8aa3b, v150
	v_mul_f32_e32 v153, 0xbfb8aa3b, v151
	v_exp_f32_e32 v152, v152
	v_exp_f32_e32 v153, v153
	v_add_f32_e32 v152, 1.0, v152
	v_add_f32_e32 v153, 1.0, v153
	v_rcp_f32_e32 v152, v152
	v_rcp_f32_e32 v153, v153
	s_nop 0
	v_pk_mul_f32 v[150:151], v[150:151], v[152:153]
	v_cvt_f32_i32_e32 v153, v73
	v_cvt_f32_i32_e32 v152, v72
	v_cvt_pk_bf16_f32 v150, v150, v151
	v_pk_mul_f32 v[152:153], v[154:155], v[152:153]
	s_nop 0
	v_mul_f32_e32 v154, 0xbfb8aa3b, v152
	v_mul_f32_e32 v155, 0xbfb8aa3b, v153
	v_exp_f32_e32 v154, v154
	v_exp_f32_e32 v155, v155
	v_add_f32_e32 v154, 1.0, v154
	v_add_f32_e32 v155, 1.0, v155
	v_rcp_f32_e32 v154, v154
	v_rcp_f32_e32 v155, v155
	s_nop 0
	v_pk_mul_f32 v[152:153], v[152:153], v[154:155]
	v_cvt_f32_i32_e32 v155, v67
	v_cvt_f32_i32_e32 v154, v66
	v_cvt_pk_bf16_f32 v151, v152, v153
	v_pk_mul_f32 v[154:155], v[156:157], v[154:155]
	s_nop 0
	v_mul_f32_e32 v156, 0xbfb8aa3b, v154
	v_mul_f32_e32 v157, 0xbfb8aa3b, v155
	v_exp_f32_e32 v156, v156
	v_exp_f32_e32 v157, v157
	v_add_f32_e32 v156, 1.0, v156
	v_add_f32_e32 v157, 1.0, v157
	v_rcp_f32_e32 v156, v156
	v_rcp_f32_e32 v157, v157
	s_nop 0
	v_pk_mul_f32 v[154:155], v[154:155], v[156:157]
	v_cvt_f32_i32_e32 v157, v69
	v_cvt_f32_i32_e32 v156, v68
	v_cvt_pk_bf16_f32 v152, v154, v155
	v_pk_mul_f32 v[154:155], v[178:179], v[8:9] op_sel_hi:[0,1]
	v_pk_mul_f32 v[156:157], v[158:159], v[156:157]
	s_nop 0
	v_mul_f32_e32 v158, 0xbfb8aa3b, v156
	v_mul_f32_e32 v159, 0xbfb8aa3b, v157
	v_exp_f32_e32 v158, v158
	v_exp_f32_e32 v159, v159
	v_add_f32_e32 v158, 1.0, v158
	v_add_f32_e32 v159, 1.0, v159
	v_rcp_f32_e32 v158, v158
	v_rcp_f32_e32 v159, v159
	s_nop 0
	v_pk_mul_f32 v[156:157], v[156:157], v[158:159]
	s_nop 0
	v_cvt_pk_bf16_f32 v153, v156, v157
	global_store_dwordx4 v[148:149], v[150:153], off nt
	v_pk_mul_f32 v[156:157], v[178:179], v[2:3] op_sel_hi:[0,1]
	v_pk_mul_f32 v[158:159], v[178:179], v[4:5] op_sel_hi:[0,1]
	v_cvt_f32_i32_e32 v151, v47
	v_cvt_f32_i32_e32 v150, v46
	v_pk_mul_f32 v[152:153], v[178:179], v[6:7] op_sel_hi:[0,1]
	v_pk_mul_f32 v[150:151], v[152:153], v[150:151]
	s_nop 0
	v_mul_f32_e32 v152, 0xbfb8aa3b, v150
	v_mul_f32_e32 v153, 0xbfb8aa3b, v151
	v_exp_f32_e32 v152, v152
	v_exp_f32_e32 v153, v153
	v_add_f32_e32 v152, 1.0, v152
	v_add_f32_e32 v153, 1.0, v153
	v_rcp_f32_e32 v152, v152
	v_rcp_f32_e32 v153, v153
	s_nop 0
	v_pk_mul_f32 v[150:151], v[150:151], v[152:153]
	v_cvt_f32_i32_e32 v153, v49
	v_cvt_f32_i32_e32 v152, v48
	v_cvt_pk_bf16_f32 v150, v150, v151
	v_pk_mul_f32 v[152:153], v[154:155], v[152:153]
	s_nop 0
	v_mul_f32_e32 v154, 0xbfb8aa3b, v152
	v_mul_f32_e32 v155, 0xbfb8aa3b, v153
	v_exp_f32_e32 v154, v154
	v_exp_f32_e32 v155, v155
	v_add_f32_e32 v154, 1.0, v154
	v_add_f32_e32 v155, 1.0, v155
	v_rcp_f32_e32 v154, v154
	v_rcp_f32_e32 v155, v155
	s_nop 0
	v_pk_mul_f32 v[152:153], v[152:153], v[154:155]
	v_cvt_f32_i32_e32 v155, v43
	v_cvt_f32_i32_e32 v154, v42
	v_cvt_pk_bf16_f32 v151, v152, v153
	v_pk_mul_f32 v[154:155], v[156:157], v[154:155]
	s_nop 0
	v_mul_f32_e32 v156, 0xbfb8aa3b, v154
	v_mul_f32_e32 v157, 0xbfb8aa3b, v155
	v_exp_f32_e32 v156, v156
	v_exp_f32_e32 v157, v157
	v_add_f32_e32 v156, 1.0, v156
	v_add_f32_e32 v157, 1.0, v157
	v_rcp_f32_e32 v156, v156
	v_rcp_f32_e32 v157, v157
	s_nop 0
	v_pk_mul_f32 v[154:155], v[154:155], v[156:157]
	v_cvt_f32_i32_e32 v157, v45
	v_cvt_f32_i32_e32 v156, v44
	v_cvt_pk_bf16_f32 v152, v154, v155
	v_pk_mul_f32 v[154:155], v[176:177], v[16:17] op_sel_hi:[0,1]
	v_pk_mul_f32 v[156:157], v[158:159], v[156:157]
	s_nop 0
	v_mul_f32_e32 v158, 0xbfb8aa3b, v156
	v_mul_f32_e32 v159, 0xbfb8aa3b, v157
	v_exp_f32_e32 v158, v158
	v_exp_f32_e32 v159, v159
	v_add_f32_e32 v158, 1.0, v158
	v_add_f32_e32 v159, 1.0, v159
	v_rcp_f32_e32 v158, v158
	v_rcp_f32_e32 v159, v159
	s_nop 0
	v_pk_mul_f32 v[156:157], v[156:157], v[158:159]
	s_nop 0
	v_cvt_pk_bf16_f32 v153, v156, v157
	global_store_dwordx4 v[148:149], v[150:153], off offset:256 nt
	v_pk_mul_f32 v[156:157], v[176:177], v[10:11] op_sel_hi:[0,1]
	v_pk_mul_f32 v[158:159], v[176:177], v[12:13] op_sel_hi:[0,1]
	v_cvt_f32_i32_e32 v151, v55
	v_cvt_f32_i32_e32 v150, v54
	v_pk_mul_f32 v[152:153], v[176:177], v[14:15] op_sel_hi:[0,1]
	v_lshlrev_b64 v[148:149], 12, v[204:205]
	v_lshl_add_u64 v[148:149], v[146:147], 0, v[148:149]
	v_pk_mul_f32 v[150:151], v[152:153], v[150:151]
	s_nop 0
	v_mul_f32_e32 v152, 0xbfb8aa3b, v150
	v_mul_f32_e32 v153, 0xbfb8aa3b, v151
	v_exp_f32_e32 v152, v152
	v_exp_f32_e32 v153, v153
	v_add_f32_e32 v152, 1.0, v152
	v_add_f32_e32 v153, 1.0, v153
	v_rcp_f32_e32 v152, v152
	v_rcp_f32_e32 v153, v153
	s_nop 0
	v_pk_mul_f32 v[150:151], v[150:151], v[152:153]
	v_cvt_f32_i32_e32 v153, v57
	v_cvt_f32_i32_e32 v152, v56
	v_cvt_pk_bf16_f32 v150, v150, v151
	v_pk_mul_f32 v[152:153], v[154:155], v[152:153]
	s_nop 0
	v_mul_f32_e32 v154, 0xbfb8aa3b, v152
	v_mul_f32_e32 v155, 0xbfb8aa3b, v153
	v_exp_f32_e32 v154, v154
	v_exp_f32_e32 v155, v155
	v_add_f32_e32 v154, 1.0, v154
	v_add_f32_e32 v155, 1.0, v155
	v_rcp_f32_e32 v154, v154
	v_rcp_f32_e32 v155, v155
	s_nop 0
	v_pk_mul_f32 v[152:153], v[152:153], v[154:155]
	v_cvt_f32_i32_e32 v155, v51
	v_cvt_f32_i32_e32 v154, v50
	v_cvt_pk_bf16_f32 v151, v152, v153
	v_pk_mul_f32 v[154:155], v[156:157], v[154:155]
	s_nop 0
	v_mul_f32_e32 v156, 0xbfb8aa3b, v154
	v_mul_f32_e32 v157, 0xbfb8aa3b, v155
	v_exp_f32_e32 v156, v156
	v_exp_f32_e32 v157, v157
	v_add_f32_e32 v156, 1.0, v156
	v_add_f32_e32 v157, 1.0, v157
	v_rcp_f32_e32 v156, v156
	v_rcp_f32_e32 v157, v157
	s_nop 0
	v_pk_mul_f32 v[154:155], v[154:155], v[156:157]
	v_cvt_f32_i32_e32 v157, v53
	v_cvt_f32_i32_e32 v156, v52
	v_cvt_pk_bf16_f32 v152, v154, v155
	v_pk_mul_f32 v[154:155], v[176:177], v[8:9] op_sel_hi:[0,1]
	v_pk_mul_f32 v[156:157], v[158:159], v[156:157]
	s_nop 0
	v_mul_f32_e32 v158, 0xbfb8aa3b, v156
	v_mul_f32_e32 v159, 0xbfb8aa3b, v157
	v_exp_f32_e32 v158, v158
	v_exp_f32_e32 v159, v159
	v_add_f32_e32 v158, 1.0, v158
	v_add_f32_e32 v159, 1.0, v159
	v_rcp_f32_e32 v158, v158
	v_rcp_f32_e32 v159, v159
	s_nop 0
	v_pk_mul_f32 v[156:157], v[156:157], v[158:159]
	s_nop 0
	v_cvt_pk_bf16_f32 v153, v156, v157
	global_store_dwordx4 v[148:149], v[150:153], off nt
	v_pk_mul_f32 v[156:157], v[176:177], v[2:3] op_sel_hi:[0,1]
	v_pk_mul_f32 v[158:159], v[176:177], v[4:5] op_sel_hi:[0,1]
	v_cvt_f32_i32_e32 v151, v31
	v_cvt_f32_i32_e32 v150, v30
	v_pk_mul_f32 v[152:153], v[176:177], v[6:7] op_sel_hi:[0,1]
	v_pk_mul_f32 v[150:151], v[152:153], v[150:151]
	s_nop 0
	v_mul_f32_e32 v152, 0xbfb8aa3b, v150
	v_mul_f32_e32 v153, 0xbfb8aa3b, v151
	v_exp_f32_e32 v152, v152
	v_exp_f32_e32 v153, v153
	v_add_f32_e32 v152, 1.0, v152
	v_add_f32_e32 v153, 1.0, v153
	v_rcp_f32_e32 v152, v152
	v_rcp_f32_e32 v153, v153
	s_nop 0
	v_pk_mul_f32 v[150:151], v[150:151], v[152:153]
	v_cvt_f32_i32_e32 v153, v33
	v_cvt_f32_i32_e32 v152, v32
	v_cvt_pk_bf16_f32 v150, v150, v151
	v_pk_mul_f32 v[152:153], v[154:155], v[152:153]
	s_nop 0
	v_mul_f32_e32 v154, 0xbfb8aa3b, v152
	v_mul_f32_e32 v155, 0xbfb8aa3b, v153
	v_exp_f32_e32 v154, v154
	v_exp_f32_e32 v155, v155
	v_add_f32_e32 v154, 1.0, v154
	v_add_f32_e32 v155, 1.0, v155
	v_rcp_f32_e32 v154, v154
	v_rcp_f32_e32 v155, v155
	s_nop 0
	v_pk_mul_f32 v[152:153], v[152:153], v[154:155]
	v_cvt_f32_i32_e32 v155, v27
	v_cvt_f32_i32_e32 v154, v26
	v_cvt_pk_bf16_f32 v151, v152, v153
	v_pk_mul_f32 v[154:155], v[156:157], v[154:155]
	s_nop 0
	v_mul_f32_e32 v156, 0xbfb8aa3b, v154
	v_mul_f32_e32 v157, 0xbfb8aa3b, v155
	v_exp_f32_e32 v156, v156
	v_exp_f32_e32 v157, v157
	v_add_f32_e32 v156, 1.0, v156
	v_add_f32_e32 v157, 1.0, v157
	v_rcp_f32_e32 v156, v156
	v_rcp_f32_e32 v157, v157
	s_nop 0
	v_pk_mul_f32 v[154:155], v[154:155], v[156:157]
	v_cvt_f32_i32_e32 v157, v29
	v_cvt_f32_i32_e32 v156, v28
	v_cvt_pk_bf16_f32 v152, v154, v155
	v_pk_mul_f32 v[154:155], v[174:175], v[10:11] op_sel_hi:[0,1]
	v_pk_mul_f32 v[156:157], v[158:159], v[156:157]
	s_nop 0
	v_mul_f32_e32 v158, 0xbfb8aa3b, v156
	v_mul_f32_e32 v159, 0xbfb8aa3b, v157
	v_exp_f32_e32 v158, v158
	v_exp_f32_e32 v159, v159
	v_add_f32_e32 v158, 1.0, v158
	v_add_f32_e32 v159, 1.0, v159
	v_rcp_f32_e32 v158, v158
	v_rcp_f32_e32 v159, v159
	s_nop 0
	v_pk_mul_f32 v[156:157], v[156:157], v[158:159]
	s_nop 0
	v_cvt_pk_bf16_f32 v153, v156, v157
	global_store_dwordx4 v[148:149], v[150:153], off offset:256 nt
	v_lshlrev_b64 v[148:149], 12, v[202:203]
	v_lshl_add_u64 v[146:147], v[146:147], 0, v[148:149]
	v_cvt_f32_i32_e32 v149, v39
	v_cvt_f32_i32_e32 v148, v38
	v_pk_mul_f32 v[150:151], v[174:175], v[14:15] op_sel_hi:[0,1]
	v_pk_mul_f32 v[152:153], v[174:175], v[16:17] op_sel_hi:[0,1]
	v_pk_mul_f32 v[156:157], v[174:175], v[12:13] op_sel_hi:[0,1]
	v_pk_mul_f32 v[148:149], v[150:151], v[148:149]
	s_nop 0
	v_mul_f32_e32 v150, 0xbfb8aa3b, v148
	v_mul_f32_e32 v151, 0xbfb8aa3b, v149
	v_exp_f32_e32 v150, v150
	v_exp_f32_e32 v151, v151
	v_add_f32_e32 v150, 1.0, v150
	v_add_f32_e32 v151, 1.0, v151
	v_rcp_f32_e32 v150, v150
	v_rcp_f32_e32 v151, v151
	s_nop 0
	v_pk_mul_f32 v[148:149], v[148:149], v[150:151]
	v_cvt_f32_i32_e32 v151, v41
	v_cvt_f32_i32_e32 v150, v40
	v_cvt_pk_bf16_f32 v148, v148, v149
	v_pk_mul_f32 v[150:151], v[152:153], v[150:151]
	s_nop 0
	v_mul_f32_e32 v152, 0xbfb8aa3b, v150
	v_mul_f32_e32 v153, 0xbfb8aa3b, v151
	v_exp_f32_e32 v152, v152
	v_exp_f32_e32 v153, v153
	v_add_f32_e32 v152, 1.0, v152
	v_add_f32_e32 v153, 1.0, v153
	v_rcp_f32_e32 v152, v152
	v_rcp_f32_e32 v153, v153
	s_nop 0
	v_pk_mul_f32 v[150:151], v[150:151], v[152:153]
	v_cvt_f32_i32_e32 v153, v35
	v_cvt_f32_i32_e32 v152, v34
	v_cvt_pk_bf16_f32 v149, v150, v151
	v_pk_mul_f32 v[152:153], v[154:155], v[152:153]
	s_nop 0
	v_mul_f32_e32 v154, 0xbfb8aa3b, v152
	v_mul_f32_e32 v155, 0xbfb8aa3b, v153
	v_exp_f32_e32 v154, v154
	v_exp_f32_e32 v155, v155
	v_add_f32_e32 v154, 1.0, v154
	v_add_f32_e32 v155, 1.0, v155
	v_rcp_f32_e32 v154, v154
	v_rcp_f32_e32 v155, v155
	s_nop 0
	v_pk_mul_f32 v[152:153], v[152:153], v[154:155]
	v_cvt_f32_i32_e32 v155, v37
	v_cvt_f32_i32_e32 v154, v36
	v_cvt_pk_bf16_f32 v150, v152, v153
	v_pk_mul_f32 v[152:153], v[174:175], v[8:9] op_sel_hi:[0,1]
	v_pk_mul_f32 v[154:155], v[156:157], v[154:155]
	s_nop 0
	v_mul_f32_e32 v156, 0xbfb8aa3b, v154
	v_mul_f32_e32 v157, 0xbfb8aa3b, v155
	v_exp_f32_e32 v156, v156
	v_exp_f32_e32 v157, v157
	v_add_f32_e32 v156, 1.0, v156
	v_add_f32_e32 v157, 1.0, v157
	v_rcp_f32_e32 v156, v156
	v_rcp_f32_e32 v157, v157
	s_nop 0
	v_pk_mul_f32 v[154:155], v[154:155], v[156:157]
	s_nop 0
	v_cvt_pk_bf16_f32 v151, v154, v155
	global_store_dwordx4 v[146:147], v[148:151], off nt
	v_pk_mul_f32 v[154:155], v[174:175], v[2:3] op_sel_hi:[0,1]
	v_pk_mul_f32 v[156:157], v[174:175], v[4:5] op_sel_hi:[0,1]
	v_cvt_f32_i32_e32 v149, v23
	v_cvt_f32_i32_e32 v148, v22
	v_pk_mul_f32 v[150:151], v[174:175], v[6:7] op_sel_hi:[0,1]
	v_pk_mul_f32 v[148:149], v[150:151], v[148:149]
	s_nop 0
	v_mul_f32_e32 v150, 0xbfb8aa3b, v148
	v_mul_f32_e32 v151, 0xbfb8aa3b, v149
	v_exp_f32_e32 v150, v150
	v_exp_f32_e32 v151, v151
	v_add_f32_e32 v150, 1.0, v150
	v_add_f32_e32 v151, 1.0, v151
	v_rcp_f32_e32 v150, v150
	v_rcp_f32_e32 v151, v151
	s_nop 0
	v_pk_mul_f32 v[148:149], v[148:149], v[150:151]
	v_cvt_f32_i32_e32 v151, v25
	v_cvt_f32_i32_e32 v150, v24
	v_cvt_pk_bf16_f32 v148, v148, v149
	v_pk_mul_f32 v[150:151], v[152:153], v[150:151]
	s_nop 0
	v_mul_f32_e32 v152, 0xbfb8aa3b, v150
	v_mul_f32_e32 v153, 0xbfb8aa3b, v151
	v_exp_f32_e32 v152, v152
	v_exp_f32_e32 v153, v153
	v_add_f32_e32 v152, 1.0, v152
	v_add_f32_e32 v153, 1.0, v153
	v_rcp_f32_e32 v152, v152
	v_rcp_f32_e32 v153, v153
	s_nop 0
	v_pk_mul_f32 v[150:151], v[150:151], v[152:153]
	v_cvt_f32_i32_e32 v153, v19
	v_cvt_f32_i32_e32 v152, v18
	v_cvt_pk_bf16_f32 v149, v150, v151
	v_pk_mul_f32 v[152:153], v[154:155], v[152:153]
	s_nop 0
	v_mul_f32_e32 v154, 0xbfb8aa3b, v152
	v_mul_f32_e32 v155, 0xbfb8aa3b, v153
	v_exp_f32_e32 v154, v154
	v_exp_f32_e32 v155, v155
	v_add_f32_e32 v154, 1.0, v154
	v_add_f32_e32 v155, 1.0, v155
	v_rcp_f32_e32 v154, v154
	v_rcp_f32_e32 v155, v155
	s_nop 0
	v_pk_mul_f32 v[152:153], v[152:153], v[154:155]
	v_cvt_f32_i32_e32 v155, v21
	v_cvt_f32_i32_e32 v154, v20
	v_cvt_pk_bf16_f32 v150, v152, v153
	v_pk_mul_f32 v[154:155], v[156:157], v[154:155]
	s_nop 0
	v_mul_f32_e32 v156, 0xbfb8aa3b, v154
	v_mul_f32_e32 v157, 0xbfb8aa3b, v155
	v_exp_f32_e32 v156, v156
	v_exp_f32_e32 v157, v157
	v_add_f32_e32 v156, 1.0, v156
	v_add_f32_e32 v157, 1.0, v157
	v_rcp_f32_e32 v156, v156
	v_rcp_f32_e32 v157, v157
	s_nop 0
	v_pk_mul_f32 v[154:155], v[154:155], v[156:157]
	s_nop 0
	v_cvt_pk_bf16_f32 v151, v154, v155
	global_store_dwordx4 v[146:147], v[148:151], off offset:256 nt

.LBB0_368:
	v_pk_mul_f32 v[20:21], v[190:191], v[14:15] op_sel_hi:[0,1]
	v_pk_mul_f32 v[22:23], v[190:191], v[16:17] op_sel_hi:[0,1]
	v_pk_mul_f32 v[26:27], v[190:191], v[10:11] op_sel_hi:[0,1]
	v_pk_mul_f32 v[28:29], v[190:191], v[12:13] op_sel_hi:[0,1]
	v_lshl_add_u64 v[18:19], v[200:201], 1, s[0:1]
	v_pk_mul_f32 v[20:21], v[20:21], v[246:247]
	v_pk_mul_f32 v[22:23], v[22:23], v[244:245]
	v_pk_mul_f32 v[26:27], v[26:27], v[242:243]
	v_pk_mul_f32 v[28:29], v[28:29], v[240:241]
	v_lshl_add_u64 v[24:25], v[18:19], 0, v[248:249]
	v_cvt_pk_bf16_f32 v20, v20, v21
	v_cvt_pk_bf16_f32 v21, v22, v23
	v_cvt_pk_bf16_f32 v22, v26, v27
	v_cvt_pk_bf16_f32 v23, v28, v29
	global_store_dwordx4 v[24:25], v[20:23], off nt
	v_pk_mul_f32 v[26:27], v[190:191], v[2:3] op_sel_hi:[0,1]
	v_pk_mul_f32 v[28:29], v[190:191], v[4:5] op_sel_hi:[0,1]
	v_pk_mul_f32 v[20:21], v[190:191], v[6:7] op_sel_hi:[0,1]
	v_pk_mul_f32 v[22:23], v[190:191], v[8:9] op_sel_hi:[0,1]
	v_pk_mul_f32 v[20:21], v[20:21], v[238:239]
	v_pk_mul_f32 v[22:23], v[22:23], v[236:237]
	v_pk_mul_f32 v[26:27], v[26:27], v[234:235]
	v_pk_mul_f32 v[28:29], v[28:29], v[232:233]
	v_cvt_pk_bf16_f32 v20, v20, v21
	v_cvt_pk_bf16_f32 v21, v22, v23
	v_cvt_pk_bf16_f32 v22, v26, v27
	v_cvt_pk_bf16_f32 v23, v28, v29
	global_store_dwordx4 v[24:25], v[20:23], off offset:256 nt
	v_pk_mul_f32 v[26:27], v[188:189], v[10:11] op_sel_hi:[0,1]
	v_pk_mul_f32 v[28:29], v[188:189], v[12:13] op_sel_hi:[0,1]
	v_pk_mul_f32 v[20:21], v[188:189], v[14:15] op_sel_hi:[0,1]
	v_pk_mul_f32 v[22:23], v[188:189], v[16:17] op_sel_hi:[0,1]
	v_pk_mul_f32 v[20:21], v[20:21], v[228:229]
	v_pk_mul_f32 v[22:23], v[22:23], v[226:227]
	v_pk_mul_f32 v[26:27], v[26:27], v[224:225]
	v_pk_mul_f32 v[28:29], v[28:29], v[222:223]
	v_lshl_add_u64 v[24:25], v[18:19], 0, v[230:231]
	v_cvt_pk_bf16_f32 v20, v20, v21
	v_cvt_pk_bf16_f32 v21, v22, v23
	v_cvt_pk_bf16_f32 v22, v26, v27
	v_cvt_pk_bf16_f32 v23, v28, v29
	global_store_dwordx4 v[24:25], v[20:23], off nt
	v_pk_mul_f32 v[26:27], v[188:189], v[2:3] op_sel_hi:[0,1]
	v_pk_mul_f32 v[28:29], v[188:189], v[4:5] op_sel_hi:[0,1]
	v_pk_mul_f32 v[20:21], v[188:189], v[6:7] op_sel_hi:[0,1]
	v_pk_mul_f32 v[22:23], v[188:189], v[8:9] op_sel_hi:[0,1]
	v_pk_mul_f32 v[20:21], v[20:21], v[220:221]
	v_pk_mul_f32 v[22:23], v[22:23], v[218:219]
	v_pk_mul_f32 v[26:27], v[26:27], v[216:217]
	v_pk_mul_f32 v[28:29], v[28:29], v[212:213]
	v_cvt_pk_bf16_f32 v20, v20, v21
	v_cvt_pk_bf16_f32 v21, v22, v23
	v_cvt_pk_bf16_f32 v22, v26, v27
	v_cvt_pk_bf16_f32 v23, v28, v29
	global_store_dwordx4 v[24:25], v[20:23], off offset:256 nt
	v_pk_mul_f32 v[26:27], v[186:187], v[10:11] op_sel_hi:[0,1]
	v_pk_mul_f32 v[28:29], v[186:187], v[12:13] op_sel_hi:[0,1]
	v_pk_mul_f32 v[20:21], v[186:187], v[14:15] op_sel_hi:[0,1]
	v_pk_mul_f32 v[22:23], v[186:187], v[16:17] op_sel_hi:[0,1]
	v_pk_mul_f32 v[20:21], v[20:21], v[210:211]
	v_pk_mul_f32 v[22:23], v[22:23], v[208:209]
	v_pk_mul_f32 v[26:27], v[26:27], v[206:207]
	v_pk_mul_f32 v[28:29], v[28:29], v[160:161]
	v_lshl_add_u64 v[24:25], v[18:19], 0, v[214:215]
	v_cvt_pk_bf16_f32 v20, v20, v21
	v_cvt_pk_bf16_f32 v21, v22, v23
	v_cvt_pk_bf16_f32 v22, v26, v27
	v_cvt_pk_bf16_f32 v23, v28, v29
	global_store_dwordx4 v[24:25], v[20:23], off nt
	v_pk_mul_f32 v[26:27], v[186:187], v[2:3] op_sel_hi:[0,1]
	v_pk_mul_f32 v[28:29], v[186:187], v[4:5] op_sel_hi:[0,1]
	v_pk_mul_f32 v[20:21], v[186:187], v[6:7] op_sel_hi:[0,1]
	v_pk_mul_f32 v[22:23], v[186:187], v[8:9] op_sel_hi:[0,1]
	v_pk_mul_f32 v[20:21], v[20:21], v[158:159]
	v_pk_mul_f32 v[22:23], v[22:23], v[156:157]
	v_pk_mul_f32 v[26:27], v[26:27], v[154:155]
	v_pk_mul_f32 v[28:29], v[28:29], v[152:153]
	v_cvt_pk_bf16_f32 v20, v20, v21
	v_cvt_pk_bf16_f32 v21, v22, v23
	v_cvt_pk_bf16_f32 v22, v26, v27
	v_cvt_pk_bf16_f32 v23, v28, v29
	global_store_dwordx4 v[24:25], v[20:23], off offset:256 nt
	v_pk_mul_f32 v[26:27], v[182:183], v[10:11] op_sel_hi:[0,1]
	v_pk_mul_f32 v[28:29], v[182:183], v[12:13] op_sel_hi:[0,1]
	v_pk_mul_f32 v[20:21], v[182:183], v[14:15] op_sel_hi:[0,1]
	v_pk_mul_f32 v[22:23], v[182:183], v[16:17] op_sel_hi:[0,1]
	v_pk_mul_f32 v[20:21], v[20:21], v[144:145]
	v_pk_mul_f32 v[22:23], v[22:23], v[142:143]
	v_pk_mul_f32 v[26:27], v[26:27], v[140:141]
	v_pk_mul_f32 v[28:29], v[28:29], v[138:139]
	v_lshl_add_u64 v[24:25], v[18:19], 0, v[150:151]
	v_cvt_pk_bf16_f32 v20, v20, v21
	v_cvt_pk_bf16_f32 v21, v22, v23
	v_cvt_pk_bf16_f32 v22, v26, v27
	v_cvt_pk_bf16_f32 v23, v28, v29
	global_store_dwordx4 v[24:25], v[20:23], off nt
	v_pk_mul_f32 v[26:27], v[182:183], v[2:3] op_sel_hi:[0,1]
	v_pk_mul_f32 v[28:29], v[182:183], v[4:5] op_sel_hi:[0,1]
	v_pk_mul_f32 v[20:21], v[182:183], v[6:7] op_sel_hi:[0,1]
	v_pk_mul_f32 v[22:23], v[182:183], v[8:9] op_sel_hi:[0,1]
	v_pk_mul_f32 v[20:21], v[20:21], v[136:137]
	v_pk_mul_f32 v[22:23], v[22:23], v[134:135]
	v_pk_mul_f32 v[26:27], v[26:27], v[132:133]
	v_pk_mul_f32 v[28:29], v[28:29], v[130:131]
	v_cvt_pk_bf16_f32 v20, v20, v21
	v_cvt_pk_bf16_f32 v21, v22, v23
	v_cvt_pk_bf16_f32 v22, v26, v27
	v_cvt_pk_bf16_f32 v23, v28, v29
	global_store_dwordx4 v[24:25], v[20:23], off offset:256 nt
	v_pk_mul_f32 v[26:27], v[180:181], v[10:11] op_sel_hi:[0,1]
	v_pk_mul_f32 v[28:29], v[180:181], v[12:13] op_sel_hi:[0,1]
	v_pk_mul_f32 v[20:21], v[180:181], v[14:15] op_sel_hi:[0,1]
	v_pk_mul_f32 v[22:23], v[180:181], v[16:17] op_sel_hi:[0,1]
	v_pk_mul_f32 v[20:21], v[20:21], v[128:129]
	v_pk_mul_f32 v[22:23], v[22:23], v[126:127]
	v_pk_mul_f32 v[26:27], v[26:27], v[124:125]
	v_pk_mul_f32 v[28:29], v[28:29], v[120:121]
	v_lshl_add_u64 v[24:25], v[18:19], 0, v[148:149]
	v_cvt_pk_bf16_f32 v20, v20, v21
	v_cvt_pk_bf16_f32 v21, v22, v23
	v_cvt_pk_bf16_f32 v22, v26, v27
	v_cvt_pk_bf16_f32 v23, v28, v29
	global_store_dwordx4 v[24:25], v[20:23], off nt
	v_pk_mul_f32 v[26:27], v[180:181], v[2:3] op_sel_hi:[0,1]
	v_pk_mul_f32 v[28:29], v[180:181], v[4:5] op_sel_hi:[0,1]
	v_pk_mul_f32 v[20:21], v[180:181], v[6:7] op_sel_hi:[0,1]
	v_pk_mul_f32 v[22:23], v[180:181], v[8:9] op_sel_hi:[0,1]
	v_pk_mul_f32 v[20:21], v[20:21], v[118:119]
	v_pk_mul_f32 v[22:23], v[22:23], v[116:117]
	v_pk_mul_f32 v[26:27], v[26:27], v[114:115]
	v_pk_mul_f32 v[28:29], v[28:29], v[112:113]
	v_cvt_pk_bf16_f32 v20, v20, v21
	v_cvt_pk_bf16_f32 v21, v22, v23
	v_cvt_pk_bf16_f32 v22, v26, v27
	v_cvt_pk_bf16_f32 v23, v28, v29
	global_store_dwordx4 v[24:25], v[20:23], off offset:256 nt
	v_pk_mul_f32 v[26:27], v[178:179], v[10:11] op_sel_hi:[0,1]
	v_pk_mul_f32 v[28:29], v[178:179], v[12:13] op_sel_hi:[0,1]
	v_pk_mul_f32 v[20:21], v[178:179], v[14:15] op_sel_hi:[0,1]
	v_pk_mul_f32 v[22:23], v[178:179], v[16:17] op_sel_hi:[0,1]
	v_pk_mul_f32 v[20:21], v[20:21], v[110:111]
	v_pk_mul_f32 v[22:23], v[22:23], v[108:109]
	v_pk_mul_f32 v[26:27], v[26:27], v[106:107]
	v_pk_mul_f32 v[28:29], v[28:29], v[104:105]
	v_lshl_add_u64 v[24:25], v[18:19], 0, v[146:147]
	v_cvt_pk_bf16_f32 v20, v20, v21
	v_cvt_pk_bf16_f32 v21, v22, v23
	v_cvt_pk_bf16_f32 v22, v26, v27
	v_cvt_pk_bf16_f32 v23, v28, v29
	global_store_dwordx4 v[24:25], v[20:23], off nt
	v_pk_mul_f32 v[26:27], v[178:179], v[2:3] op_sel_hi:[0,1]
	v_pk_mul_f32 v[28:29], v[178:179], v[4:5] op_sel_hi:[0,1]
	v_pk_mul_f32 v[20:21], v[178:179], v[6:7] op_sel_hi:[0,1]
	v_pk_mul_f32 v[22:23], v[178:179], v[8:9] op_sel_hi:[0,1]
	v_pk_mul_f32 v[20:21], v[20:21], v[102:103]
	v_pk_mul_f32 v[22:23], v[22:23], v[98:99]
	v_pk_mul_f32 v[26:27], v[26:27], v[96:97]
	v_pk_mul_f32 v[28:29], v[28:29], v[94:95]
	v_cvt_pk_bf16_f32 v20, v20, v21
	v_cvt_pk_bf16_f32 v21, v22, v23
	v_cvt_pk_bf16_f32 v22, v26, v27
	v_cvt_pk_bf16_f32 v23, v28, v29
	global_store_dwordx4 v[24:25], v[20:23], off offset:256 nt
	v_pk_mul_f32 v[26:27], v[176:177], v[10:11] op_sel_hi:[0,1]
	v_pk_mul_f32 v[28:29], v[176:177], v[12:13] op_sel_hi:[0,1]
	v_pk_mul_f32 v[20:21], v[176:177], v[14:15] op_sel_hi:[0,1]
	v_pk_mul_f32 v[22:23], v[176:177], v[16:17] op_sel_hi:[0,1]
	v_pk_mul_f32 v[20:21], v[20:21], v[90:91]
	v_pk_mul_f32 v[22:23], v[22:23], v[88:89]
	v_pk_mul_f32 v[26:27], v[26:27], v[86:87]
	v_pk_mul_f32 v[28:29], v[28:29], v[84:85]
	v_lshl_add_u64 v[24:25], v[18:19], 0, v[92:93]
	v_cvt_pk_bf16_f32 v20, v20, v21
	v_cvt_pk_bf16_f32 v21, v22, v23
	v_cvt_pk_bf16_f32 v22, v26, v27
	v_cvt_pk_bf16_f32 v23, v28, v29
	global_store_dwordx4 v[24:25], v[20:23], off nt
	v_pk_mul_f32 v[26:27], v[176:177], v[2:3] op_sel_hi:[0,1]
	v_pk_mul_f32 v[28:29], v[176:177], v[4:5] op_sel_hi:[0,1]
	v_pk_mul_f32 v[20:21], v[176:177], v[6:7] op_sel_hi:[0,1]
	v_pk_mul_f32 v[22:23], v[176:177], v[8:9] op_sel_hi:[0,1]
	v_pk_mul_f32 v[20:21], v[20:21], v[82:83]
	v_pk_mul_f32 v[22:23], v[22:23], v[80:81]
	v_pk_mul_f32 v[26:27], v[26:27], v[78:79]
	v_pk_mul_f32 v[28:29], v[28:29], v[74:75]
	v_cvt_pk_bf16_f32 v20, v20, v21
	v_cvt_pk_bf16_f32 v21, v22, v23
	v_cvt_pk_bf16_f32 v22, v26, v27
	v_cvt_pk_bf16_f32 v23, v28, v29
	global_store_dwordx4 v[24:25], v[20:23], off offset:256 nt
	v_pk_mul_f32 v[24:25], v[174:175], v[10:11] op_sel_hi:[0,1]
	v_pk_mul_f32 v[26:27], v[174:175], v[12:13] op_sel_hi:[0,1]
	v_lshl_add_u64 v[22:23], v[18:19], 0, v[76:77]
	v_pk_mul_f32 v[18:19], v[174:175], v[14:15] op_sel_hi:[0,1]
	v_pk_mul_f32 v[20:21], v[174:175], v[16:17] op_sel_hi:[0,1]
	v_pk_mul_f32 v[18:19], v[18:19], v[72:73]
	v_pk_mul_f32 v[20:21], v[20:21], v[70:71]
	v_pk_mul_f32 v[24:25], v[24:25], v[68:69]
	v_pk_mul_f32 v[26:27], v[26:27], v[66:67]
	v_cvt_pk_bf16_f32 v18, v18, v19
	v_cvt_pk_bf16_f32 v19, v20, v21
	v_cvt_pk_bf16_f32 v20, v24, v25
	v_cvt_pk_bf16_f32 v21, v26, v27
	global_store_dwordx4 v[22:23], v[18:21], off nt
	v_pk_mul_f32 v[24:25], v[174:175], v[2:3] op_sel_hi:[0,1]
	v_pk_mul_f32 v[26:27], v[174:175], v[4:5] op_sel_hi:[0,1]
	v_pk_mul_f32 v[18:19], v[174:175], v[6:7] op_sel_hi:[0,1]
	v_pk_mul_f32 v[20:21], v[174:175], v[8:9] op_sel_hi:[0,1]
	v_pk_mul_f32 v[18:19], v[18:19], v[64:65]
	v_pk_mul_f32 v[20:21], v[20:21], v[62:63]
	v_pk_mul_f32 v[24:25], v[24:25], v[60:61]
	v_pk_mul_f32 v[26:27], v[26:27], v[58:59]
	v_cvt_pk_bf16_f32 v18, v18, v19
	v_cvt_pk_bf16_f32 v19, v20, v21
	v_cvt_pk_bf16_f32 v20, v24, v25
	v_cvt_pk_bf16_f32 v21, v26, v27
	global_store_dwordx4 v[22:23], v[18:21], off offset:256 nt
	s_cbranch_execnz .LBB0_354
.LBB0_369:
	s_nop 0
	v_lshlrev_b32_e32 v18, 4, v192
	v_and_b32_e32 v19, 8, v194
	s_mov_b32 s18, 0xfcf0
	v_and_or_b32 v18, v18, s18, v19
	v_lshlrev_b32_e32 v18, 3, v18
	global_load_dwordx4 v[34:37], v18, s[64:65] offset:48
	global_load_dwordx4 v[38:41], v18, s[64:65] offset:32
	global_load_dwordx4 v[42:45], v18, s[64:65] offset:16
	global_load_dwordx4 v[46:49], v18, s[64:65]
	v_cmp_gt_i32_e32 vcc, 2, v0
	v_lshlrev_b32_e32 v175, 1, v19
	s_mov_b32 s18, 0x1f9e0
	v_cndmask_b32_e64 v100, 1.0, -1.0, vcc
	v_cmp_lt_i32_e32 vcc, 1, v0
	v_lshlrev_b32_e32 v0, 5, v192
	v_and_or_b32 v0, v0, s18, v175
	v_lshlrev_b32_e32 v0, 2, v0
	v_lshl_add_u64 v[50:51], s[64:65], 0, v[0:1]
	global_load_dwordx4 v[18:21], v0, s[64:65] offset:2096
	global_load_dwordx4 v[22:25], v0, s[64:65] offset:2080
	global_load_dwordx4 v[26:29], v0, s[64:65] offset:2064
	global_load_dwordx4 v[30:33], v0, s[64:65] offset:2048
	v_mul_f32_e32 v0, v190, v14
	v_mul_f32_e32 v56, v0, v246
	v_mov_b32_e32 v0, v56
	v_mov_b32_e32 v54, v56
	s_nop 1
	v_permlane32_swap_b32_e32 v0, v54
	v_mul_f32_e32 v101, v190, v15
	v_cndmask_b32_e32 v246, v54, v0, vcc
	v_pk_mul_f32 v[192:193], v[100:101], v[246:247]
	v_mul_f32_e32 v177, v190, v16
	v_mov_b32_e32 v0, v193
	v_mov_b32_e32 v54, v193
	s_nop 1
	v_permlane32_swap_b32_e32 v0, v54
	v_cndmask_b32_e32 v0, v54, v0, vcc
	v_mul_f32_e32 v57, v100, v0
	v_mul_f32_e32 v179, v190, v17
	v_mov_b32_e32 v101, v179
	v_lshl_add_u64 v[122:123], v[200:201], 1, s[0:1]
	v_mul_f32_e32 v179, v190, v13
	s_movk_i32 s19, 0x1000
	v_lshl_add_u64 v[52:53], v[122:123], 0, v[248:249]
	s_mov_b64 s[30:31], 0x1000
	s_mov_b64 s[28:29], 0x1800
	v_lshl_add_u64 v[92:93], v[122:123], 0, v[92:93]
	s_waitcnt vmcnt(7)
	v_mov_b32_e32 v204, v35
	v_mov_b32_e32 v35, v37
	v_mov_b32_e32 v205, v36
	s_waitcnt vmcnt(4)
	v_mov_b32_e32 v54, v47
	v_mov_b32_e32 v47, v49
	v_mov_b32_e32 v55, v48
	v_pk_mul_f32 v[48:49], v[56:57], v[46:47]
	s_nop 0
	v_pk_fma_f32 v[56:57], v[54:55], v[192:193], v[48:49]
	v_mul_f32_e32 v192, v177, v244
	v_mov_b32_e32 v0, v192
	v_mov_b32_e32 v48, v192
	s_nop 1
	v_permlane32_swap_b32_e32 v0, v48
	v_cndmask_b32_e32 v244, v48, v0, vcc
	v_pk_mul_f32 v[194:195], v[100:101], v[244:245]
	v_mov_b32_e32 v49, v44
	v_mov_b32_e32 v0, v195
	v_mov_b32_e32 v48, v195
	s_nop 1
	v_permlane32_swap_b32_e32 v0, v48
	v_cndmask_b32_e32 v0, v48, v0, vcc
	v_mov_b32_e32 v48, v43
	v_mul_f32_e32 v193, v100, v0
	v_mov_b32_e32 v43, v45
	v_pk_mul_f32 v[44:45], v[192:193], v[42:43]
	v_mul_f32_e32 v0, v190, v10
	v_pk_fma_f32 v[44:45], v[48:49], v[194:195], v[44:45]
	v_mul_f32_e32 v194, v0, v242
	v_mov_b32_e32 v0, v194
	v_mov_b32_e32 v181, v194
	s_nop 1
	v_permlane32_swap_b32_e32 v0, v181
	v_mul_f32_e32 v101, v190, v11
	v_cndmask_b32_e32 v242, v181, v0, vcc
	v_pk_mul_f32 v[200:201], v[100:101], v[242:243]
	v_mul_f32_e32 v177, v190, v12
	v_mov_b32_e32 v0, v201
	v_mov_b32_e32 v101, v201
	s_nop 1
	v_permlane32_swap_b32_e32 v0, v101
	v_cndmask_b32_e32 v0, v101, v0, vcc
	v_mov_b32_e32 v192, v39
	v_mul_f32_e32 v195, v100, v0
	v_mov_b32_e32 v39, v41
	v_mov_b32_e32 v193, v40
	v_pk_mul_f32 v[40:41], v[194:195], v[38:39]
	v_mul_f32_e32 v194, v177, v240
	v_mov_b32_e32 v0, v194
	v_mov_b32_e32 v101, v194
	s_nop 1
	v_permlane32_swap_b32_e32 v0, v101
	v_cndmask_b32_e32 v240, v101, v0, vcc
	v_mov_b32_e32 v101, v179
	v_pk_fma_f32 v[40:41], v[192:193], v[200:201], v[40:41]
	v_pk_mul_f32 v[200:201], v[100:101], v[240:241]
	v_cvt_pk_bf16_f32 v202, v40, v41
	v_mov_b32_e32 v0, v201
	v_mov_b32_e32 v101, v201
	s_nop 1
	v_permlane32_swap_b32_e32 v0, v101
	v_cndmask_b32_e32 v0, v101, v0, vcc
	v_mul_f32_e32 v195, v100, v0
	v_pk_mul_f32 v[36:37], v[194:195], v[34:35]
	v_mul_f32_e32 v0, v190, v6
	v_pk_fma_f32 v[36:37], v[204:205], v[200:201], v[36:37]
	v_mul_f32_e32 v101, v190, v7
	v_cvt_pk_bf16_f32 v203, v36, v37
	v_mul_f32_e32 v36, v0, v238
	v_mov_b32_e32 v0, v36
	v_mov_b32_e32 v37, v36
	s_nop 1
	v_permlane32_swap_b32_e32 v0, v37
	v_cndmask_b32_e32 v238, v37, v0, vcc
	v_pk_mul_f32 v[40:41], v[100:101], v[238:239]
	v_cvt_pk_bf16_f32 v201, v44, v45
	v_mov_b32_e32 v0, v41
	v_mov_b32_e32 v37, v41
	s_nop 1
	v_permlane32_swap_b32_e32 v0, v37
	v_cndmask_b32_e32 v0, v37, v0, vcc
	v_mul_f32_e32 v37, v100, v0
	v_mul_f32_e32 v44, v190, v8
	v_pk_mul_f32 v[36:37], v[36:37], v[46:47]
	v_mul_f32_e32 v45, v190, v9
	v_pk_fma_f32 v[36:37], v[54:55], v[40:41], v[36:37]
	v_mul_f32_e32 v40, v44, v236
	v_mov_b32_e32 v0, v40
	v_mov_b32_e32 v41, v40
	s_nop 1
	v_permlane32_swap_b32_e32 v0, v41
	v_cndmask_b32_e32 v236, v41, v0, vcc
	v_mov_b32_e32 v101, v45
	v_pk_mul_f32 v[44:45], v[100:101], v[236:237]
	v_mul_f32_e32 v101, v190, v3
	v_mov_b32_e32 v0, v45
	v_mov_b32_e32 v41, v45
	s_nop 1
	v_permlane32_swap_b32_e32 v0, v41
	v_cndmask_b32_e32 v0, v41, v0, vcc
	v_mul_f32_e32 v41, v100, v0
	v_mul_f32_e32 v0, v190, v2
	v_pk_mul_f32 v[40:41], v[40:41], v[42:43]
	v_mul_f32_e32 v42, v0, v234
	v_mov_b32_e32 v0, v42
	v_mov_b32_e32 v43, v42
	s_nop 1
	v_permlane32_swap_b32_e32 v0, v43
	v_cndmask_b32_e32 v234, v43, v0, vcc
	v_pk_fma_f32 v[40:41], v[48:49], v[44:45], v[40:41]
	v_pk_mul_f32 v[44:45], v[100:101], v[234:235]
	v_mul_f32_e32 v46, v190, v4
	v_mov_b32_e32 v0, v45
	v_mov_b32_e32 v43, v45
	s_nop 1
	v_permlane32_swap_b32_e32 v0, v43
	v_cndmask_b32_e32 v0, v43, v0, vcc
	v_mul_f32_e32 v43, v100, v0
	v_pk_mul_f32 v[38:39], v[42:43], v[38:39]
	v_mul_f32_e32 v42, v46, v232
	v_mov_b32_e32 v0, v42
	v_mov_b32_e32 v43, v42
	v_mul_f32_e32 v47, v190, v5
	s_nop 0
	v_permlane32_swap_b32_e32 v0, v43
	v_cndmask_b32_e32 v232, v43, v0, vcc
	v_mov_b32_e32 v101, v47
	v_pk_fma_f32 v[38:39], v[192:193], v[44:45], v[38:39]
	v_pk_mul_f32 v[44:45], v[100:101], v[232:233]
	v_mul_f32_e32 v101, v188, v15
	v_mov_b32_e32 v0, v45
	v_mov_b32_e32 v43, v45
	s_nop 1
	v_permlane32_swap_b32_e32 v0, v43
	v_cndmask_b32_e32 v0, v43, v0, vcc
	v_mul_f32_e32 v43, v100, v0
	v_mul_f32_e32 v0, v188, v14
	v_mul_f32_e32 v46, v0, v228
	v_mov_b32_e32 v0, v46
	v_mov_b32_e32 v47, v46
	s_nop 1
	v_permlane32_swap_b32_e32 v0, v47
	v_cndmask_b32_e32 v228, v47, v0, vcc
	v_pk_mul_f32 v[48:49], v[100:101], v[228:229]
	v_pk_mul_f32 v[34:35], v[42:43], v[34:35]
	v_mov_b32_e32 v0, v49
	v_mov_b32_e32 v47, v49
	s_nop 1
	v_permlane32_swap_b32_e32 v0, v47
	v_pk_fma_f32 v[42:43], v[204:205], v[44:45], v[34:35]
	v_cndmask_b32_e32 v0, v47, v0, vcc
	v_cvt_pk_bf16_f32 v200, v56, v57
	v_cvt_pk_bf16_f32 v34, v36, v37
	v_cvt_pk_bf16_f32 v35, v40, v41
	v_cvt_pk_bf16_f32 v36, v38, v39
	v_cvt_pk_bf16_f32 v37, v42, v43
	v_add_co_u32_e64 v190, s[0:1], s19, v50
	v_mul_f32_e32 v177, v188, v16
	s_waitcnt vmcnt(0)
	v_mov_b32_e32 v192, v31
	v_mul_f32_e32 v47, v100, v0
	v_mov_b32_e32 v31, v33
	global_store_dwordx4 v[52:53], v[200:203], off nt
	global_store_dwordx4 v[52:53], v[34:37], off offset:256 nt
	v_lshl_add_u64 v[42:43], v[50:51], 0, s[30:31]
	v_addc_co_u32_e64 v191, s[0:1], 0, v51, s[0:1]
	v_mov_b32_e32 v193, v32
	v_pk_mul_f32 v[32:33], v[46:47], v[30:31]
	v_mul_f32_e32 v46, v177, v226
	global_load_dwordx4 v[54:57], v[190:191], off
	global_load_dwordx4 v[34:37], v[42:43], off offset:48
	global_load_dwordx4 v[38:41], v[42:43], off offset:32
	s_nop 0
	global_load_dwordx4 v[42:45], v[42:43], off offset:16
	v_mov_b32_e32 v0, v46
	v_mov_b32_e32 v47, v46
	v_mul_f32_e32 v179, v188, v17
	s_nop 0
	v_permlane32_swap_b32_e32 v0, v47
	v_cndmask_b32_e32 v226, v47, v0, vcc
	v_mov_b32_e32 v101, v179
	v_pk_fma_f32 v[32:33], v[192:193], v[48:49], v[32:33]
	v_pk_mul_f32 v[48:49], v[100:101], v[226:227]
	v_mov_b32_e32 v194, v27
	v_mov_b32_e32 v0, v49
	v_mov_b32_e32 v47, v49
	s_nop 1
	v_permlane32_swap_b32_e32 v0, v47
	v_cndmask_b32_e32 v0, v47, v0, vcc
	v_mul_f32_e32 v47, v100, v0
	v_mov_b32_e32 v27, v29
	v_mul_f32_e32 v0, v188, v10
	v_mov_b32_e32 v195, v28
	v_pk_mul_f32 v[28:29], v[46:47], v[26:27]
	v_mul_f32_e32 v46, v0, v224
	v_mov_b32_e32 v0, v46
	v_mov_b32_e32 v47, v46
	s_nop 1
	v_permlane32_swap_b32_e32 v0, v47
	v_mul_f32_e32 v101, v188, v11
	v_cndmask_b32_e32 v224, v47, v0, vcc
	v_pk_fma_f32 v[28:29], v[194:195], v[48:49], v[28:29]
	v_pk_mul_f32 v[48:49], v[100:101], v[224:225]
	v_mul_f32_e32 v177, v188, v12
	v_mov_b32_e32 v0, v49
	v_mov_b32_e32 v47, v49
	s_nop 1
	v_permlane32_swap_b32_e32 v0, v47
	v_cndmask_b32_e32 v0, v47, v0, vcc
	v_mov_b32_e32 v200, v23
	v_mul_f32_e32 v47, v100, v0
	v_mov_b32_e32 v23, v25
	v_mov_b32_e32 v201, v24
	v_pk_mul_f32 v[24:25], v[46:47], v[22:23]
	v_mul_f32_e32 v46, v177, v222
	v_mov_b32_e32 v0, v46
	v_mov_b32_e32 v47, v46
	v_mul_f32_e32 v179, v188, v13
	s_nop 0
	v_permlane32_swap_b32_e32 v0, v47
	v_cndmask_b32_e32 v222, v47, v0, vcc
	v_mov_b32_e32 v101, v179
	v_pk_fma_f32 v[24:25], v[200:201], v[48:49], v[24:25]
	v_pk_mul_f32 v[48:49], v[100:101], v[222:223]
	v_mov_b32_e32 v202, v19
	v_mov_b32_e32 v0, v49
	v_mov_b32_e32 v47, v49
	s_nop 1
	v_permlane32_swap_b32_e32 v0, v47
	v_cndmask_b32_e32 v0, v47, v0, vcc
	v_mul_f32_e32 v47, v100, v0
	v_mov_b32_e32 v19, v21
	v_mov_b32_e32 v203, v20
	v_pk_mul_f32 v[20:21], v[46:47], v[18:19]
	v_mul_f32_e32 v0, v188, v6
	v_pk_fma_f32 v[20:21], v[202:203], v[48:49], v[20:21]
	v_mul_f32_e32 v101, v188, v7
	v_cvt_pk_bf16_f32 v49, v20, v21
	v_mul_f32_e32 v20, v0, v220
	v_mov_b32_e32 v0, v20
	v_mov_b32_e32 v21, v20
	s_nop 1
	v_permlane32_swap_b32_e32 v0, v21
	v_cndmask_b32_e32 v220, v21, v0, vcc
	v_cvt_pk_bf16_f32 v48, v24, v25
	v_pk_mul_f32 v[24:25], v[100:101], v[220:221]
	v_cvt_pk_bf16_f32 v47, v28, v29
	v_mov_b32_e32 v0, v25
	v_mov_b32_e32 v21, v25
	s_nop 1
	v_permlane32_swap_b32_e32 v0, v21
	v_cndmask_b32_e32 v0, v21, v0, vcc
	v_mul_f32_e32 v21, v100, v0
	v_mul_f32_e32 v28, v188, v8
	v_pk_mul_f32 v[20:21], v[20:21], v[30:31]
	v_mul_f32_e32 v29, v188, v9
	v_pk_fma_f32 v[20:21], v[192:193], v[24:25], v[20:21]
	v_mul_f32_e32 v24, v28, v218
	v_mov_b32_e32 v0, v24
	v_mov_b32_e32 v25, v24
	s_nop 1
	v_permlane32_swap_b32_e32 v0, v25
	v_cndmask_b32_e32 v218, v25, v0, vcc
	v_mov_b32_e32 v101, v29
	v_pk_mul_f32 v[28:29], v[100:101], v[218:219]
	v_mul_f32_e32 v101, v188, v3
	v_mov_b32_e32 v0, v29
	v_mov_b32_e32 v25, v29
	s_nop 1
	v_permlane32_swap_b32_e32 v0, v25
	v_cndmask_b32_e32 v0, v25, v0, vcc
	v_mul_f32_e32 v25, v100, v0
	v_mul_f32_e32 v0, v188, v2
	v_pk_mul_f32 v[24:25], v[24:25], v[26:27]
	v_mul_f32_e32 v26, v0, v216
	v_mov_b32_e32 v0, v26
	v_mov_b32_e32 v27, v26
	s_nop 1
	v_permlane32_swap_b32_e32 v0, v27
	v_cndmask_b32_e32 v216, v27, v0, vcc
	v_pk_fma_f32 v[24:25], v[194:195], v[28:29], v[24:25]
	v_pk_mul_f32 v[28:29], v[100:101], v[216:217]
	v_mul_f32_e32 v30, v188, v4
	v_mov_b32_e32 v0, v29
	v_mov_b32_e32 v27, v29
	s_nop 1
	v_permlane32_swap_b32_e32 v0, v27
	v_cndmask_b32_e32 v0, v27, v0, vcc
	v_mul_f32_e32 v27, v100, v0
	v_pk_mul_f32 v[22:23], v[26:27], v[22:23]
	v_mul_f32_e32 v26, v30, v212
	v_mov_b32_e32 v0, v26
	v_mov_b32_e32 v27, v26
	v_mul_f32_e32 v31, v188, v5
	s_nop 0
	v_permlane32_swap_b32_e32 v0, v27
	v_cndmask_b32_e32 v212, v27, v0, vcc
	v_mov_b32_e32 v101, v31
	v_pk_fma_f32 v[22:23], v[200:201], v[28:29], v[22:23]
	v_pk_mul_f32 v[28:29], v[100:101], v[212:213]
	v_lshl_add_u64 v[52:53], v[122:123], 0, v[230:231]
	v_mov_b32_e32 v0, v29
	v_mov_b32_e32 v27, v29
	s_nop 1
	v_permlane32_swap_b32_e32 v0, v27
	v_cndmask_b32_e32 v0, v27, v0, vcc
	v_mul_f32_e32 v27, v100, v0
	v_pk_mul_f32 v[18:19], v[26:27], v[18:19]
	v_cvt_pk_bf16_f32 v46, v32, v33
	v_pk_fma_f32 v[26:27], v[202:203], v[28:29], v[18:19]
	v_cvt_pk_bf16_f32 v18, v20, v21
	v_cvt_pk_bf16_f32 v19, v24, v25
	v_cvt_pk_bf16_f32 v20, v22, v23
	v_cvt_pk_bf16_f32 v21, v26, v27
	global_store_dwordx4 v[52:53], v[46:49], off nt
	global_store_dwordx4 v[52:53], v[18:21], off offset:256 nt
	v_lshl_add_u64 v[22:23], v[50:51], 0, s[28:29]
	v_mul_f32_e32 v0, v186, v14
	global_load_dwordx4 v[50:53], v[190:191], off offset:2048
	global_load_dwordx4 v[18:21], v[22:23], off offset:48
	global_load_dwordx4 v[26:29], v[22:23], off offset:32
	global_load_dwordx4 v[46:49], v[22:23], off offset:16
	v_mul_f32_e32 v22, v0, v210
	v_mov_b32_e32 v0, v22
	v_mov_b32_e32 v23, v22
	s_nop 1
	v_permlane32_swap_b32_e32 v0, v23
	v_mul_f32_e32 v101, v186, v15
	v_cndmask_b32_e32 v210, v23, v0, vcc
	v_pk_mul_f32 v[24:25], v[100:101], v[210:211]
	s_waitcnt vmcnt(9)
	v_mov_b32_e32 v32, v55
	v_mov_b32_e32 v0, v25
	v_mov_b32_e32 v23, v25
	s_nop 1
	v_permlane32_swap_b32_e32 v0, v23
	v_cndmask_b32_e32 v0, v23, v0, vcc
	v_mul_f32_e32 v23, v100, v0
	v_mov_b32_e32 v55, v57
	v_mul_f32_e32 v177, v186, v16
	v_mov_b32_e32 v33, v56
	v_pk_mul_f32 v[22:23], v[22:23], v[54:55]
	v_mul_f32_e32 v179, v186, v17
	v_pk_fma_f32 v[22:23], v[32:33], v[24:25], v[22:23]
	v_mul_f32_e32 v24, v177, v208
	v_mov_b32_e32 v0, v24
	v_mov_b32_e32 v25, v24
	s_nop 1
	v_permlane32_swap_b32_e32 v0, v25
	v_cndmask_b32_e32 v208, v25, v0, vcc
	v_mov_b32_e32 v101, v179
	v_pk_mul_f32 v[56:57], v[100:101], v[208:209]
	s_waitcnt vmcnt(6)
	v_mov_b32_e32 v189, v44
	v_mov_b32_e32 v0, v57
	v_mov_b32_e32 v25, v57
	s_nop 1
	v_permlane32_swap_b32_e32 v0, v25
	v_cndmask_b32_e32 v0, v25, v0, vcc
	v_mul_f32_e32 v25, v100, v0
	v_mul_f32_e32 v0, v186, v10
	v_mul_f32_e32 v44, v0, v206
	v_mov_b32_e32 v188, v43
	v_mov_b32_e32 v43, v45
	v_mov_b32_e32 v0, v44
	v_mov_b32_e32 v45, v44
	s_nop 1
	v_permlane32_swap_b32_e32 v0, v45
	v_pk_mul_f32 v[24:25], v[24:25], v[42:43]
	v_mul_f32_e32 v101, v186, v11
	v_cndmask_b32_e32 v206, v45, v0, vcc
	v_pk_fma_f32 v[24:25], v[188:189], v[56:57], v[24:25]
	v_pk_mul_f32 v[56:57], v[100:101], v[206:207]
	v_mul_f32_e32 v177, v186, v12
	v_mov_b32_e32 v0, v57
	v_mov_b32_e32 v45, v57
	s_nop 1
	v_permlane32_swap_b32_e32 v0, v45
	v_cndmask_b32_e32 v0, v45, v0, vcc
	v_mov_b32_e32 v190, v39
	v_mul_f32_e32 v45, v100, v0
	v_mov_b32_e32 v39, v41
	v_mov_b32_e32 v191, v40
	v_pk_mul_f32 v[40:41], v[44:45], v[38:39]
	v_mul_f32_e32 v44, v177, v160
	v_mov_b32_e32 v0, v44
	v_mov_b32_e32 v45, v44
	v_mul_f32_e32 v179, v186, v13
	s_nop 0
	v_permlane32_swap_b32_e32 v0, v45
	v_cndmask_b32_e32 v160, v45, v0, vcc
	v_mov_b32_e32 v101, v179
	v_pk_fma_f32 v[40:41], v[190:191], v[56:57], v[40:41]
	v_pk_mul_f32 v[56:57], v[100:101], v[160:161]
	v_mov_b32_e32 v160, v35
	v_mov_b32_e32 v0, v57
	v_mov_b32_e32 v45, v57
	s_nop 1
	v_permlane32_swap_b32_e32 v0, v45
	v_cndmask_b32_e32 v0, v45, v0, vcc
	v_mul_f32_e32 v45, v100, v0
	v_mov_b32_e32 v35, v37
	v_mov_b32_e32 v161, v36
	v_pk_mul_f32 v[36:37], v[44:45], v[34:35]
	v_lshl_add_u64 v[30:31], v[122:123], 0, v[214:215]
	v_pk_fma_f32 v[36:37], v[160:161], v[56:57], v[36:37]
	v_cvt_pk_bf16_f32 v22, v22, v23
	v_cvt_pk_bf16_f32 v23, v24, v25
	v_cvt_pk_bf16_f32 v24, v40, v41
	v_cvt_pk_bf16_f32 v25, v36, v37
	v_mul_f32_e32 v0, v186, v6
	global_store_dwordx4 v[30:31], v[22:25], off nt
	v_mul_f32_e32 v101, v186, v7
	v_mul_f32_e32 v36, v186, v8
	v_mul_f32_e32 v22, v0, v158
	v_mov_b32_e32 v0, v22
	v_mov_b32_e32 v23, v22
	s_nop 1
	v_permlane32_swap_b32_e32 v0, v23
	v_cndmask_b32_e32 v158, v23, v0, vcc
	v_pk_mul_f32 v[24:25], v[100:101], v[158:159]
	v_mul_f32_e32 v37, v186, v9
	v_mov_b32_e32 v0, v25
	v_mov_b32_e32 v23, v25
	s_nop 1
	v_permlane32_swap_b32_e32 v0, v23
	v_cndmask_b32_e32 v0, v23, v0, vcc
	v_mul_f32_e32 v23, v100, v0
	v_pk_mul_f32 v[22:23], v[22:23], v[54:55]
	v_mov_b32_e32 v101, v37
	v_pk_fma_f32 v[22:23], v[32:33], v[24:25], v[22:23]
	v_mul_f32_e32 v24, v36, v156
	v_mov_b32_e32 v0, v24
	v_mov_b32_e32 v25, v24
	s_nop 1
	v_permlane32_swap_b32_e32 v0, v25
	v_cndmask_b32_e32 v156, v25, v0, vcc
	v_pk_mul_f32 v[32:33], v[100:101], v[156:157]
	v_mul_f32_e32 v101, v186, v3
	v_mov_b32_e32 v0, v33
	v_mov_b32_e32 v25, v33
	s_nop 1
	v_permlane32_swap_b32_e32 v0, v25
	v_cndmask_b32_e32 v0, v25, v0, vcc
	v_mul_f32_e32 v25, v100, v0
	v_pk_mul_f32 v[24:25], v[24:25], v[42:43]
	v_mul_f32_e32 v0, v186, v2
	v_pk_fma_f32 v[24:25], v[188:189], v[32:33], v[24:25]
	v_mul_f32_e32 v32, v0, v154
	v_mov_b32_e32 v0, v32
	v_mov_b32_e32 v33, v32
	s_nop 1
	v_permlane32_swap_b32_e32 v0, v33
	v_cndmask_b32_e32 v154, v33, v0, vcc
	v_pk_mul_f32 v[36:37], v[100:101], v[154:155]
	v_mul_f32_e32 v40, v186, v4
	v_mov_b32_e32 v0, v37
	v_mov_b32_e32 v33, v37
	s_nop 1
	v_permlane32_swap_b32_e32 v0, v33
	v_cndmask_b32_e32 v0, v33, v0, vcc
	v_mul_f32_e32 v33, v100, v0
	v_pk_mul_f32 v[32:33], v[32:33], v[38:39]
	v_mul_f32_e32 v41, v186, v5
	v_pk_fma_f32 v[32:33], v[190:191], v[36:37], v[32:33]
	v_mul_f32_e32 v36, v40, v152
	v_mov_b32_e32 v0, v36
	v_mov_b32_e32 v37, v36
	s_nop 1
	v_permlane32_swap_b32_e32 v0, v37
	v_cndmask_b32_e32 v152, v37, v0, vcc
	v_mov_b32_e32 v101, v41
	v_pk_mul_f32 v[38:39], v[100:101], v[152:153]
	v_cvt_pk_bf16_f32 v22, v22, v23
	v_mov_b32_e32 v0, v39
	v_mov_b32_e32 v37, v39
	s_nop 1
	v_permlane32_swap_b32_e32 v0, v37
	v_cndmask_b32_e32 v0, v37, v0, vcc
	v_mul_f32_e32 v37, v100, v0
	v_pk_mul_f32 v[34:35], v[36:37], v[34:35]
	v_cvt_pk_bf16_f32 v23, v24, v25
	v_pk_fma_f32 v[34:35], v[160:161], v[38:39], v[34:35]
	v_mul_f32_e32 v101, v182, v15
	v_cvt_pk_bf16_f32 v25, v34, v35
	v_mul_f32_e32 v34, v182, v14
	v_mul_f32_e32 v34, v34, v144
	v_mov_b32_e32 v35, v34
	v_mov_b32_e32 v36, v34
	s_nop 1
	v_permlane32_swap_b32_e32 v35, v36
	v_cndmask_b32_e32 v144, v36, v35, vcc
	v_pk_mul_f32 v[36:37], v[100:101], v[144:145]
	s_waitcnt vmcnt(4)
	v_mov_b32_e32 v144, v51
	v_mov_b32_e32 v35, v37
	v_mov_b32_e32 v101, v37
	s_nop 1
	v_permlane32_swap_b32_e32 v35, v101
	v_cndmask_b32_e32 v35, v101, v35, vcc
	v_mul_f32_e32 v35, v100, v35
	v_mov_b32_e32 v51, v53
	v_lshl_add_u64 v[56:57], v[122:123], 0, v[150:151]
	v_lshlrev_b32_e32 v0, 5, v184
	v_mul_f32_e32 v150, v182, v16
	v_mov_b32_e32 v145, v52
	v_pk_mul_f32 v[34:35], v[34:35], v[50:51]
	v_cvt_pk_bf16_f32 v24, v32, v33
	v_and_or_b32 v0, v0, s18, v175
	v_pk_fma_f32 v[34:35], v[144:145], v[36:37], v[34:35]
	v_mul_f32_e32 v36, v150, v142
	global_store_dwordx4 v[30:31], v[22:25], off offset:256 nt
	v_lshlrev_b32_e32 v0, 2, v0
	v_mov_b32_e32 v37, v36
	v_mov_b32_e32 v52, v36
	global_load_dwordx4 v[22:25], v0, s[64:65] offset:48
	global_load_dwordx4 v[30:33], v0, s[64:65] offset:32
	global_load_dwordx4 v[38:41], v0, s[64:65] offset:16
	global_load_dwordx4 v[42:45], v0, s[64:65]
	v_mul_f32_e32 v151, v182, v17
	v_permlane32_swap_b32_e32 v37, v52
	v_cndmask_b32_e32 v142, v52, v37, vcc
	v_mov_b32_e32 v101, v151
	v_pk_mul_f32 v[52:53], v[100:101], v[142:143]
	s_waitcnt vmcnt(6)
	v_mov_b32_e32 v142, v47
	v_mov_b32_e32 v37, v53
	v_mov_b32_e32 v101, v53
	s_nop 1
	v_permlane32_swap_b32_e32 v37, v101
	v_cndmask_b32_e32 v37, v101, v37, vcc
	v_mov_b32_e32 v143, v48
	v_mul_f32_e32 v37, v100, v37
	v_mov_b32_e32 v47, v49
	v_mul_f32_e32 v48, v182, v10
	v_pk_mul_f32 v[36:37], v[36:37], v[46:47]
	v_mul_f32_e32 v48, v48, v140
	v_pk_fma_f32 v[36:37], v[142:143], v[52:53], v[36:37]
	v_mov_b32_e32 v49, v48
	v_mov_b32_e32 v52, v48
	s_nop 1
	v_permlane32_swap_b32_e32 v49, v52
	v_mul_f32_e32 v101, v182, v11
	v_cndmask_b32_e32 v140, v52, v49, vcc
	v_pk_mul_f32 v[52:53], v[100:101], v[140:141]
	v_mul_f32_e32 v150, v182, v12
	v_mov_b32_e32 v49, v53
	v_mov_b32_e32 v101, v53
	s_nop 1
	v_permlane32_swap_b32_e32 v49, v101
	v_cndmask_b32_e32 v49, v101, v49, vcc
	v_mov_b32_e32 v140, v27
	v_mul_f32_e32 v49, v100, v49
	v_mov_b32_e32 v27, v29
	v_mov_b32_e32 v141, v28
	v_pk_mul_f32 v[28:29], v[48:49], v[26:27]
	v_mul_f32_e32 v48, v150, v138
	v_pk_fma_f32 v[28:29], v[140:141], v[52:53], v[28:29]
	v_mov_b32_e32 v49, v48
	v_mov_b32_e32 v52, v48
	v_mul_f32_e32 v151, v182, v13
	s_nop 0
	v_permlane32_swap_b32_e32 v49, v52
	v_cndmask_b32_e32 v138, v52, v49, vcc
	v_mov_b32_e32 v101, v151
	v_pk_mul_f32 v[52:53], v[100:101], v[138:139]
	v_mov_b32_e32 v138, v19
	v_mov_b32_e32 v49, v53
	v_mov_b32_e32 v101, v53
	s_nop 1
	v_permlane32_swap_b32_e32 v49, v101
	v_cndmask_b32_e32 v49, v101, v49, vcc
	v_mul_f32_e32 v49, v100, v49
	v_mov_b32_e32 v19, v21
	v_mov_b32_e32 v139, v20
	v_pk_mul_f32 v[20:21], v[48:49], v[18:19]
	v_cvt_pk_bf16_f32 v34, v34, v35
	v_pk_fma_f32 v[20:21], v[138:139], v[52:53], v[20:21]
	v_cvt_pk_bf16_f32 v35, v36, v37
	v_cvt_pk_bf16_f32 v37, v20, v21
	v_mul_f32_e32 v20, v182, v6
	v_mul_f32_e32 v20, v20, v136
	v_cvt_pk_bf16_f32 v36, v28, v29
	v_mov_b32_e32 v21, v20
	v_mov_b32_e32 v28, v20
	s_nop 1
	v_permlane32_swap_b32_e32 v21, v28
	v_mul_f32_e32 v101, v182, v7
	v_cndmask_b32_e32 v136, v28, v21, vcc
	v_pk_mul_f32 v[28:29], v[100:101], v[136:137]
	global_store_dwordx4 v[56:57], v[34:37], off nt
	v_mov_b32_e32 v21, v29
	v_lshl_add_u64 v[54:55], s[64:65], 0, v[0:1]
	v_mov_b32_e32 v36, v29
	s_nop 1
	v_permlane32_swap_b32_e32 v21, v36
	v_cndmask_b32_e32 v21, v36, v21, vcc
	v_mul_f32_e32 v21, v100, v21
	v_mul_f32_e32 v34, v182, v8
	v_pk_mul_f32 v[20:21], v[20:21], v[50:51]
	v_mul_f32_e32 v35, v182, v9
	v_pk_fma_f32 v[20:21], v[144:145], v[28:29], v[20:21]
	v_mul_f32_e32 v28, v34, v134
	v_mov_b32_e32 v29, v28
	v_mov_b32_e32 v34, v28
	s_nop 1
	v_permlane32_swap_b32_e32 v29, v34
	v_cndmask_b32_e32 v134, v34, v29, vcc
	v_mov_b32_e32 v101, v35
	v_pk_mul_f32 v[34:35], v[100:101], v[134:135]
	v_mul_f32_e32 v101, v182, v3
	v_mov_b32_e32 v29, v35
	v_mov_b32_e32 v36, v35
	s_nop 1
	v_permlane32_swap_b32_e32 v29, v36
	v_cndmask_b32_e32 v29, v36, v29, vcc
	v_mul_f32_e32 v29, v100, v29
	v_pk_mul_f32 v[28:29], v[28:29], v[46:47]
	v_mul_f32_e32 v46, v182, v4
	v_pk_fma_f32 v[28:29], v[142:143], v[34:35], v[28:29]
	v_mul_f32_e32 v34, v182, v2
	v_mul_f32_e32 v34, v34, v132
	v_mov_b32_e32 v35, v34
	v_mov_b32_e32 v36, v34
	s_nop 1
	v_permlane32_swap_b32_e32 v35, v36
	v_cndmask_b32_e32 v132, v36, v35, vcc
	v_pk_mul_f32 v[36:37], v[100:101], v[132:133]
	v_mul_f32_e32 v47, v182, v5
	v_mov_b32_e32 v35, v37
	v_mov_b32_e32 v48, v37
	s_nop 1
	v_permlane32_swap_b32_e32 v35, v48
	v_cndmask_b32_e32 v35, v48, v35, vcc
	v_mul_f32_e32 v35, v100, v35
	v_pk_mul_f32 v[26:27], v[34:35], v[26:27]
	v_mul_f32_e32 v34, v46, v130
	v_pk_fma_f32 v[26:27], v[140:141], v[36:37], v[26:27]
	v_mov_b32_e32 v35, v34
	v_mov_b32_e32 v36, v34
	s_nop 1
	v_permlane32_swap_b32_e32 v35, v36
	v_cndmask_b32_e32 v130, v36, v35, vcc
	v_mov_b32_e32 v101, v47
	v_pk_mul_f32 v[36:37], v[100:101], v[130:131]
	v_mul_f32_e32 v101, v180, v15
	v_mov_b32_e32 v35, v37
	v_mov_b32_e32 v46, v37
	s_nop 1
	v_permlane32_swap_b32_e32 v35, v46
	v_cndmask_b32_e32 v35, v46, v35, vcc
	v_mul_f32_e32 v35, v100, v35
	v_pk_mul_f32 v[18:19], v[34:35], v[18:19]
	v_mul_f32_e32 v130, v180, v16
	v_pk_fma_f32 v[34:35], v[138:139], v[36:37], v[18:19]
	v_cvt_pk_bf16_f32 v18, v20, v21
	v_cvt_pk_bf16_f32 v19, v28, v29
	v_cvt_pk_bf16_f32 v20, v26, v27
	v_cvt_pk_bf16_f32 v21, v34, v35
	global_store_dwordx4 v[56:57], v[18:21], off offset:256 nt
	global_load_dwordx4 v[18:21], v0, s[64:65] offset:2096
	s_nop 0
	global_load_dwordx4 v[26:29], v0, s[64:65] offset:2080
	global_load_dwordx4 v[34:37], v0, s[64:65] offset:2064
	global_load_dwordx4 v[46:49], v0, s[64:65] offset:2048
	v_mul_f32_e32 v0, v180, v14
	v_mul_f32_e32 v50, v0, v128
	v_mov_b32_e32 v0, v50
	v_mov_b32_e32 v51, v50
	s_nop 1
	v_permlane32_swap_b32_e32 v0, v51
	v_cndmask_b32_e32 v128, v51, v0, vcc
	v_pk_mul_f32 v[52:53], v[100:101], v[128:129]
	s_waitcnt vmcnt(6)
	v_mov_b32_e32 v128, v43
	v_mov_b32_e32 v0, v53
	v_mov_b32_e32 v51, v53
	s_nop 1
	v_permlane32_swap_b32_e32 v0, v51
	v_cndmask_b32_e32 v0, v51, v0, vcc
	v_mul_f32_e32 v51, v100, v0
	v_mov_b32_e32 v43, v45
	v_mov_b32_e32 v129, v44
	v_pk_mul_f32 v[44:45], v[50:51], v[42:43]
	v_mul_f32_e32 v50, v130, v126
	v_mov_b32_e32 v0, v50
	v_mov_b32_e32 v51, v50
	v_mul_f32_e32 v131, v180, v17
	s_nop 0
	v_permlane32_swap_b32_e32 v0, v51
	v_cndmask_b32_e32 v126, v51, v0, vcc
	v_mov_b32_e32 v101, v131
	v_pk_fma_f32 v[44:45], v[128:129], v[52:53], v[44:45]
	v_pk_mul_f32 v[52:53], v[100:101], v[126:127]
	v_mov_b32_e32 v126, v39
	v_mov_b32_e32 v0, v53
	v_mov_b32_e32 v51, v53
	s_nop 1
	v_permlane32_swap_b32_e32 v0, v51
	v_cndmask_b32_e32 v0, v51, v0, vcc
	v_mul_f32_e32 v51, v100, v0
	v_mov_b32_e32 v39, v41
	v_mul_f32_e32 v0, v180, v10
	v_mov_b32_e32 v127, v40
	v_pk_mul_f32 v[40:41], v[50:51], v[38:39]
	v_mul_f32_e32 v50, v0, v124
	v_mov_b32_e32 v0, v50
	v_mov_b32_e32 v51, v50
	s_nop 1
	v_permlane32_swap_b32_e32 v0, v51
	v_mul_f32_e32 v101, v180, v11
	v_cndmask_b32_e32 v124, v51, v0, vcc
	v_pk_fma_f32 v[40:41], v[126:127], v[52:53], v[40:41]
	v_pk_mul_f32 v[52:53], v[100:101], v[124:125]
	v_mul_f32_e32 v130, v180, v12
	v_mov_b32_e32 v0, v53
	v_mov_b32_e32 v51, v53
	s_nop 1
	v_permlane32_swap_b32_e32 v0, v51
	v_cndmask_b32_e32 v0, v51, v0, vcc
	v_mov_b32_e32 v124, v31
	v_mul_f32_e32 v51, v100, v0
	v_mov_b32_e32 v31, v33
	v_mov_b32_e32 v125, v32
	v_pk_mul_f32 v[32:33], v[50:51], v[30:31]
	v_mul_f32_e32 v50, v130, v120
	v_mov_b32_e32 v0, v50
	v_mov_b32_e32 v51, v50
	v_mul_f32_e32 v131, v180, v13
	s_nop 0
	v_permlane32_swap_b32_e32 v0, v51
	v_cndmask_b32_e32 v120, v51, v0, vcc
	v_mov_b32_e32 v101, v131
	v_pk_fma_f32 v[32:33], v[124:125], v[52:53], v[32:33]
	v_pk_mul_f32 v[52:53], v[100:101], v[120:121]
	v_mov_b32_e32 v120, v23
	v_mov_b32_e32 v0, v53
	v_mov_b32_e32 v51, v53
	s_nop 1
	v_permlane32_swap_b32_e32 v0, v51
	v_cndmask_b32_e32 v0, v51, v0, vcc
	v_mul_f32_e32 v51, v100, v0
	v_mov_b32_e32 v23, v25
	v_mov_b32_e32 v121, v24
	v_pk_mul_f32 v[24:25], v[50:51], v[22:23]
	v_mul_f32_e32 v0, v180, v6
	v_pk_fma_f32 v[24:25], v[120:121], v[52:53], v[24:25]
	v_mul_f32_e32 v101, v180, v7
	v_cvt_pk_bf16_f32 v53, v24, v25
	v_mul_f32_e32 v24, v0, v118
	v_mov_b32_e32 v0, v24
	v_mov_b32_e32 v25, v24
	s_nop 1
	v_permlane32_swap_b32_e32 v0, v25
	v_cndmask_b32_e32 v118, v25, v0, vcc
	v_cvt_pk_bf16_f32 v52, v32, v33
	v_pk_mul_f32 v[32:33], v[100:101], v[118:119]
	v_cvt_pk_bf16_f32 v51, v40, v41
	v_mov_b32_e32 v0, v33
	v_mov_b32_e32 v25, v33
	s_nop 1
	v_permlane32_swap_b32_e32 v0, v25
	v_cndmask_b32_e32 v0, v25, v0, vcc
	v_mul_f32_e32 v25, v100, v0
	v_mul_f32_e32 v40, v180, v8
	v_pk_mul_f32 v[24:25], v[24:25], v[42:43]
	v_mul_f32_e32 v41, v180, v9
	v_pk_fma_f32 v[24:25], v[128:129], v[32:33], v[24:25]
	v_mul_f32_e32 v32, v40, v116
	v_mov_b32_e32 v0, v32
	v_mov_b32_e32 v33, v32
	s_nop 1
	v_permlane32_swap_b32_e32 v0, v33
	v_cndmask_b32_e32 v116, v33, v0, vcc
	v_mov_b32_e32 v101, v41
	v_pk_mul_f32 v[40:41], v[100:101], v[116:117]
	v_mul_f32_e32 v101, v180, v3
	v_mov_b32_e32 v0, v41
	v_mov_b32_e32 v33, v41
	s_nop 1
	v_permlane32_swap_b32_e32 v0, v33
	v_cndmask_b32_e32 v0, v33, v0, vcc
	v_mul_f32_e32 v33, v100, v0
	v_mul_f32_e32 v0, v180, v2
	v_pk_mul_f32 v[32:33], v[32:33], v[38:39]
	v_mul_f32_e32 v38, v0, v114
	v_mov_b32_e32 v0, v38
	v_mov_b32_e32 v39, v38
	s_nop 1
	v_permlane32_swap_b32_e32 v0, v39
	v_cndmask_b32_e32 v114, v39, v0, vcc
	v_pk_fma_f32 v[32:33], v[126:127], v[40:41], v[32:33]
	v_pk_mul_f32 v[40:41], v[100:101], v[114:115]
	v_mul_f32_e32 v42, v180, v4
	v_mov_b32_e32 v0, v41
	v_mov_b32_e32 v39, v41
	s_nop 1
	v_permlane32_swap_b32_e32 v0, v39
	v_cndmask_b32_e32 v0, v39, v0, vcc
	v_mul_f32_e32 v39, v100, v0
	v_pk_mul_f32 v[30:31], v[38:39], v[30:31]
	v_mul_f32_e32 v38, v42, v112
	v_mov_b32_e32 v0, v38
	v_mov_b32_e32 v39, v38
	v_mul_f32_e32 v43, v180, v5
	s_nop 0
	v_permlane32_swap_b32_e32 v0, v39
	v_cndmask_b32_e32 v112, v39, v0, vcc
	v_mov_b32_e32 v101, v43
	v_pk_fma_f32 v[30:31], v[124:125], v[40:41], v[30:31]
	v_pk_mul_f32 v[40:41], v[100:101], v[112:113]
	v_lshl_add_u64 v[56:57], v[122:123], 0, v[148:149]
	v_mov_b32_e32 v0, v41
	v_mov_b32_e32 v39, v41
	s_nop 1
	v_permlane32_swap_b32_e32 v0, v39
	v_cndmask_b32_e32 v0, v39, v0, vcc
	v_cvt_pk_bf16_f32 v50, v44, v45
	v_mul_f32_e32 v39, v100, v0
	v_mul_f32_e32 v0, v178, v14
	global_store_dwordx4 v[56:57], v[50:53], off nt
	v_pk_mul_f32 v[22:23], v[38:39], v[22:23]
	v_mul_f32_e32 v101, v178, v15
	v_mul_f32_e32 v50, v0, v110
	v_mov_b32_e32 v0, v50
	v_mov_b32_e32 v51, v50
	v_pk_fma_f32 v[38:39], v[120:121], v[40:41], v[22:23]
	s_nop 0
	v_permlane32_swap_b32_e32 v0, v51
	v_cvt_pk_bf16_f32 v22, v24, v25
	v_cvt_pk_bf16_f32 v23, v32, v33
	v_cvt_pk_bf16_f32 v24, v30, v31
	v_cvt_pk_bf16_f32 v25, v38, v39
	v_cndmask_b32_e32 v110, v51, v0, vcc
	global_store_dwordx4 v[56:57], v[22:25], off offset:256 nt
	v_add_co_u32_e64 v56, s[0:1], s19, v54
	v_pk_mul_f32 v[110:111], v[100:101], v[110:111]
	v_lshl_add_u64 v[38:39], v[54:55], 0, s[30:31]
	v_addc_co_u32_e64 v57, s[0:1], 0, v55, s[0:1]
	v_mov_b32_e32 v0, v111
	v_mov_b32_e32 v51, v111
	global_load_dwordx4 v[42:45], v[56:57], off
	global_load_dwordx4 v[22:25], v[38:39], off offset:48
	global_load_dwordx4 v[30:33], v[38:39], off offset:32
	s_nop 0
	global_load_dwordx4 v[38:41], v[38:39], off offset:16
	v_permlane32_swap_b32_e32 v0, v51
	v_cndmask_b32_e32 v0, v51, v0, vcc
	v_mul_f32_e32 v114, v178, v16
	s_waitcnt vmcnt(6)
	v_mov_b32_e32 v112, v47
	v_mul_f32_e32 v51, v100, v0
	v_mov_b32_e32 v47, v49
	v_mov_b32_e32 v113, v48
	v_pk_mul_f32 v[48:49], v[50:51], v[46:47]
	v_mul_f32_e32 v50, v114, v108
	v_mov_b32_e32 v0, v50
	v_mov_b32_e32 v51, v50
	v_mul_f32_e32 v115, v178, v17
	s_nop 0
	v_permlane32_swap_b32_e32 v0, v51
	v_cndmask_b32_e32 v108, v51, v0, vcc
	v_mov_b32_e32 v101, v115
	v_pk_mul_f32 v[108:109], v[100:101], v[108:109]
	v_pk_fma_f32 v[48:49], v[112:113], v[110:111], v[48:49]
	v_mov_b32_e32 v0, v109
	v_mov_b32_e32 v51, v109
	s_nop 1
	v_permlane32_swap_b32_e32 v0, v51
	v_cndmask_b32_e32 v0, v51, v0, vcc
	v_mov_b32_e32 v110, v35
	v_mul_f32_e32 v51, v100, v0
	v_mov_b32_e32 v35, v37
	v_mul_f32_e32 v0, v178, v10
	v_mov_b32_e32 v111, v36
	v_pk_mul_f32 v[36:37], v[50:51], v[34:35]
	v_mul_f32_e32 v50, v0, v106
	v_mov_b32_e32 v0, v50
	v_mov_b32_e32 v51, v50
	s_nop 1
	v_permlane32_swap_b32_e32 v0, v51
	v_mul_f32_e32 v101, v178, v11
	v_cndmask_b32_e32 v106, v51, v0, vcc
	v_pk_mul_f32 v[106:107], v[100:101], v[106:107]
	v_pk_fma_f32 v[36:37], v[110:111], v[108:109], v[36:37]
	v_mov_b32_e32 v0, v107
	v_mov_b32_e32 v51, v107
	s_nop 1
	v_permlane32_swap_b32_e32 v0, v51
	v_cndmask_b32_e32 v0, v51, v0, vcc
	v_mul_f32_e32 v114, v178, v12
	v_mov_b32_e32 v108, v27
	v_mul_f32_e32 v51, v100, v0
	v_mov_b32_e32 v27, v29
	v_mov_b32_e32 v109, v28
	v_pk_mul_f32 v[28:29], v[50:51], v[26:27]
	v_mul_f32_e32 v50, v114, v104
	v_mov_b32_e32 v0, v50
	v_mov_b32_e32 v51, v50
	v_mul_f32_e32 v115, v178, v13
	s_nop 0
	v_permlane32_swap_b32_e32 v0, v51
	v_cndmask_b32_e32 v104, v51, v0, vcc
	v_mov_b32_e32 v101, v115
	v_pk_mul_f32 v[104:105], v[100:101], v[104:105]
	v_pk_fma_f32 v[28:29], v[108:109], v[106:107], v[28:29]
	v_mov_b32_e32 v0, v105
	v_mov_b32_e32 v51, v105
	s_nop 1
	v_permlane32_swap_b32_e32 v0, v51
	v_cndmask_b32_e32 v0, v51, v0, vcc
	v_mov_b32_e32 v106, v19
	v_mul_f32_e32 v51, v100, v0
	v_mov_b32_e32 v19, v21
	v_mov_b32_e32 v107, v20
	v_pk_mul_f32 v[20:21], v[50:51], v[18:19]
	v_mul_f32_e32 v0, v178, v6
	v_pk_fma_f32 v[20:21], v[106:107], v[104:105], v[20:21]
	v_mul_f32_e32 v101, v178, v7
	v_cvt_pk_bf16_f32 v51, v20, v21
	v_mul_f32_e32 v20, v0, v102
	v_mov_b32_e32 v0, v20
	v_mov_b32_e32 v21, v20
	s_nop 1
	v_permlane32_swap_b32_e32 v0, v21
	v_cndmask_b32_e32 v102, v21, v0, vcc
	v_cvt_pk_bf16_f32 v50, v28, v29
	v_pk_mul_f32 v[28:29], v[100:101], v[102:103]
	v_cvt_pk_bf16_f32 v48, v48, v49
	v_mov_b32_e32 v0, v29
	v_mov_b32_e32 v21, v29
	s_nop 1
	v_permlane32_swap_b32_e32 v0, v21
	v_cndmask_b32_e32 v0, v21, v0, vcc
	v_mul_f32_e32 v21, v100, v0
	v_cvt_pk_bf16_f32 v49, v36, v37
	v_mul_f32_e32 v36, v178, v8
	v_pk_mul_f32 v[20:21], v[20:21], v[46:47]
	v_mul_f32_e32 v37, v178, v9
	v_pk_fma_f32 v[20:21], v[112:113], v[28:29], v[20:21]
	v_mul_f32_e32 v28, v36, v98
	v_mov_b32_e32 v0, v28
	v_mov_b32_e32 v29, v28
	s_nop 1
	v_permlane32_swap_b32_e32 v0, v29
	v_cndmask_b32_e32 v98, v29, v0, vcc
	v_mov_b32_e32 v101, v37
	v_pk_mul_f32 v[36:37], v[100:101], v[98:99]
	v_mul_f32_e32 v101, v178, v3
	v_mov_b32_e32 v0, v37
	v_mov_b32_e32 v29, v37
	s_nop 1
	v_permlane32_swap_b32_e32 v0, v29
	v_cndmask_b32_e32 v0, v29, v0, vcc
	v_mul_f32_e32 v29, v100, v0
	v_mul_f32_e32 v0, v178, v2
	v_pk_mul_f32 v[28:29], v[28:29], v[34:35]
	v_mul_f32_e32 v34, v0, v96
	v_mov_b32_e32 v0, v34
	v_mov_b32_e32 v35, v34
	s_nop 1
	v_permlane32_swap_b32_e32 v0, v35
	v_cndmask_b32_e32 v96, v35, v0, vcc
	v_pk_fma_f32 v[28:29], v[110:111], v[36:37], v[28:29]
	v_pk_mul_f32 v[36:37], v[100:101], v[96:97]
	v_mul_f32_e32 v46, v178, v4
	v_mov_b32_e32 v0, v37
	v_mov_b32_e32 v35, v37
	s_nop 1
	v_permlane32_swap_b32_e32 v0, v35
	v_cndmask_b32_e32 v0, v35, v0, vcc
	v_mul_f32_e32 v35, v100, v0
	v_pk_mul_f32 v[26:27], v[34:35], v[26:27]
	v_mul_f32_e32 v34, v46, v94
	v_mov_b32_e32 v0, v34
	v_mov_b32_e32 v35, v34
	v_mul_f32_e32 v47, v178, v5
	s_nop 0
	v_permlane32_swap_b32_e32 v0, v35
	v_cndmask_b32_e32 v94, v35, v0, vcc
	v_mov_b32_e32 v101, v47
	v_pk_fma_f32 v[26:27], v[108:109], v[36:37], v[26:27]
	v_pk_mul_f32 v[36:37], v[100:101], v[94:95]
	v_lshl_add_u64 v[52:53], v[122:123], 0, v[146:147]
	v_mov_b32_e32 v0, v37
	v_mov_b32_e32 v35, v37
	s_nop 1
	v_permlane32_swap_b32_e32 v0, v35
	v_cndmask_b32_e32 v0, v35, v0, vcc
	v_mul_f32_e32 v35, v100, v0
	v_mul_f32_e32 v0, v176, v14
	global_store_dwordx4 v[52:53], v[48:51], off nt
	v_pk_mul_f32 v[18:19], v[34:35], v[18:19]
	v_mul_f32_e32 v101, v176, v15
	v_mul_f32_e32 v50, v0, v90
	v_mov_b32_e32 v0, v50
	v_mov_b32_e32 v51, v50
	v_pk_fma_f32 v[34:35], v[106:107], v[36:37], v[18:19]
	s_nop 0
	v_permlane32_swap_b32_e32 v0, v51
	v_cvt_pk_bf16_f32 v18, v20, v21
	v_cvt_pk_bf16_f32 v19, v28, v29
	v_cvt_pk_bf16_f32 v20, v26, v27
	v_cvt_pk_bf16_f32 v21, v34, v35
	v_cndmask_b32_e32 v90, v51, v0, vcc
	global_store_dwordx4 v[52:53], v[18:21], off offset:256 nt
	v_pk_mul_f32 v[52:53], v[100:101], v[90:91]
	v_lshl_add_u64 v[34:35], v[54:55], 0, s[28:29]
	v_mov_b32_e32 v0, v53
	v_mov_b32_e32 v51, v53
	global_load_dwordx4 v[46:49], v[56:57], off offset:2048
	global_load_dwordx4 v[18:21], v[34:35], off offset:48
	global_load_dwordx4 v[26:29], v[34:35], off offset:32
	s_nop 0
	global_load_dwordx4 v[34:37], v[34:35], off offset:16
	v_permlane32_swap_b32_e32 v0, v51
	v_cndmask_b32_e32 v0, v51, v0, vcc
	v_mul_f32_e32 v56, v176, v16
	s_waitcnt vmcnt(9)
	v_mov_b32_e32 v54, v43
	v_mul_f32_e32 v51, v100, v0
	v_mov_b32_e32 v43, v45
	v_mov_b32_e32 v55, v44
	v_pk_mul_f32 v[44:45], v[50:51], v[42:43]
	v_mul_f32_e32 v50, v56, v88
	v_mov_b32_e32 v0, v50
	v_mov_b32_e32 v51, v50
	v_mul_f32_e32 v57, v176, v17
	s_nop 0
	v_permlane32_swap_b32_e32 v0, v51
	v_cndmask_b32_e32 v88, v51, v0, vcc
	v_mov_b32_e32 v101, v57
	v_pk_fma_f32 v[44:45], v[54:55], v[52:53], v[44:45]
	v_pk_mul_f32 v[52:53], v[100:101], v[88:89]
	s_waitcnt vmcnt(6)
	v_mov_b32_e32 v56, v39
	v_mov_b32_e32 v0, v53
	v_mov_b32_e32 v51, v53
	s_nop 1
	v_permlane32_swap_b32_e32 v0, v51
	v_cndmask_b32_e32 v0, v51, v0, vcc
	v_mul_f32_e32 v51, v100, v0
	v_mov_b32_e32 v39, v41
	v_mul_f32_e32 v0, v176, v10
	v_mov_b32_e32 v57, v40
	v_pk_mul_f32 v[40:41], v[50:51], v[38:39]
	v_mul_f32_e32 v50, v0, v86
	v_mov_b32_e32 v0, v50
	v_mov_b32_e32 v51, v50
	s_nop 1
	v_permlane32_swap_b32_e32 v0, v51
	v_mul_f32_e32 v101, v176, v11
	v_cndmask_b32_e32 v86, v51, v0, vcc
	v_pk_fma_f32 v[40:41], v[56:57], v[52:53], v[40:41]
	v_pk_mul_f32 v[52:53], v[100:101], v[86:87]
	v_mul_f32_e32 v88, v176, v12
	v_mov_b32_e32 v0, v53
	v_mov_b32_e32 v51, v53
	s_nop 1
	v_permlane32_swap_b32_e32 v0, v51
	v_cndmask_b32_e32 v0, v51, v0, vcc
	v_mov_b32_e32 v86, v31
	v_mul_f32_e32 v51, v100, v0
	v_mov_b32_e32 v31, v33
	v_mov_b32_e32 v87, v32
	v_pk_mul_f32 v[32:33], v[50:51], v[30:31]
	v_mul_f32_e32 v50, v88, v84
	v_mov_b32_e32 v0, v50
	v_mov_b32_e32 v51, v50
	v_mul_f32_e32 v89, v176, v13
	s_nop 0
	v_permlane32_swap_b32_e32 v0, v51
	v_cndmask_b32_e32 v84, v51, v0, vcc
	v_mov_b32_e32 v101, v89
	v_pk_fma_f32 v[32:33], v[86:87], v[52:53], v[32:33]
	v_pk_mul_f32 v[52:53], v[100:101], v[84:85]
	v_mov_b32_e32 v84, v23
	v_mov_b32_e32 v0, v53
	v_mov_b32_e32 v51, v53
	s_nop 1
	v_permlane32_swap_b32_e32 v0, v51
	v_cndmask_b32_e32 v0, v51, v0, vcc
	v_mul_f32_e32 v51, v100, v0
	v_mov_b32_e32 v23, v25
	v_mov_b32_e32 v85, v24
	v_pk_mul_f32 v[24:25], v[50:51], v[22:23]
	v_mul_f32_e32 v0, v176, v6
	v_pk_fma_f32 v[24:25], v[84:85], v[52:53], v[24:25]
	v_mul_f32_e32 v101, v176, v7
	v_cvt_pk_bf16_f32 v53, v24, v25
	v_mul_f32_e32 v24, v0, v82
	v_mov_b32_e32 v0, v24
	v_mov_b32_e32 v25, v24
	s_nop 1
	v_permlane32_swap_b32_e32 v0, v25
	v_cndmask_b32_e32 v82, v25, v0, vcc
	v_cvt_pk_bf16_f32 v52, v32, v33
	v_pk_mul_f32 v[32:33], v[100:101], v[82:83]
	v_cvt_pk_bf16_f32 v51, v40, v41
	v_mov_b32_e32 v0, v33
	v_mov_b32_e32 v25, v33
	s_nop 1
	v_permlane32_swap_b32_e32 v0, v25
	v_cndmask_b32_e32 v0, v25, v0, vcc
	v_mul_f32_e32 v25, v100, v0
	v_mul_f32_e32 v40, v176, v8
	v_pk_mul_f32 v[24:25], v[24:25], v[42:43]
	v_mul_f32_e32 v41, v176, v9
	v_pk_fma_f32 v[24:25], v[54:55], v[32:33], v[24:25]
	v_mul_f32_e32 v32, v40, v80
	v_mov_b32_e32 v0, v32
	v_mov_b32_e32 v33, v32
	s_nop 1
	v_permlane32_swap_b32_e32 v0, v33
	v_cndmask_b32_e32 v80, v33, v0, vcc
	v_mov_b32_e32 v101, v41
	v_pk_mul_f32 v[40:41], v[100:101], v[80:81]
	v_mul_f32_e32 v101, v176, v3
	v_mov_b32_e32 v0, v41
	v_mov_b32_e32 v33, v41
	s_nop 1
	v_permlane32_swap_b32_e32 v0, v33
	v_cndmask_b32_e32 v0, v33, v0, vcc
	v_mul_f32_e32 v33, v100, v0
	v_mul_f32_e32 v0, v176, v2
	v_pk_mul_f32 v[32:33], v[32:33], v[38:39]
	v_mul_f32_e32 v38, v0, v78
	v_mov_b32_e32 v0, v38
	v_mov_b32_e32 v39, v38
	s_nop 1
	v_permlane32_swap_b32_e32 v0, v39
	v_cndmask_b32_e32 v78, v39, v0, vcc
	v_pk_fma_f32 v[32:33], v[56:57], v[40:41], v[32:33]
	v_pk_mul_f32 v[40:41], v[100:101], v[78:79]
	v_mul_f32_e32 v42, v176, v4
	v_mov_b32_e32 v0, v41
	v_mov_b32_e32 v39, v41
	s_nop 1
	v_permlane32_swap_b32_e32 v0, v39
	v_cndmask_b32_e32 v0, v39, v0, vcc
	v_mul_f32_e32 v39, v100, v0
	v_pk_mul_f32 v[30:31], v[38:39], v[30:31]
	v_mul_f32_e32 v38, v42, v74
	v_mov_b32_e32 v0, v38
	v_mov_b32_e32 v39, v38
	v_mul_f32_e32 v43, v176, v5
	s_nop 0
	v_permlane32_swap_b32_e32 v0, v39
	v_cndmask_b32_e32 v74, v39, v0, vcc
	v_mov_b32_e32 v101, v43
	v_pk_fma_f32 v[30:31], v[86:87], v[40:41], v[30:31]
	v_pk_mul_f32 v[40:41], v[100:101], v[74:75]
	v_mul_f32_e32 v101, v174, v15
	v_mov_b32_e32 v0, v41
	v_mov_b32_e32 v39, v41
	s_nop 1
	v_permlane32_swap_b32_e32 v0, v39
	v_cndmask_b32_e32 v0, v39, v0, vcc
	v_mul_f32_e32 v39, v100, v0
	v_mul_f32_e32 v0, v174, v14
	v_mul_f32_e32 v14, v0, v72
	v_mov_b32_e32 v0, v14
	v_mov_b32_e32 v15, v14
	s_nop 1
	v_permlane32_swap_b32_e32 v0, v15
	v_pk_mul_f32 v[22:23], v[38:39], v[22:23]
	v_cndmask_b32_e32 v72, v15, v0, vcc
	v_pk_fma_f32 v[38:39], v[84:85], v[40:41], v[22:23]
	v_cvt_pk_bf16_f32 v22, v24, v25
	v_cvt_pk_bf16_f32 v24, v30, v31
	v_mul_f32_e32 v30, v174, v16
	v_mul_f32_e32 v31, v174, v17
	v_pk_mul_f32 v[16:17], v[100:101], v[72:73]
	v_cvt_pk_bf16_f32 v23, v32, v33
	v_mov_b32_e32 v0, v17
	v_mov_b32_e32 v15, v17
	s_nop 1
	v_permlane32_swap_b32_e32 v0, v15
	v_cvt_pk_bf16_f32 v25, v38, v39
	v_cndmask_b32_e32 v0, v15, v0, vcc
	global_store_dwordx4 v[92:93], v[22:25], off offset:256 nt
	v_mul_f32_e32 v15, v100, v0
	v_mov_b32_e32 v101, v31
	s_waitcnt vmcnt(4)
	v_mov_b32_e32 v24, v47
	v_mov_b32_e32 v47, v49
	v_mov_b32_e32 v25, v48
	v_pk_mul_f32 v[14:15], v[14:15], v[46:47]
	s_waitcnt vmcnt(1)
	v_mov_b32_e32 v32, v35
	v_pk_fma_f32 v[14:15], v[24:25], v[16:17], v[14:15]
	v_mul_f32_e32 v16, v30, v70
	v_mov_b32_e32 v0, v16
	v_mov_b32_e32 v17, v16
	s_nop 1
	v_permlane32_swap_b32_e32 v0, v17
	v_cndmask_b32_e32 v70, v17, v0, vcc
	v_pk_mul_f32 v[30:31], v[100:101], v[70:71]
	v_mul_f32_e32 v101, v174, v11
	v_mov_b32_e32 v0, v31
	v_mov_b32_e32 v17, v31
	s_nop 1
	v_permlane32_swap_b32_e32 v0, v17
	v_cndmask_b32_e32 v0, v17, v0, vcc
	v_mul_f32_e32 v17, v100, v0
	v_mul_f32_e32 v0, v174, v10
	v_mul_f32_e32 v10, v0, v68
	v_mov_b32_e32 v0, v10
	v_mov_b32_e32 v11, v10
	s_nop 1
	v_permlane32_swap_b32_e32 v0, v11
	v_cndmask_b32_e32 v68, v11, v0, vcc
	v_mov_b32_e32 v33, v36
	v_mov_b32_e32 v35, v37
	v_mul_f32_e32 v36, v174, v12
	v_mul_f32_e32 v37, v174, v13
	v_pk_mul_f32 v[12:13], v[100:101], v[68:69]
	v_pk_mul_f32 v[16:17], v[16:17], v[34:35]
	v_mov_b32_e32 v0, v13
	v_mov_b32_e32 v11, v13
	s_nop 1
	v_permlane32_swap_b32_e32 v0, v11
	v_cndmask_b32_e32 v0, v11, v0, vcc
	v_pk_fma_f32 v[16:17], v[32:33], v[30:31], v[16:17]
	v_mov_b32_e32 v30, v27
	v_mul_f32_e32 v11, v100, v0
	v_mov_b32_e32 v27, v29
	v_mov_b32_e32 v31, v28
	v_pk_mul_f32 v[10:11], v[10:11], v[26:27]
	v_mov_b32_e32 v101, v37
	v_pk_fma_f32 v[12:13], v[30:31], v[12:13], v[10:11]
	v_mul_f32_e32 v10, v36, v66
	v_mov_b32_e32 v0, v10
	v_mov_b32_e32 v11, v10
	s_nop 1
	v_permlane32_swap_b32_e32 v0, v11
	v_cndmask_b32_e32 v66, v11, v0, vcc
	v_pk_mul_f32 v[28:29], v[100:101], v[66:67]
	v_mov_b32_e32 v36, v19
	v_mov_b32_e32 v0, v29
	v_mov_b32_e32 v11, v29
	s_nop 1
	v_permlane32_swap_b32_e32 v0, v11
	v_cndmask_b32_e32 v0, v11, v0, vcc
	v_mul_f32_e32 v11, v100, v0
	v_mul_f32_e32 v0, v174, v6
	v_mov_b32_e32 v19, v21
	v_mul_f32_e32 v6, v0, v64
	v_mov_b32_e32 v37, v20
	v_pk_mul_f32 v[10:11], v[10:11], v[18:19]
	v_mul_f32_e32 v101, v174, v7
	v_mov_b32_e32 v0, v6
	v_mov_b32_e32 v7, v6
	v_pk_fma_f32 v[20:21], v[36:37], v[28:29], v[10:11]
	s_nop 0
	v_permlane32_swap_b32_e32 v0, v7
	v_lshl_add_u64 v[22:23], v[122:123], 0, v[76:77]
	v_cvt_pk_bf16_f32 v10, v14, v15
	v_cvt_pk_bf16_f32 v11, v16, v17
	v_cvt_pk_bf16_f32 v12, v12, v13
	v_cvt_pk_bf16_f32 v13, v20, v21
	v_cndmask_b32_e32 v64, v7, v0, vcc
	global_store_dwordx4 v[22:23], v[10:13], off nt
	v_cvt_pk_bf16_f32 v50, v44, v45
	global_store_dwordx4 v[92:93], v[50:53], off nt
	v_mul_f32_e32 v10, v174, v8
	v_mul_f32_e32 v11, v174, v9
	v_pk_mul_f32 v[8:9], v[100:101], v[64:65]
	v_mov_b32_e32 v101, v11
	v_mov_b32_e32 v0, v9
	v_mov_b32_e32 v7, v9
	s_nop 1
	v_permlane32_swap_b32_e32 v0, v7
	v_cndmask_b32_e32 v0, v7, v0, vcc
	v_mul_f32_e32 v7, v100, v0
	v_pk_mul_f32 v[6:7], v[6:7], v[46:47]
	s_nop 0
	v_pk_fma_f32 v[6:7], v[24:25], v[8:9], v[6:7]
	v_mul_f32_e32 v8, v10, v62
	v_mov_b32_e32 v0, v8
	v_mov_b32_e32 v9, v8
	s_nop 1
	v_permlane32_swap_b32_e32 v0, v9
	v_cndmask_b32_e32 v62, v9, v0, vcc
	v_pk_mul_f32 v[10:11], v[100:101], v[62:63]
	v_mul_f32_e32 v101, v174, v3
	v_mov_b32_e32 v0, v11
	v_mov_b32_e32 v9, v11
	s_nop 1
	v_permlane32_swap_b32_e32 v0, v9
	v_cndmask_b32_e32 v0, v9, v0, vcc
	v_mul_f32_e32 v9, v100, v0
	v_mul_f32_e32 v0, v174, v2
	v_mul_f32_e32 v2, v0, v60
	v_mov_b32_e32 v0, v2
	v_mov_b32_e32 v3, v2
	s_nop 1
	v_permlane32_swap_b32_e32 v0, v3
	v_pk_mul_f32 v[8:9], v[8:9], v[34:35]
	v_cndmask_b32_e32 v60, v3, v0, vcc
	v_pk_fma_f32 v[8:9], v[32:33], v[10:11], v[8:9]
	v_mul_f32_e32 v10, v174, v4
	v_mul_f32_e32 v11, v174, v5
	v_pk_mul_f32 v[4:5], v[100:101], v[60:61]
	v_mov_b32_e32 v101, v11
	v_mov_b32_e32 v0, v5
	v_mov_b32_e32 v3, v5
	s_nop 1
	v_permlane32_swap_b32_e32 v0, v3
	v_cndmask_b32_e32 v0, v3, v0, vcc
	v_mul_f32_e32 v3, v100, v0
	v_pk_mul_f32 v[2:3], v[2:3], v[26:27]
	s_nop 0
	v_pk_fma_f32 v[4:5], v[30:31], v[4:5], v[2:3]
	v_mul_f32_e32 v2, v10, v58
	v_mov_b32_e32 v0, v2
	v_mov_b32_e32 v3, v2
	s_nop 1
	v_permlane32_swap_b32_e32 v0, v3
	v_cndmask_b32_e32 v58, v3, v0, vcc
	v_pk_mul_f32 v[10:11], v[100:101], v[58:59]
	v_cvt_pk_bf16_f32 v4, v4, v5
	v_mov_b32_e32 v0, v11
	v_mov_b32_e32 v3, v11
	s_nop 1
	v_permlane32_swap_b32_e32 v0, v3
	v_cndmask_b32_e32 v0, v3, v0, vcc
	v_mul_f32_e32 v3, v100, v0
	v_pk_mul_f32 v[2:3], v[2:3], v[18:19]
	s_nop 0
	v_pk_fma_f32 v[10:11], v[36:37], v[10:11], v[2:3]
	v_cvt_pk_bf16_f32 v2, v6, v7
	v_cvt_pk_bf16_f32 v3, v8, v9
	v_cvt_pk_bf16_f32 v5, v10, v11
	global_store_dwordx4 v[22:23], v[2:5], off offset:256 nt
	s_and_b64 vcc, exec, s[40:41]
	s_mov_b64 s[0:1], -1
	s_cbranch_vccnz .LBB0_355
